# as previous, plus the redundant lgkmcnt(0) after each pre-MMA barrier removed (counter already drained before the barrier)
# baseline (speedup 1.0000x reference)
; #define PG8_STAGE(bufoff, gbase, voff) do { _Pragma("unroll") for (int _i = 0; _i < 2; ++_i) \
;         __builtin_amdgcn_global_load_lds((const unsigned*)((const char*)(gbase) + (voff)[_i]), (LAS unsigned*)(lds + (bufoff) + ldsw + _i * 8192), 16, 0, 0); } while (0)
; #define PG8_LDA(dst, b, h) do { _Pragma("unroll") for (int m = 0; m < 4; ++m) _Pragma("unroll") for (int k = 0; k < 2; ++k) dst[m][k] = *(const LAS bf16x8*)(lds + PG8_SA(b, h) + aoff + m * 2048 + k * 1024); } while (0)
; #define PG8_LDB(dst, b, h) do { _Pragma("unroll") for (int n = 0; n < 2; ++n) _Pragma("unroll") for (int k = 0; k < 2; ++k) dst[n][k] = *(const LAS bf16x8*)(lds + PG8_SB(b, h) + boff + n * 2048 + k * 1024); } while (0)
; #define PG8_MMA(ai, bj, At, Bt) do { __builtin_amdgcn_s_setprio(1); _Pragma("unroll") for (int m = 0; m < 4; ++m) _Pragma("unroll") for (int n = 0; n < 2; ++n) _Pragma("unroll") for (int k = 0; k < 2; ++k) \
;         acc[ai][bj][m][n] = __builtin_amdgcn_mfma_f32_16x16x32_bf16(Bt[n][k], At[m][k], acc[ai][bj][m][n], 0, 0, 0); __builtin_amdgcn_s_setprio(0); } while (0)
; template <class Epi, bool PERMA = false, bool DUAL = false, bool ALIGN_EPI = true, bool SP2 = true>
; __device__ __forceinline__ void gemm_phase(LAS unsigned char* lds, const Gemm g, const StaticOrder& S, const Epi& E) {
;     ...
;         const char* nA = has_next ? (const char*)gA_ + (size_t)nxt.pm * tstepA : cA; const char* nB = has_next ? (const char*)gB_ + (size_t)nxt.pn * tstepB : cB;
;         for (int t = 0; t < nt; t += 2) {
;             const bool last = (t == nt - 2);
;             const char* a1 = cA + (size_t)(t + 1) * kstep;
;             const char* a2 = last ? nA : cA + (size_t)(t + 2) * kstep; const char* b2 = last ? nB : cB + (size_t)(t + 2) * kstep;
;             const char* a3 = a2 + kstep; const char* b3 = b2 + kstep;
;             if constexpr (SP2) {
;             PG8_LDB(B0, 0, 0); PG8_LDB(B1, 0, 1); PG8_SCHED; PG8_LDA(At, 0, 0); PG8_STAGE(PG8_SA(1, 1), a1 + hstepA, voffA);
;             PG8_WAIT_V(8); PG8_WAIT_L(0); PG8_BAR; PG8_MMA(0, 0, At, B0); PG8_MMA(0, 1, At, B1); PG8_BAR; PG8_SCHED;
;             PG8_LDA(At, 0, 1); PG8_STAGE(PG8_SB(0, 0), b2, voffB); PG8_STAGE(PG8_SB(0, 1), b2 + hstepB, voffB); PG8_STAGE(PG8_SA(0, 0), a2, voffA);
;             PG8_WAIT_V(8); PG8_WAIT_L(0); PG8_BAR; PG8_MMA(1, 0, At, B0); PG8_MMA(1, 1, At, B1); PG8_BAR; PG8_SCHED;
.LBB0_130:
	s_add_u32 s16, s14, 0xfff80080
	s_addc_u32 s17, s15, -1
	s_add_i32 s38, 0, 0x10000
	s_cmp_eq_u32 s37, 28
	s_cselect_b32 s19, s9, s17
	s_cselect_b32 s18, s33, s16
	s_cselect_b32 s17, s7, s36
	s_cselect_b32 s16, s34, s35
	s_add_i32 s40, 0, 0x14000
	v_add_u32_e32 v156, s38, v141
	v_add_u32_e32 v172, s40, v141
	ds_read_b128 v[144:147], v156
	ds_read_b128 v[148:151], v156 offset:1024
	ds_read_b128 v[152:155], v156 offset:2048
	ds_read_b128 v[156:159], v156 offset:3072
	ds_read_b128 v[160:163], v172
	ds_read_b128 v[164:167], v172 offset:1024
	ds_read_b128 v[168:171], v172 offset:2048
	ds_read_b128 v[172:175], v172 offset:3072
	v_lshl_add_u64 v[222:223], s[14:15], 0, v[136:137]
	s_add_i32 m0, s21, 0xc000
	ds_read_b128 v[176:179], v143
	ds_read_b128 v[180:183], v143 offset:1024
	ds_read_b128 v[184:187], v143 offset:2048
	ds_read_b128 v[188:191], v143 offset:3072
	ds_read_b128 v[206:209], v143 offset:4096
	ds_read_b128 v[210:213], v143 offset:5120
	ds_read_b128 v[214:217], v143 offset:6144
	ds_read_b128 v[218:221], v143 offset:7168
	global_load_lds_dwordx4 v[222:223], off
	v_lshl_add_u64 v[222:223], s[14:15], 0, v[138:139]
	s_add_i32 m0, s21, 0xe000
	s_nop 0
	global_load_lds_dwordx4 v[222:223], off
	s_waitcnt vmcnt(8)
	s_waitcnt lgkmcnt(0)
	s_setprio 1
	s_barrier
	v_mfma_f32_16x16x32_bf16 v[124:127], v[144:147], v[176:179], v[124:127]
	v_mfma_f32_16x16x32_bf16 v[120:123], v[152:155], v[176:179], v[120:123]
	v_mfma_f32_16x16x32_bf16 v[116:119], v[144:147], v[184:187], v[116:119]
	v_mfma_f32_16x16x32_bf16 v[108:111], v[152:155], v[184:187], v[108:111]
	v_mfma_f32_16x16x32_bf16 v[100:103], v[144:147], v[206:209], v[100:103]
	v_mfma_f32_16x16x32_bf16 v[92:95], v[152:155], v[206:209], v[92:95]
	v_mfma_f32_16x16x32_bf16 v[84:87], v[144:147], v[214:217], v[84:87]
	v_mfma_f32_16x16x32_bf16 v[76:79], v[152:155], v[214:217], v[76:79]
	v_mfma_f32_16x16x32_bf16 v[124:127], v[148:151], v[180:183], v[124:127]
	v_mfma_f32_16x16x32_bf16 v[120:123], v[156:159], v[180:183], v[120:123]
	v_mfma_f32_16x16x32_bf16 v[116:119], v[148:151], v[188:191], v[116:119]
	v_mfma_f32_16x16x32_bf16 v[108:111], v[156:159], v[188:191], v[108:111]
	v_mfma_f32_16x16x32_bf16 v[100:103], v[148:151], v[210:213], v[100:103]
	v_mfma_f32_16x16x32_bf16 v[92:95], v[156:159], v[210:213], v[92:95]
	v_mfma_f32_16x16x32_bf16 v[84:87], v[148:151], v[218:221], v[84:87]
	v_mfma_f32_16x16x32_bf16 v[76:79], v[156:159], v[218:221], v[76:79]
	v_mfma_f32_16x16x32_bf16 v[112:115], v[160:163], v[176:179], v[112:115]
	v_mfma_f32_16x16x32_bf16 v[104:107], v[168:171], v[176:179], v[104:107]
	v_mfma_f32_16x16x32_bf16 v[96:99], v[160:163], v[184:187], v[96:99]
	v_mfma_f32_16x16x32_bf16 v[88:91], v[168:171], v[184:187], v[88:91]
	v_mfma_f32_16x16x32_bf16 v[80:83], v[160:163], v[206:209], v[80:83]
	v_mfma_f32_16x16x32_bf16 v[72:75], v[168:171], v[206:209], v[72:75]
	v_mfma_f32_16x16x32_bf16 v[68:71], v[160:163], v[214:217], v[68:71]
	v_mfma_f32_16x16x32_bf16 v[64:67], v[168:171], v[214:217], v[64:67]
	v_mfma_f32_16x16x32_bf16 v[112:115], v[164:167], v[180:183], v[112:115]
	v_mfma_f32_16x16x32_bf16 v[104:107], v[172:175], v[180:183], v[104:107]
	v_mfma_f32_16x16x32_bf16 v[96:99], v[164:167], v[188:191], v[96:99]
	v_mfma_f32_16x16x32_bf16 v[88:91], v[172:175], v[188:191], v[88:91]
	v_mfma_f32_16x16x32_bf16 v[80:83], v[164:167], v[210:213], v[80:83]
	v_mfma_f32_16x16x32_bf16 v[72:75], v[172:175], v[210:213], v[72:75]
	v_mfma_f32_16x16x32_bf16 v[68:71], v[164:167], v[218:221], v[68:71]
	v_mfma_f32_16x16x32_bf16 v[64:67], v[172:175], v[218:221], v[64:67]
	s_barrier
	s_setprio 0
	s_add_i32 s38, s38, s20
	v_lshl_add_u64 v[222:223], s[16:17], 0, v[132:133]
	s_mov_b32 m0, s38
	ds_read_b128 v[176:179], v143 offset:16384
	ds_read_b128 v[180:183], v143 offset:17408
	ds_read_b128 v[184:187], v143 offset:18432
	ds_read_b128 v[188:191], v143 offset:19456
	ds_read_b128 v[206:209], v143 offset:20480
	ds_read_b128 v[210:213], v143 offset:21504
	ds_read_b128 v[214:217], v143 offset:22528
	ds_read_b128 v[218:221], v143 offset:23552
	global_load_lds_dwordx4 v[222:223], off
	s_add_i32 m0, s38, 0x2000
	s_add_u32 s38, s16, 0x80000
	v_lshl_add_u64 v[224:225], s[16:17], 0, v[128:129]
	s_addc_u32 s39, s17, 0
	s_add_i32 s40, s40, s20
	global_load_lds_dwordx4 v[224:225], off
	v_lshl_add_u64 v[226:227], s[38:39], 0, v[132:133]
	s_mov_b32 m0, s40
	v_lshl_add_u64 v[228:229], s[18:19], 0, v[130:131]
	global_load_lds_dwordx4 v[226:227], off
	v_lshl_add_u64 v[226:227], s[38:39], 0, v[128:129]
	s_add_i32 m0, s40, 0x2000
	s_nop 0
	global_load_lds_dwordx4 v[226:227], off
	v_lshl_add_u64 v[226:227], s[18:19], 0, v[134:135]
	s_mov_b32 m0, s21
	s_nop 0
	global_load_lds_dwordx4 v[226:227], off
	s_mov_b32 m0, s22
	s_nop 0
	global_load_lds_dwordx4 v[228:229], off
	s_waitcnt vmcnt(8)
	s_waitcnt lgkmcnt(0)
	s_setprio 1
	s_barrier
; #define PG8_STAGE(bufoff, gbase, voff) do { _Pragma("unroll") for (int _i = 0; _i < 2; ++_i) \
;         __builtin_amdgcn_global_load_lds((const unsigned*)((const char*)(gbase) + (voff)[_i]), (LAS unsigned*)(lds + (bufoff) + ldsw + _i * 8192), 16, 0, 0); } while (0)
; #define PG8_LDA(dst, b, h) do { _Pragma("unroll") for (int m = 0; m < 4; ++m) _Pragma("unroll") for (int k = 0; k < 2; ++k) dst[m][k] = *(const LAS bf16x8*)(lds + PG8_SA(b, h) + aoff + m * 2048 + k * 1024); } while (0)
; #define PG8_LDB(dst, b, h) do { _Pragma("unroll") for (int n = 0; n < 2; ++n) _Pragma("unroll") for (int k = 0; k < 2; ++k) dst[n][k] = *(const LAS bf16x8*)(lds + PG8_SB(b, h) + boff + n * 2048 + k * 1024); } while (0)
; #define PG8_MMA(ai, bj, At, Bt) do { __builtin_amdgcn_s_setprio(1); _Pragma("unroll") for (int m = 0; m < 4; ++m) _Pragma("unroll") for (int n = 0; n < 2; ++n) _Pragma("unroll") for (int k = 0; k < 2; ++k) \
;         acc[ai][bj][m][n] = __builtin_amdgcn_mfma_f32_16x16x32_bf16(Bt[n][k], At[m][k], acc[ai][bj][m][n], 0, 0, 0); __builtin_amdgcn_s_setprio(0); } while (0)
; #define PG8_WAIT_V(n) asm volatile("s_waitcnt vmcnt(" #n ")" ::: "memory")
; #define PG8_WAIT_L(n) asm volatile("s_waitcnt lgkmcnt(" #n ")" ::: "memory")
; #define PG8_BAR __builtin_amdgcn_s_barrier()
; #define PG8_SCHED __builtin_amdgcn_sched_barrier(0)
; template <class Epi, bool PERMA = false, bool DUAL = false, bool ALIGN_EPI = true, bool SP2 = true>
; __device__ __forceinline__ void gemm_phase(LAS unsigned char* lds, const Gemm g, const StaticOrder& S, const Epi& E) {
;     ...
;             PG8_WAIT_V(8); PG8_WAIT_L(0); PG8_BAR; PG8_MMA(1, 0, At, B0); PG8_MMA(1, 1, At, B1); PG8_BAR; PG8_SCHED;
;             PG8_LDB(B0, 1, 0); PG8_LDB(B1, 1, 1); PG8_SCHED; PG8_LDA(At, 1, 0); PG8_STAGE(PG8_SA(0, 1), a2 + hstepA, voffA);
;             PG8_WAIT_V(8); PG8_WAIT_L(0); PG8_BAR; PG8_MMA(0, 0, At, B0); PG8_MMA(0, 1, At, B1); PG8_BAR; PG8_SCHED;
	v_mfma_f32_16x16x32_bf16 v[60:63], v[144:147], v[176:179], v[60:63]
	v_mfma_f32_16x16x32_bf16 v[56:59], v[152:155], v[176:179], v[56:59]
	v_mfma_f32_16x16x32_bf16 v[52:55], v[144:147], v[184:187], v[52:55]
	v_mfma_f32_16x16x32_bf16 v[44:47], v[152:155], v[184:187], v[44:47]
	v_mfma_f32_16x16x32_bf16 v[36:39], v[144:147], v[206:209], v[36:39]
	v_mfma_f32_16x16x32_bf16 v[28:31], v[152:155], v[206:209], v[28:31]
	v_mfma_f32_16x16x32_bf16 v[20:23], v[144:147], v[214:217], v[20:23]
	v_mfma_f32_16x16x32_bf16 v[12:15], v[152:155], v[214:217], v[12:15]
	v_mfma_f32_16x16x32_bf16 v[60:63], v[148:151], v[180:183], v[60:63]
	v_mfma_f32_16x16x32_bf16 v[56:59], v[156:159], v[180:183], v[56:59]
	v_mfma_f32_16x16x32_bf16 v[52:55], v[148:151], v[188:191], v[52:55]
	v_mfma_f32_16x16x32_bf16 v[44:47], v[156:159], v[188:191], v[44:47]
	v_mfma_f32_16x16x32_bf16 v[36:39], v[148:151], v[210:213], v[36:39]
	v_mfma_f32_16x16x32_bf16 v[28:31], v[156:159], v[210:213], v[28:31]
	v_mfma_f32_16x16x32_bf16 v[20:23], v[148:151], v[218:221], v[20:23]
	v_mfma_f32_16x16x32_bf16 v[12:15], v[156:159], v[218:221], v[12:15]
	v_mfma_f32_16x16x32_bf16 v[48:51], v[160:163], v[176:179], v[48:51]
	v_mfma_f32_16x16x32_bf16 v[40:43], v[168:171], v[176:179], v[40:43]
	v_mfma_f32_16x16x32_bf16 v[32:35], v[160:163], v[184:187], v[32:35]
	v_mfma_f32_16x16x32_bf16 v[24:27], v[168:171], v[184:187], v[24:27]
	v_mfma_f32_16x16x32_bf16 v[16:19], v[160:163], v[206:209], v[16:19]
	v_mfma_f32_16x16x32_bf16 v[8:11], v[168:171], v[206:209], v[8:11]
	v_mfma_f32_16x16x32_bf16 v[4:7], v[160:163], v[214:217], v[4:7]
	v_mfma_f32_16x16x32_bf16 v[0:3], v[168:171], v[214:217], v[0:3]
	v_mfma_f32_16x16x32_bf16 v[48:51], v[164:167], v[180:183], v[48:51]
	v_mfma_f32_16x16x32_bf16 v[40:43], v[172:175], v[180:183], v[40:43]
	v_mfma_f32_16x16x32_bf16 v[32:35], v[164:167], v[188:191], v[32:35]
	v_mfma_f32_16x16x32_bf16 v[24:27], v[172:175], v[188:191], v[24:27]
	v_mfma_f32_16x16x32_bf16 v[16:19], v[164:167], v[210:213], v[16:19]
	v_mfma_f32_16x16x32_bf16 v[8:11], v[172:175], v[210:213], v[8:11]
	v_mfma_f32_16x16x32_bf16 v[4:7], v[164:167], v[218:221], v[4:7]
	v_mfma_f32_16x16x32_bf16 v[0:3], v[172:175], v[218:221], v[0:3]
	s_barrier
	s_setprio 0
	s_add_i32 s38, 0, 0x18000
	s_add_i32 s39, 0, 0x1c000
	v_add_u32_e32 v156, s38, v141
	v_add_u32_e32 v172, s39, v141
	ds_read_b128 v[144:147], v156
	ds_read_b128 v[148:151], v156 offset:1024
	ds_read_b128 v[152:155], v156 offset:2048
	ds_read_b128 v[156:159], v156 offset:3072
	ds_read_b128 v[160:163], v172
	ds_read_b128 v[164:167], v172 offset:1024
	ds_read_b128 v[168:171], v172 offset:2048
	ds_read_b128 v[172:175], v172 offset:3072
	s_add_u32 s18, s18, 0x80000
	s_addc_u32 s19, s19, 0
	s_mov_b32 m0, s23
	v_lshl_add_u64 v[238:239], s[18:19], 0, v[134:135]
	ds_read_b128 v[176:179], v143 offset:32768
	ds_read_b128 v[180:183], v143 offset:33792
	ds_read_b128 v[184:187], v143 offset:34816
	ds_read_b128 v[188:191], v143 offset:35840
	ds_read_b128 v[206:209], v143 offset:36864
	ds_read_b128 v[210:213], v143 offset:37888
	ds_read_b128 v[214:217], v143 offset:38912
	ds_read_b128 v[218:221], v143 offset:39936
	global_load_lds_dwordx4 v[238:239], off
	v_lshl_add_u64 v[238:239], s[18:19], 0, v[130:131]
	s_mov_b32 m0, s24
	s_nop 0
	global_load_lds_dwordx4 v[238:239], off
	s_waitcnt vmcnt(8)
	s_waitcnt lgkmcnt(0)
	s_setprio 1
	s_barrier
	v_mfma_f32_16x16x32_bf16 v[124:127], v[144:147], v[176:179], v[124:127]
	v_mfma_f32_16x16x32_bf16 v[120:123], v[152:155], v[176:179], v[120:123]
	v_mfma_f32_16x16x32_bf16 v[116:119], v[144:147], v[184:187], v[116:119]
	v_mfma_f32_16x16x32_bf16 v[108:111], v[152:155], v[184:187], v[108:111]
	v_mfma_f32_16x16x32_bf16 v[100:103], v[144:147], v[206:209], v[100:103]
	v_mfma_f32_16x16x32_bf16 v[92:95], v[152:155], v[206:209], v[92:95]
	v_mfma_f32_16x16x32_bf16 v[84:87], v[144:147], v[214:217], v[84:87]
	v_mfma_f32_16x16x32_bf16 v[76:79], v[152:155], v[214:217], v[76:79]
	v_mfma_f32_16x16x32_bf16 v[124:127], v[148:151], v[180:183], v[124:127]
	v_mfma_f32_16x16x32_bf16 v[120:123], v[156:159], v[180:183], v[120:123]
	v_mfma_f32_16x16x32_bf16 v[116:119], v[148:151], v[188:191], v[116:119]
	v_mfma_f32_16x16x32_bf16 v[108:111], v[156:159], v[188:191], v[108:111]
	v_mfma_f32_16x16x32_bf16 v[100:103], v[148:151], v[210:213], v[100:103]
	v_mfma_f32_16x16x32_bf16 v[92:95], v[156:159], v[210:213], v[92:95]
	v_mfma_f32_16x16x32_bf16 v[84:87], v[148:151], v[218:221], v[84:87]
	v_mfma_f32_16x16x32_bf16 v[76:79], v[156:159], v[218:221], v[76:79]
	v_mfma_f32_16x16x32_bf16 v[112:115], v[160:163], v[176:179], v[112:115]
	v_mfma_f32_16x16x32_bf16 v[104:107], v[168:171], v[176:179], v[104:107]
	v_mfma_f32_16x16x32_bf16 v[96:99], v[160:163], v[184:187], v[96:99]
	v_mfma_f32_16x16x32_bf16 v[88:91], v[168:171], v[184:187], v[88:91]
	v_mfma_f32_16x16x32_bf16 v[80:83], v[160:163], v[206:209], v[80:83]
	v_mfma_f32_16x16x32_bf16 v[72:75], v[168:171], v[206:209], v[72:75]
	v_mfma_f32_16x16x32_bf16 v[68:71], v[160:163], v[214:217], v[68:71]
	v_mfma_f32_16x16x32_bf16 v[64:67], v[168:171], v[214:217], v[64:67]
	v_mfma_f32_16x16x32_bf16 v[112:115], v[164:167], v[180:183], v[112:115]
	v_mfma_f32_16x16x32_bf16 v[104:107], v[172:175], v[180:183], v[104:107]
	v_mfma_f32_16x16x32_bf16 v[96:99], v[164:167], v[188:191], v[96:99]
	v_mfma_f32_16x16x32_bf16 v[88:91], v[172:175], v[188:191], v[88:91]
	v_mfma_f32_16x16x32_bf16 v[80:83], v[164:167], v[210:213], v[80:83]
	v_mfma_f32_16x16x32_bf16 v[72:75], v[172:175], v[210:213], v[72:75]
	v_mfma_f32_16x16x32_bf16 v[68:71], v[164:167], v[218:221], v[68:71]
	v_mfma_f32_16x16x32_bf16 v[64:67], v[172:175], v[218:221], v[64:67]
	s_barrier
; #define PG8_STAGE(bufoff, gbase, voff) do { _Pragma("unroll") for (int _i = 0; _i < 2; ++_i) \
;         __builtin_amdgcn_global_load_lds((const unsigned*)((const char*)(gbase) + (voff)[_i]), (LAS unsigned*)(lds + (bufoff) + ldsw + _i * 8192), 16, 0, 0); } while (0)
; #define PG8_LDA(dst, b, h) do { _Pragma("unroll") for (int m = 0; m < 4; ++m) _Pragma("unroll") for (int k = 0; k < 2; ++k) dst[m][k] = *(const LAS bf16x8*)(lds + PG8_SA(b, h) + aoff + m * 2048 + k * 1024); } while (0)
; #define PG8_MMA(ai, bj, At, Bt) do { __builtin_amdgcn_s_setprio(1); _Pragma("unroll") for (int m = 0; m < 4; ++m) _Pragma("unroll") for (int n = 0; n < 2; ++n) _Pragma("unroll") for (int k = 0; k < 2; ++k) \
;         acc[ai][bj][m][n] = __builtin_amdgcn_mfma_f32_16x16x32_bf16(Bt[n][k], At[m][k], acc[ai][bj][m][n], 0, 0, 0); __builtin_amdgcn_s_setprio(0); } while (0)
; #define PG8_WAIT_V(n) asm volatile("s_waitcnt vmcnt(" #n ")" ::: "memory")
; #define PG8_WAIT_L(n) asm volatile("s_waitcnt lgkmcnt(" #n ")" ::: "memory")
; #define PG8_BAR __builtin_amdgcn_s_barrier()
; #define PG8_SCHED __builtin_amdgcn_sched_barrier(0)
; template <class Epi, bool PERMA = false, bool DUAL = false, bool ALIGN_EPI = true, bool SP2 = true>
; __device__ __forceinline__ void gemm_phase(LAS unsigned char* lds, const Gemm g, const StaticOrder& S, const Epi& E) {
;     ...
;             PG8_LDA(At, 1, 1); PG8_STAGE(PG8_SB(1, 0), b3, voffB); PG8_STAGE(PG8_SB(1, 1), b3 + hstepB, voffB); PG8_STAGE(PG8_SA(1, 0), a3, voffA);
;             PG8_WAIT_V(8); PG8_WAIT_L(0); PG8_BAR; PG8_MMA(1, 0, At, B0); PG8_MMA(1, 1, At, B1); PG8_BAR; PG8_SCHED;
;     ...
;         if constexpr (ALIGN_EPI) { if (wr == 0) PG8_BAR; }
	s_setprio 0
	s_add_i32 s18, s38, s20
	v_lshl_add_u64 v[222:223], v[222:223], 0, s[46:47]
	s_mov_b32 m0, s18
	ds_read_b128 v[176:179], v143 offset:49152
	ds_read_b128 v[180:183], v143 offset:50176
	ds_read_b128 v[184:187], v143 offset:51200
	ds_read_b128 v[188:191], v143 offset:52224
	ds_read_b128 v[206:209], v143 offset:53248
	ds_read_b128 v[210:213], v143 offset:54272
	ds_read_b128 v[214:217], v143 offset:55296
	ds_read_b128 v[218:221], v143 offset:56320
	global_load_lds_dwordx4 v[222:223], off
	s_add_i32 m0, s18, 0x2000
	s_add_u32 s16, s16, 0x80080
	v_lshl_add_u64 v[222:223], v[224:225], 0, s[46:47]
	s_addc_u32 s17, s17, 0
	s_add_i32 s18, s39, s20
	global_load_lds_dwordx4 v[222:223], off
	v_lshl_add_u64 v[222:223], s[16:17], 0, v[132:133]
	s_mov_b32 m0, s18
	s_nop 0
	global_load_lds_dwordx4 v[222:223], off
	v_lshl_add_u64 v[222:223], s[16:17], 0, v[128:129]
	s_add_i32 m0, s18, 0x2000
	s_nop 0
	global_load_lds_dwordx4 v[222:223], off
	v_lshl_add_u64 v[222:223], v[226:227], 0, s[46:47]
	s_mov_b32 m0, s25
	s_nop 0
	global_load_lds_dwordx4 v[222:223], off
	v_lshl_add_u64 v[222:223], v[228:229], 0, s[46:47]
	s_mov_b32 m0, s26
	s_nop 0
	global_load_lds_dwordx4 v[222:223], off
	s_waitcnt vmcnt(8)
	s_waitcnt lgkmcnt(0)
	s_setprio 1
	s_barrier
	v_mfma_f32_16x16x32_bf16 v[60:63], v[144:147], v[176:179], v[60:63]
	v_mfma_f32_16x16x32_bf16 v[56:59], v[152:155], v[176:179], v[56:59]
	v_mfma_f32_16x16x32_bf16 v[52:55], v[144:147], v[184:187], v[52:55]
	v_mfma_f32_16x16x32_bf16 v[44:47], v[152:155], v[184:187], v[44:47]
	v_mfma_f32_16x16x32_bf16 v[36:39], v[144:147], v[206:209], v[36:39]
	v_mfma_f32_16x16x32_bf16 v[28:31], v[152:155], v[206:209], v[28:31]
	v_mfma_f32_16x16x32_bf16 v[20:23], v[144:147], v[214:217], v[20:23]
	v_mfma_f32_16x16x32_bf16 v[12:15], v[152:155], v[214:217], v[12:15]
	v_mfma_f32_16x16x32_bf16 v[60:63], v[148:151], v[180:183], v[60:63]
	v_mfma_f32_16x16x32_bf16 v[56:59], v[156:159], v[180:183], v[56:59]
	v_mfma_f32_16x16x32_bf16 v[52:55], v[148:151], v[188:191], v[52:55]
	v_mfma_f32_16x16x32_bf16 v[44:47], v[156:159], v[188:191], v[44:47]
	v_mfma_f32_16x16x32_bf16 v[36:39], v[148:151], v[210:213], v[36:39]
	v_mfma_f32_16x16x32_bf16 v[28:31], v[156:159], v[210:213], v[28:31]
	v_mfma_f32_16x16x32_bf16 v[20:23], v[148:151], v[218:221], v[20:23]
	v_mfma_f32_16x16x32_bf16 v[12:15], v[156:159], v[218:221], v[12:15]
	v_mfma_f32_16x16x32_bf16 v[48:51], v[160:163], v[176:179], v[48:51]
	v_mfma_f32_16x16x32_bf16 v[40:43], v[168:171], v[176:179], v[40:43]
	v_mfma_f32_16x16x32_bf16 v[32:35], v[160:163], v[184:187], v[32:35]
	v_mfma_f32_16x16x32_bf16 v[24:27], v[168:171], v[184:187], v[24:27]
	v_mfma_f32_16x16x32_bf16 v[16:19], v[160:163], v[206:209], v[16:19]
	v_mfma_f32_16x16x32_bf16 v[8:11], v[168:171], v[206:209], v[8:11]
	v_mfma_f32_16x16x32_bf16 v[4:7], v[160:163], v[214:217], v[4:7]
	v_mfma_f32_16x16x32_bf16 v[0:3], v[168:171], v[214:217], v[0:3]
	v_mfma_f32_16x16x32_bf16 v[48:51], v[164:167], v[180:183], v[48:51]
	v_mfma_f32_16x16x32_bf16 v[40:43], v[172:175], v[180:183], v[40:43]
	v_mfma_f32_16x16x32_bf16 v[32:35], v[164:167], v[188:191], v[32:35]
	v_mfma_f32_16x16x32_bf16 v[24:27], v[172:175], v[188:191], v[24:27]
	v_mfma_f32_16x16x32_bf16 v[16:19], v[164:167], v[210:213], v[16:19]
	v_mfma_f32_16x16x32_bf16 v[8:11], v[172:175], v[210:213], v[8:11]
	v_mfma_f32_16x16x32_bf16 v[4:7], v[164:167], v[218:221], v[4:7]
	v_mfma_f32_16x16x32_bf16 v[0:3], v[172:175], v[218:221], v[0:3]
	s_barrier
	s_setprio 0
	s_add_i32 s37, s37, 2
	s_add_u32 s14, s14, 0x100
	s_addc_u32 s15, s15, 0
	s_add_u32 s35, s35, 0x100
	s_addc_u32 s36, s36, 0
	s_cmp_gt_u32 s37, 29
	s_cbranch_scc0 .LBB0_130
	s_and_b64 vcc, exec, s[4:5]
	s_cbranch_vccz .LBB0_133
	s_barrier

; #define PG8_STAGE(bufoff, gbase, voff) do { _Pragma("unroll") for (int _i = 0; _i < 2; ++_i) \
;         __builtin_amdgcn_global_load_lds((const unsigned*)((const char*)(gbase) + (voff)[_i]), (LAS unsigned*)(lds + (bufoff) + ldsw + _i * 8192), 16, 0, 0); } while (0)
; #define PG8_LDA(dst, b, h) do { _Pragma("unroll") for (int m = 0; m < 4; ++m) _Pragma("unroll") for (int k = 0; k < 2; ++k) dst[m][k] = *(const LAS bf16x8*)(lds + PG8_SA(b, h) + aoff + m * 2048 + k * 1024); } while (0)
; #define PG8_LDB(dst, b, h) do { _Pragma("unroll") for (int n = 0; n < 2; ++n) _Pragma("unroll") for (int k = 0; k < 2; ++k) dst[n][k] = *(const LAS bf16x8*)(lds + PG8_SB(b, h) + boff + n * 2048 + k * 1024); } while (0)
; #define PG8_MMA(ai, bj, At, Bt) do { __builtin_amdgcn_s_setprio(1); _Pragma("unroll") for (int m = 0; m < 4; ++m) _Pragma("unroll") for (int n = 0; n < 2; ++n) _Pragma("unroll") for (int k = 0; k < 2; ++k) \
;         acc[ai][bj][m][n] = __builtin_amdgcn_mfma_f32_16x16x32_bf16(Bt[n][k], At[m][k], acc[ai][bj][m][n], 0, 0, 0); __builtin_amdgcn_s_setprio(0); } while (0)
; template <class Epi, bool PERMA = false, bool DUAL = false, bool ALIGN_EPI = true, bool SP2 = true>
; __device__ __forceinline__ void gemm_phase(LAS unsigned char* lds, const Gemm g, const StaticOrder& S, const Epi& E) {
;     ...
;         const char* nA = has_next ? (const char*)gA_ + (size_t)nxt.pm * tstepA : cA; const char* nB = has_next ? (const char*)gB_ + (size_t)nxt.pn * tstepB : cB;
;         for (int t = 0; t < nt; t += 2) {
;             const bool last = (t == nt - 2);
;             const char* a1 = cA + (size_t)(t + 1) * kstep;
;             const char* a2 = last ? nA : cA + (size_t)(t + 2) * kstep; const char* b2 = last ? nB : cB + (size_t)(t + 2) * kstep;
;             const char* a3 = a2 + kstep; const char* b3 = b2 + kstep;
;             if constexpr (SP2) {
;             PG8_LDB(B0, 0, 0); PG8_LDB(B1, 0, 1); PG8_SCHED; PG8_LDA(At, 0, 0); PG8_STAGE(PG8_SA(1, 1), a1 + hstepA, voffA);
;             PG8_WAIT_V(8); PG8_WAIT_L(0); PG8_BAR; PG8_MMA(0, 0, At, B0); PG8_MMA(0, 1, At, B1); PG8_BAR; PG8_SCHED;
;             PG8_LDA(At, 0, 1); PG8_STAGE(PG8_SB(0, 0), b2, voffB); PG8_STAGE(PG8_SB(0, 1), b2 + hstepB, voffB); PG8_STAGE(PG8_SA(0, 0), a2, voffA);
;             PG8_WAIT_V(8); PG8_WAIT_L(0); PG8_BAR; PG8_MMA(1, 0, At, B0); PG8_MMA(1, 1, At, B1); PG8_BAR; PG8_SCHED;
.LBB0_329:
	s_add_u32 s0, s12, 0x100
	s_addc_u32 s1, s13, 0
	s_add_i32 s38, 0, 0x10000
	s_cmp_eq_u32 s37, 4
	s_cselect_b32 s17, s9, s1
	s_cselect_b32 s16, s8, s0
	s_cselect_b32 s15, s7, s36
	s_cselect_b32 s14, s34, s35
	s_add_i32 s39, 0, 0x14000
	v_add_u32_e32 v140, s38, v193
	v_add_u32_e32 v156, s39, v193
	ds_read_b128 v[128:131], v140
	ds_read_b128 v[132:135], v140 offset:1024
	ds_read_b128 v[136:139], v140 offset:2048
	ds_read_b128 v[140:143], v140 offset:3072
	ds_read_b128 v[144:147], v156
	ds_read_b128 v[148:151], v156 offset:1024
	ds_read_b128 v[152:155], v156 offset:2048
	ds_read_b128 v[156:159], v156 offset:3072
	v_lshl_add_u64 v[220:221], s[12:13], 0, v[216:217]
	s_add_i32 m0, s19, 0xc000
	ds_read_b128 v[160:163], v238
	ds_read_b128 v[164:167], v238 offset:1024
	ds_read_b128 v[168:171], v238 offset:2048
	ds_read_b128 v[172:175], v238 offset:3072
	ds_read_b128 v[176:179], v238 offset:4096
	ds_read_b128 v[180:183], v238 offset:5120
	ds_read_b128 v[184:187], v238 offset:6144
	ds_read_b128 v[188:191], v238 offset:7168
	global_load_lds_dwordx4 v[220:221], off
	v_lshl_add_u64 v[220:221], s[12:13], 0, v[218:219]
	s_add_i32 m0, s19, 0xe000
	s_nop 0
	global_load_lds_dwordx4 v[220:221], off
	s_waitcnt vmcnt(8)
	s_waitcnt lgkmcnt(0)
	s_setprio 1
	s_barrier
	v_mfma_f32_16x16x32_bf16 v[124:127], v[128:131], v[160:163], v[124:127]
	v_mfma_f32_16x16x32_bf16 v[120:123], v[136:139], v[160:163], v[120:123]
	v_mfma_f32_16x16x32_bf16 v[108:111], v[128:131], v[168:171], v[108:111]
	v_mfma_f32_16x16x32_bf16 v[104:107], v[136:139], v[168:171], v[104:107]
	v_mfma_f32_16x16x32_bf16 v[92:95], v[128:131], v[176:179], v[92:95]
	v_mfma_f32_16x16x32_bf16 v[88:91], v[136:139], v[176:179], v[88:91]
	v_mfma_f32_16x16x32_bf16 v[76:79], v[128:131], v[184:187], v[76:79]
	v_mfma_f32_16x16x32_bf16 v[72:75], v[136:139], v[184:187], v[72:75]
	v_mfma_f32_16x16x32_bf16 v[124:127], v[132:135], v[164:167], v[124:127]
	v_mfma_f32_16x16x32_bf16 v[120:123], v[140:143], v[164:167], v[120:123]
	v_mfma_f32_16x16x32_bf16 v[108:111], v[132:135], v[172:175], v[108:111]
	v_mfma_f32_16x16x32_bf16 v[104:107], v[140:143], v[172:175], v[104:107]
	v_mfma_f32_16x16x32_bf16 v[92:95], v[132:135], v[180:183], v[92:95]
	v_mfma_f32_16x16x32_bf16 v[88:91], v[140:143], v[180:183], v[88:91]
	v_mfma_f32_16x16x32_bf16 v[76:79], v[132:135], v[188:191], v[76:79]
	v_mfma_f32_16x16x32_bf16 v[72:75], v[140:143], v[188:191], v[72:75]
	v_mfma_f32_16x16x32_bf16 v[116:119], v[144:147], v[160:163], v[116:119]
	v_mfma_f32_16x16x32_bf16 v[112:115], v[152:155], v[160:163], v[112:115]
	v_mfma_f32_16x16x32_bf16 v[100:103], v[144:147], v[168:171], v[100:103]
	v_mfma_f32_16x16x32_bf16 v[96:99], v[152:155], v[168:171], v[96:99]
	v_mfma_f32_16x16x32_bf16 v[84:87], v[144:147], v[176:179], v[84:87]
	v_mfma_f32_16x16x32_bf16 v[80:83], v[152:155], v[176:179], v[80:83]
	v_mfma_f32_16x16x32_bf16 v[68:71], v[144:147], v[184:187], v[68:71]
	v_mfma_f32_16x16x32_bf16 v[64:67], v[152:155], v[184:187], v[64:67]
	v_mfma_f32_16x16x32_bf16 v[116:119], v[148:151], v[164:167], v[116:119]
	v_mfma_f32_16x16x32_bf16 v[112:115], v[156:159], v[164:167], v[112:115]
	v_mfma_f32_16x16x32_bf16 v[100:103], v[148:151], v[172:175], v[100:103]
	v_mfma_f32_16x16x32_bf16 v[96:99], v[156:159], v[172:175], v[96:99]
	v_mfma_f32_16x16x32_bf16 v[84:87], v[148:151], v[180:183], v[84:87]
	v_mfma_f32_16x16x32_bf16 v[80:83], v[156:159], v[180:183], v[80:83]
	v_mfma_f32_16x16x32_bf16 v[68:71], v[148:151], v[188:191], v[68:71]
	v_mfma_f32_16x16x32_bf16 v[64:67], v[156:159], v[188:191], v[64:67]
	s_barrier
	s_setprio 0
	s_add_i32 s12, s38, s18
	v_lshl_add_u64 v[220:221], s[14:15], 0, v[210:211]
	s_mov_b32 m0, s12
	ds_read_b128 v[160:163], v238 offset:16384
	ds_read_b128 v[164:167], v238 offset:17408
	ds_read_b128 v[168:171], v238 offset:18432
	ds_read_b128 v[172:175], v238 offset:19456
	ds_read_b128 v[176:179], v238 offset:20480
	ds_read_b128 v[180:183], v238 offset:21504
	ds_read_b128 v[184:187], v238 offset:22528
	ds_read_b128 v[188:191], v238 offset:23552
	global_load_lds_dwordx4 v[220:221], off
	s_add_i32 m0, s12, 0x2000
	s_add_u32 s12, s14, 0x20000
	v_lshl_add_u64 v[222:223], s[14:15], 0, v[206:207]
	s_addc_u32 s13, s15, 0
	s_add_i32 s38, s39, s18
	global_load_lds_dwordx4 v[222:223], off
	v_lshl_add_u64 v[224:225], s[12:13], 0, v[210:211]
	s_mov_b32 m0, s38
	v_lshl_add_u64 v[226:227], s[16:17], 0, v[208:209]
	global_load_lds_dwordx4 v[224:225], off
	v_lshl_add_u64 v[224:225], s[12:13], 0, v[206:207]
	s_add_i32 m0, s38, 0x2000
	s_nop 0
	global_load_lds_dwordx4 v[224:225], off
	v_lshl_add_u64 v[224:225], s[16:17], 0, v[212:213]
	s_mov_b32 m0, s19
	s_nop 0
	global_load_lds_dwordx4 v[224:225], off
	s_mov_b32 m0, s20
	s_nop 0
	global_load_lds_dwordx4 v[226:227], off
	s_waitcnt vmcnt(8)
	s_waitcnt lgkmcnt(0)
	s_setprio 1
	s_barrier
; #define PG8_STAGE(bufoff, gbase, voff) do { _Pragma("unroll") for (int _i = 0; _i < 2; ++_i) \
;         __builtin_amdgcn_global_load_lds((const unsigned*)((const char*)(gbase) + (voff)[_i]), (LAS unsigned*)(lds + (bufoff) + ldsw + _i * 8192), 16, 0, 0); } while (0)
; #define PG8_LDA(dst, b, h) do { _Pragma("unroll") for (int m = 0; m < 4; ++m) _Pragma("unroll") for (int k = 0; k < 2; ++k) dst[m][k] = *(const LAS bf16x8*)(lds + PG8_SA(b, h) + aoff + m * 2048 + k * 1024); } while (0)
; #define PG8_LDB(dst, b, h) do { _Pragma("unroll") for (int n = 0; n < 2; ++n) _Pragma("unroll") for (int k = 0; k < 2; ++k) dst[n][k] = *(const LAS bf16x8*)(lds + PG8_SB(b, h) + boff + n * 2048 + k * 1024); } while (0)
; #define PG8_MMA(ai, bj, At, Bt) do { __builtin_amdgcn_s_setprio(1); _Pragma("unroll") for (int m = 0; m < 4; ++m) _Pragma("unroll") for (int n = 0; n < 2; ++n) _Pragma("unroll") for (int k = 0; k < 2; ++k) \
;         acc[ai][bj][m][n] = __builtin_amdgcn_mfma_f32_16x16x32_bf16(Bt[n][k], At[m][k], acc[ai][bj][m][n], 0, 0, 0); __builtin_amdgcn_s_setprio(0); } while (0)
; #define PG8_WAIT_V(n) asm volatile("s_waitcnt vmcnt(" #n ")" ::: "memory")
; #define PG8_WAIT_L(n) asm volatile("s_waitcnt lgkmcnt(" #n ")" ::: "memory")
; #define PG8_BAR __builtin_amdgcn_s_barrier()
; #define PG8_SCHED __builtin_amdgcn_sched_barrier(0)
; template <class Epi, bool PERMA = false, bool DUAL = false, bool ALIGN_EPI = true, bool SP2 = true>
; __device__ __forceinline__ void gemm_phase(LAS unsigned char* lds, const Gemm g, const StaticOrder& S, const Epi& E) {
;     ...
;             PG8_WAIT_V(8); PG8_WAIT_L(0); PG8_BAR; PG8_MMA(1, 0, At, B0); PG8_MMA(1, 1, At, B1); PG8_BAR; PG8_SCHED;
;             PG8_LDB(B0, 1, 0); PG8_LDB(B1, 1, 1); PG8_SCHED; PG8_LDA(At, 1, 0); PG8_STAGE(PG8_SA(0, 1), a2 + hstepA, voffA);
;             PG8_WAIT_V(8); PG8_WAIT_L(0); PG8_BAR; PG8_MMA(0, 0, At, B0); PG8_MMA(0, 1, At, B1); PG8_BAR; PG8_SCHED;
	v_mfma_f32_16x16x32_bf16 v[60:63], v[128:131], v[160:163], v[60:63]
	v_mfma_f32_16x16x32_bf16 v[56:59], v[136:139], v[160:163], v[56:59]
	v_mfma_f32_16x16x32_bf16 v[44:47], v[128:131], v[168:171], v[44:47]
	v_mfma_f32_16x16x32_bf16 v[40:43], v[136:139], v[168:171], v[40:43]
	v_mfma_f32_16x16x32_bf16 v[28:31], v[128:131], v[176:179], v[28:31]
	v_mfma_f32_16x16x32_bf16 v[24:27], v[136:139], v[176:179], v[24:27]
	v_mfma_f32_16x16x32_bf16 v[12:15], v[128:131], v[184:187], v[12:15]
	v_mfma_f32_16x16x32_bf16 v[8:11], v[136:139], v[184:187], v[8:11]
	v_mfma_f32_16x16x32_bf16 v[60:63], v[132:135], v[164:167], v[60:63]
	v_mfma_f32_16x16x32_bf16 v[56:59], v[140:143], v[164:167], v[56:59]
	v_mfma_f32_16x16x32_bf16 v[44:47], v[132:135], v[172:175], v[44:47]
	v_mfma_f32_16x16x32_bf16 v[40:43], v[140:143], v[172:175], v[40:43]
	v_mfma_f32_16x16x32_bf16 v[28:31], v[132:135], v[180:183], v[28:31]
	v_mfma_f32_16x16x32_bf16 v[24:27], v[140:143], v[180:183], v[24:27]
	v_mfma_f32_16x16x32_bf16 v[12:15], v[132:135], v[188:191], v[12:15]
	v_mfma_f32_16x16x32_bf16 v[8:11], v[140:143], v[188:191], v[8:11]
	v_mfma_f32_16x16x32_bf16 v[52:55], v[144:147], v[160:163], v[52:55]
	v_mfma_f32_16x16x32_bf16 v[48:51], v[152:155], v[160:163], v[48:51]
	v_mfma_f32_16x16x32_bf16 v[36:39], v[144:147], v[168:171], v[36:39]
	v_mfma_f32_16x16x32_bf16 v[32:35], v[152:155], v[168:171], v[32:35]
	v_mfma_f32_16x16x32_bf16 v[20:23], v[144:147], v[176:179], v[20:23]
	v_mfma_f32_16x16x32_bf16 v[16:19], v[152:155], v[176:179], v[16:19]
	v_mfma_f32_16x16x32_bf16 v[4:7], v[144:147], v[184:187], v[4:7]
	v_mfma_f32_16x16x32_bf16 v[0:3], v[152:155], v[184:187], v[0:3]
	v_mfma_f32_16x16x32_bf16 v[52:55], v[148:151], v[164:167], v[52:55]
	v_mfma_f32_16x16x32_bf16 v[48:51], v[156:159], v[164:167], v[48:51]
	v_mfma_f32_16x16x32_bf16 v[36:39], v[148:151], v[172:175], v[36:39]
	v_mfma_f32_16x16x32_bf16 v[32:35], v[156:159], v[172:175], v[32:35]
	v_mfma_f32_16x16x32_bf16 v[20:23], v[148:151], v[180:183], v[20:23]
	v_mfma_f32_16x16x32_bf16 v[16:19], v[156:159], v[180:183], v[16:19]
	v_mfma_f32_16x16x32_bf16 v[4:7], v[148:151], v[188:191], v[4:7]
	v_mfma_f32_16x16x32_bf16 v[0:3], v[156:159], v[188:191], v[0:3]
	s_barrier
	s_setprio 0
	s_add_i32 s38, 0, 0x18000
	s_add_i32 s39, 0, 0x1c000
	v_add_u32_e32 v140, s38, v193
	v_add_u32_e32 v156, s39, v193
	ds_read_b128 v[128:131], v140
	ds_read_b128 v[132:135], v140 offset:1024
	ds_read_b128 v[136:139], v140 offset:2048
	ds_read_b128 v[140:143], v140 offset:3072
	ds_read_b128 v[144:147], v156
	ds_read_b128 v[148:151], v156 offset:1024
	ds_read_b128 v[152:155], v156 offset:2048
	ds_read_b128 v[156:159], v156 offset:3072
	s_add_u32 s12, s16, 0x180000
	s_addc_u32 s13, s17, 0
	s_mov_b32 m0, s21
	v_lshl_add_u64 v[228:229], s[12:13], 0, v[212:213]
	ds_read_b128 v[160:163], v238 offset:32768
	ds_read_b128 v[164:167], v238 offset:33792
	ds_read_b128 v[168:171], v238 offset:34816
	ds_read_b128 v[172:175], v238 offset:35840
	ds_read_b128 v[176:179], v238 offset:36864
	ds_read_b128 v[180:183], v238 offset:37888
	ds_read_b128 v[184:187], v238 offset:38912
	ds_read_b128 v[188:191], v238 offset:39936
	global_load_lds_dwordx4 v[228:229], off
	v_lshl_add_u64 v[228:229], s[12:13], 0, v[208:209]
	s_mov_b32 m0, s22
	s_nop 0
	global_load_lds_dwordx4 v[228:229], off
	s_waitcnt vmcnt(8)
	s_waitcnt lgkmcnt(0)
	s_setprio 1
	s_barrier
	v_mfma_f32_16x16x32_bf16 v[124:127], v[128:131], v[160:163], v[124:127]
	v_mfma_f32_16x16x32_bf16 v[120:123], v[136:139], v[160:163], v[120:123]
	v_mfma_f32_16x16x32_bf16 v[108:111], v[128:131], v[168:171], v[108:111]
	v_mfma_f32_16x16x32_bf16 v[104:107], v[136:139], v[168:171], v[104:107]
	v_mfma_f32_16x16x32_bf16 v[92:95], v[128:131], v[176:179], v[92:95]
	v_mfma_f32_16x16x32_bf16 v[88:91], v[136:139], v[176:179], v[88:91]
	v_mfma_f32_16x16x32_bf16 v[76:79], v[128:131], v[184:187], v[76:79]
	v_mfma_f32_16x16x32_bf16 v[72:75], v[136:139], v[184:187], v[72:75]
	v_mfma_f32_16x16x32_bf16 v[124:127], v[132:135], v[164:167], v[124:127]
	v_mfma_f32_16x16x32_bf16 v[120:123], v[140:143], v[164:167], v[120:123]
	v_mfma_f32_16x16x32_bf16 v[108:111], v[132:135], v[172:175], v[108:111]
	v_mfma_f32_16x16x32_bf16 v[104:107], v[140:143], v[172:175], v[104:107]
	v_mfma_f32_16x16x32_bf16 v[92:95], v[132:135], v[180:183], v[92:95]
	v_mfma_f32_16x16x32_bf16 v[88:91], v[140:143], v[180:183], v[88:91]
	v_mfma_f32_16x16x32_bf16 v[76:79], v[132:135], v[188:191], v[76:79]
	v_mfma_f32_16x16x32_bf16 v[72:75], v[140:143], v[188:191], v[72:75]
	v_mfma_f32_16x16x32_bf16 v[116:119], v[144:147], v[160:163], v[116:119]
	v_mfma_f32_16x16x32_bf16 v[112:115], v[152:155], v[160:163], v[112:115]
	v_mfma_f32_16x16x32_bf16 v[100:103], v[144:147], v[168:171], v[100:103]
	v_mfma_f32_16x16x32_bf16 v[96:99], v[152:155], v[168:171], v[96:99]
	v_mfma_f32_16x16x32_bf16 v[84:87], v[144:147], v[176:179], v[84:87]
	v_mfma_f32_16x16x32_bf16 v[80:83], v[152:155], v[176:179], v[80:83]
	v_mfma_f32_16x16x32_bf16 v[68:71], v[144:147], v[184:187], v[68:71]
	v_mfma_f32_16x16x32_bf16 v[64:67], v[152:155], v[184:187], v[64:67]
	v_mfma_f32_16x16x32_bf16 v[116:119], v[148:151], v[164:167], v[116:119]
	v_mfma_f32_16x16x32_bf16 v[112:115], v[156:159], v[164:167], v[112:115]
	v_mfma_f32_16x16x32_bf16 v[100:103], v[148:151], v[172:175], v[100:103]
	v_mfma_f32_16x16x32_bf16 v[96:99], v[156:159], v[172:175], v[96:99]
	v_mfma_f32_16x16x32_bf16 v[84:87], v[148:151], v[180:183], v[84:87]
	v_mfma_f32_16x16x32_bf16 v[80:83], v[156:159], v[180:183], v[80:83]
	v_mfma_f32_16x16x32_bf16 v[68:71], v[148:151], v[188:191], v[68:71]
	v_mfma_f32_16x16x32_bf16 v[64:67], v[156:159], v[188:191], v[64:67]
	s_barrier
; #define PG8_STAGE(bufoff, gbase, voff) do { _Pragma("unroll") for (int _i = 0; _i < 2; ++_i) \
;         __builtin_amdgcn_global_load_lds((const unsigned*)((const char*)(gbase) + (voff)[_i]), (LAS unsigned*)(lds + (bufoff) + ldsw + _i * 8192), 16, 0, 0); } while (0)
; #define PG8_LDA(dst, b, h) do { _Pragma("unroll") for (int m = 0; m < 4; ++m) _Pragma("unroll") for (int k = 0; k < 2; ++k) dst[m][k] = *(const LAS bf16x8*)(lds + PG8_SA(b, h) + aoff + m * 2048 + k * 1024); } while (0)
; #define PG8_MMA(ai, bj, At, Bt) do { __builtin_amdgcn_s_setprio(1); _Pragma("unroll") for (int m = 0; m < 4; ++m) _Pragma("unroll") for (int n = 0; n < 2; ++n) _Pragma("unroll") for (int k = 0; k < 2; ++k) \
;         acc[ai][bj][m][n] = __builtin_amdgcn_mfma_f32_16x16x32_bf16(Bt[n][k], At[m][k], acc[ai][bj][m][n], 0, 0, 0); __builtin_amdgcn_s_setprio(0); } while (0)
; #define PG8_WAIT_V(n) asm volatile("s_waitcnt vmcnt(" #n ")" ::: "memory")
; #define PG8_WAIT_L(n) asm volatile("s_waitcnt lgkmcnt(" #n ")" ::: "memory")
; #define PG8_BAR __builtin_amdgcn_s_barrier()
; #define PG8_SCHED __builtin_amdgcn_sched_barrier(0)
; template <class Epi, bool PERMA = false, bool DUAL = false, bool ALIGN_EPI = true, bool SP2 = true>
; __device__ __forceinline__ void gemm_phase(LAS unsigned char* lds, const Gemm g, const StaticOrder& S, const Epi& E) {
;     ...
;             PG8_LDA(At, 1, 1); PG8_STAGE(PG8_SB(1, 0), b3, voffB); PG8_STAGE(PG8_SB(1, 1), b3 + hstepB, voffB); PG8_STAGE(PG8_SA(1, 0), a3, voffA);
;             PG8_WAIT_V(8); PG8_WAIT_L(0); PG8_BAR; PG8_MMA(1, 0, At, B0); PG8_MMA(1, 1, At, B1); PG8_BAR; PG8_SCHED;
;     ...
;         if constexpr (ALIGN_EPI) { if (wr == 0) PG8_BAR; }
	s_setprio 0
	s_add_i32 s12, s38, s18
	v_lshl_add_u64 v[220:221], v[220:221], 0, s[46:47]
	s_mov_b32 m0, s12
	ds_read_b128 v[160:163], v238 offset:49152
	ds_read_b128 v[164:167], v238 offset:50176
	ds_read_b128 v[168:171], v238 offset:51200
	ds_read_b128 v[172:175], v238 offset:52224
	ds_read_b128 v[176:179], v238 offset:53248
	ds_read_b128 v[180:183], v238 offset:54272
	ds_read_b128 v[184:187], v238 offset:55296
	ds_read_b128 v[188:191], v238 offset:56320
	global_load_lds_dwordx4 v[220:221], off
	s_add_i32 m0, s12, 0x2000
	s_add_u32 s12, s14, 0x20080
	v_lshl_add_u64 v[220:221], v[222:223], 0, s[46:47]
	s_addc_u32 s13, s15, 0
	s_add_i32 s14, s39, s18
	global_load_lds_dwordx4 v[220:221], off
	v_lshl_add_u64 v[220:221], s[12:13], 0, v[210:211]
	s_mov_b32 m0, s14
	s_nop 0
	global_load_lds_dwordx4 v[220:221], off
	v_lshl_add_u64 v[220:221], s[12:13], 0, v[206:207]
	s_add_i32 m0, s14, 0x2000
	s_nop 0
	global_load_lds_dwordx4 v[220:221], off
	v_lshl_add_u64 v[220:221], v[224:225], 0, s[46:47]
	s_mov_b32 m0, s25
	s_nop 0
	global_load_lds_dwordx4 v[220:221], off
	v_lshl_add_u64 v[220:221], v[226:227], 0, s[46:47]
	s_mov_b32 m0, s26
	s_nop 0
	global_load_lds_dwordx4 v[220:221], off
	s_waitcnt vmcnt(8)
	s_waitcnt lgkmcnt(0)
	s_setprio 1
	s_barrier
	v_mfma_f32_16x16x32_bf16 v[60:63], v[128:131], v[160:163], v[60:63]
	v_mfma_f32_16x16x32_bf16 v[56:59], v[136:139], v[160:163], v[56:59]
	v_mfma_f32_16x16x32_bf16 v[44:47], v[128:131], v[168:171], v[44:47]
	v_mfma_f32_16x16x32_bf16 v[40:43], v[136:139], v[168:171], v[40:43]
	v_mfma_f32_16x16x32_bf16 v[28:31], v[128:131], v[176:179], v[28:31]
	v_mfma_f32_16x16x32_bf16 v[24:27], v[136:139], v[176:179], v[24:27]
	v_mfma_f32_16x16x32_bf16 v[12:15], v[128:131], v[184:187], v[12:15]
	v_mfma_f32_16x16x32_bf16 v[8:11], v[136:139], v[184:187], v[8:11]
	v_mfma_f32_16x16x32_bf16 v[60:63], v[132:135], v[164:167], v[60:63]
	v_mfma_f32_16x16x32_bf16 v[56:59], v[140:143], v[164:167], v[56:59]
	v_mfma_f32_16x16x32_bf16 v[44:47], v[132:135], v[172:175], v[44:47]
	v_mfma_f32_16x16x32_bf16 v[40:43], v[140:143], v[172:175], v[40:43]
	v_mfma_f32_16x16x32_bf16 v[28:31], v[132:135], v[180:183], v[28:31]
	v_mfma_f32_16x16x32_bf16 v[24:27], v[140:143], v[180:183], v[24:27]
	v_mfma_f32_16x16x32_bf16 v[12:15], v[132:135], v[188:191], v[12:15]
	v_mfma_f32_16x16x32_bf16 v[8:11], v[140:143], v[188:191], v[8:11]
	v_mfma_f32_16x16x32_bf16 v[52:55], v[144:147], v[160:163], v[52:55]
	v_mfma_f32_16x16x32_bf16 v[48:51], v[152:155], v[160:163], v[48:51]
	v_mfma_f32_16x16x32_bf16 v[36:39], v[144:147], v[168:171], v[36:39]
	v_mfma_f32_16x16x32_bf16 v[32:35], v[152:155], v[168:171], v[32:35]
	v_mfma_f32_16x16x32_bf16 v[20:23], v[144:147], v[176:179], v[20:23]
	v_mfma_f32_16x16x32_bf16 v[16:19], v[152:155], v[176:179], v[16:19]
	v_mfma_f32_16x16x32_bf16 v[4:7], v[144:147], v[184:187], v[4:7]
	v_mfma_f32_16x16x32_bf16 v[0:3], v[152:155], v[184:187], v[0:3]
	v_mfma_f32_16x16x32_bf16 v[52:55], v[148:151], v[164:167], v[52:55]
	v_mfma_f32_16x16x32_bf16 v[48:51], v[156:159], v[164:167], v[48:51]
	v_mfma_f32_16x16x32_bf16 v[36:39], v[148:151], v[172:175], v[36:39]
	v_mfma_f32_16x16x32_bf16 v[32:35], v[156:159], v[172:175], v[32:35]
	v_mfma_f32_16x16x32_bf16 v[20:23], v[148:151], v[180:183], v[20:23]
	v_mfma_f32_16x16x32_bf16 v[16:19], v[156:159], v[180:183], v[16:19]
	v_mfma_f32_16x16x32_bf16 v[4:7], v[148:151], v[188:191], v[4:7]
	v_mfma_f32_16x16x32_bf16 v[0:3], v[156:159], v[188:191], v[0:3]
	s_barrier
	s_setprio 0
	s_add_i32 s37, s37, 2
	s_add_u32 s35, s35, 0x100
	s_addc_u32 s36, s36, 0
	s_cmp_gt_u32 s37, 5
	s_mov_b64 s[12:13], s[0:1]
	s_cbranch_scc0 .LBB0_329
	s_and_b64 vcc, exec, s[4:5]
	s_cbranch_vccz .LBB0_332
	s_barrier

; #define PG8_STAGE(bufoff, gbase, voff) do { _Pragma("unroll") for (int _i = 0; _i < 2; ++_i) \
;         __builtin_amdgcn_global_load_lds((const unsigned*)((const char*)(gbase) + (voff)[_i]), (LAS unsigned*)(lds + (bufoff) + ldsw + _i * 8192), 16, 0, 0); } while (0)
; #define PG8_LDA(dst, b, h) do { _Pragma("unroll") for (int m = 0; m < 4; ++m) _Pragma("unroll") for (int k = 0; k < 2; ++k) dst[m][k] = *(const LAS bf16x8*)(lds + PG8_SA(b, h) + aoff + m * 2048 + k * 1024); } while (0)
; #define PG8_LDB(dst, b, h) do { _Pragma("unroll") for (int n = 0; n < 2; ++n) _Pragma("unroll") for (int k = 0; k < 2; ++k) dst[n][k] = *(const LAS bf16x8*)(lds + PG8_SB(b, h) + boff + n * 2048 + k * 1024); } while (0)
; #define PG8_MMA(ai, bj, At, Bt) do { __builtin_amdgcn_s_setprio(1); _Pragma("unroll") for (int m = 0; m < 4; ++m) _Pragma("unroll") for (int n = 0; n < 2; ++n) _Pragma("unroll") for (int k = 0; k < 2; ++k) \
;         acc[ai][bj][m][n] = __builtin_amdgcn_mfma_f32_16x16x32_bf16(Bt[n][k], At[m][k], acc[ai][bj][m][n], 0, 0, 0); __builtin_amdgcn_s_setprio(0); } while (0)
; template <class Epi, bool PERMA = false, bool DUAL = false, bool ALIGN_EPI = true, bool SP2 = true>
; __device__ __forceinline__ void gemm_phase(LAS unsigned char* lds, const Gemm g, const StaticOrder& S, const Epi& E) {
;     ...
;         const char* nA = has_next ? (const char*)gA_ + (size_t)nxt.pm * tstepA : cA; const char* nB = has_next ? (const char*)gB_ + (size_t)nxt.pn * tstepB : cB;
;         for (int t = 0; t < nt; t += 2) {
;             const bool last = (t == nt - 2);
;             const char* a1 = cA + (size_t)(t + 1) * kstep;
;             const char* a2 = last ? nA : cA + (size_t)(t + 2) * kstep; const char* b2 = last ? nB : cB + (size_t)(t + 2) * kstep;
;             const char* a3 = a2 + kstep; const char* b3 = b2 + kstep;
;             if constexpr (SP2) {
;             PG8_LDB(B0, 0, 0); PG8_LDB(B1, 0, 1); PG8_SCHED; PG8_LDA(At, 0, 0); PG8_STAGE(PG8_SA(1, 1), a1 + hstepA, voffA);
;             PG8_WAIT_V(8); PG8_WAIT_L(0); PG8_BAR; PG8_MMA(0, 0, At, B0); PG8_MMA(0, 1, At, B1); PG8_BAR; PG8_SCHED;
;             PG8_LDA(At, 0, 1); PG8_STAGE(PG8_SB(0, 0), b2, voffB); PG8_STAGE(PG8_SB(0, 1), b2 + hstepB, voffB); PG8_STAGE(PG8_SA(0, 0), a2, voffA);
;             PG8_WAIT_V(8); PG8_WAIT_L(0); PG8_BAR; PG8_MMA(1, 0, At, B0); PG8_MMA(1, 1, At, B1); PG8_BAR; PG8_SCHED;
.LBB0_405:
	s_add_u32 s16, s14, 0xfff00080
	s_addc_u32 s17, s15, -1
	s_add_i32 s38, 0, 0x10000
	s_cmp_eq_u32 s37, 28
	s_cselect_b32 s19, s9, s17
	s_cselect_b32 s18, s33, s16
	v_add_u32_e32 v142, s38, v144
	s_cselect_b32 s17, s7, s36
	s_cselect_b32 s16, s34, s35
	s_add_i32 s40, 0, 0x14000
	ds_read_b128 v[146:149], v142
	ds_read_b128 v[150:153], v142 offset:1024
	ds_read_b128 v[154:157], v142 offset:2048
	ds_read_b128 v[158:161], v142 offset:3072
	v_add_u32_e32 v142, s40, v144
	ds_read_b128 v[162:165], v142
	ds_read_b128 v[166:169], v142 offset:1024
	ds_read_b128 v[170:173], v142 offset:2048
	ds_read_b128 v[174:177], v142 offset:3072
	v_lshl_add_u64 v[142:143], s[14:15], 0, v[138:139]
	s_add_i32 m0, s21, 0xc000
	ds_read_b128 v[178:181], v145
	ds_read_b128 v[182:185], v145 offset:1024
	ds_read_b128 v[186:189], v145 offset:2048
	ds_read_b128 v[206:209], v145 offset:3072
	ds_read_b128 v[210:213], v145 offset:4096
	ds_read_b128 v[214:217], v145 offset:5120
	ds_read_b128 v[218:221], v145 offset:6144
	ds_read_b128 v[222:225], v145 offset:7168
	global_load_lds_dwordx4 v[142:143], off
	v_lshl_add_u64 v[142:143], s[14:15], 0, v[140:141]
	s_add_i32 m0, s21, 0xe000
	s_nop 0
	global_load_lds_dwordx4 v[142:143], off
	s_waitcnt vmcnt(8)
	s_waitcnt lgkmcnt(0)
	s_setprio 1
	s_barrier
	v_mfma_f32_16x16x32_bf16 v[124:127], v[146:149], v[178:181], v[124:127]
	v_mfma_f32_16x16x32_bf16 v[120:123], v[154:157], v[178:181], v[120:123]
	v_mfma_f32_16x16x32_bf16 v[116:119], v[146:149], v[186:189], v[116:119]
	v_mfma_f32_16x16x32_bf16 v[108:111], v[154:157], v[186:189], v[108:111]
	v_mfma_f32_16x16x32_bf16 v[100:103], v[146:149], v[210:213], v[100:103]
	v_mfma_f32_16x16x32_bf16 v[92:95], v[154:157], v[210:213], v[92:95]
	v_mfma_f32_16x16x32_bf16 v[84:87], v[146:149], v[218:221], v[84:87]
	v_mfma_f32_16x16x32_bf16 v[76:79], v[154:157], v[218:221], v[76:79]
	v_mfma_f32_16x16x32_bf16 v[124:127], v[150:153], v[182:185], v[124:127]
	v_mfma_f32_16x16x32_bf16 v[120:123], v[158:161], v[182:185], v[120:123]
	v_mfma_f32_16x16x32_bf16 v[116:119], v[150:153], v[206:209], v[116:119]
	v_mfma_f32_16x16x32_bf16 v[108:111], v[158:161], v[206:209], v[108:111]
	v_mfma_f32_16x16x32_bf16 v[100:103], v[150:153], v[214:217], v[100:103]
	v_mfma_f32_16x16x32_bf16 v[92:95], v[158:161], v[214:217], v[92:95]
	v_mfma_f32_16x16x32_bf16 v[84:87], v[150:153], v[222:225], v[84:87]
	v_mfma_f32_16x16x32_bf16 v[76:79], v[158:161], v[222:225], v[76:79]
	v_mfma_f32_16x16x32_bf16 v[112:115], v[162:165], v[178:181], v[112:115]
	v_mfma_f32_16x16x32_bf16 v[104:107], v[170:173], v[178:181], v[104:107]
	v_mfma_f32_16x16x32_bf16 v[96:99], v[162:165], v[186:189], v[96:99]
	v_mfma_f32_16x16x32_bf16 v[88:91], v[170:173], v[186:189], v[88:91]
	v_mfma_f32_16x16x32_bf16 v[80:83], v[162:165], v[210:213], v[80:83]
	v_mfma_f32_16x16x32_bf16 v[72:75], v[170:173], v[210:213], v[72:75]
	v_mfma_f32_16x16x32_bf16 v[68:71], v[162:165], v[218:221], v[68:71]
	v_mfma_f32_16x16x32_bf16 v[64:67], v[170:173], v[218:221], v[64:67]
	v_mfma_f32_16x16x32_bf16 v[112:115], v[166:169], v[182:185], v[112:115]
	v_mfma_f32_16x16x32_bf16 v[104:107], v[174:177], v[182:185], v[104:107]
	v_mfma_f32_16x16x32_bf16 v[96:99], v[166:169], v[206:209], v[96:99]
	v_mfma_f32_16x16x32_bf16 v[88:91], v[174:177], v[206:209], v[88:91]
	v_mfma_f32_16x16x32_bf16 v[80:83], v[166:169], v[214:217], v[80:83]
	v_mfma_f32_16x16x32_bf16 v[72:75], v[174:177], v[214:217], v[72:75]
	v_mfma_f32_16x16x32_bf16 v[68:71], v[166:169], v[222:225], v[68:71]
	v_mfma_f32_16x16x32_bf16 v[64:67], v[174:177], v[222:225], v[64:67]
	s_barrier
	s_setprio 0
	s_add_i32 s38, s38, s20
	v_lshl_add_u64 v[142:143], s[16:17], 0, v[132:133]
	s_mov_b32 m0, s38
	ds_read_b128 v[178:181], v145 offset:16384
	ds_read_b128 v[182:185], v145 offset:17408
	ds_read_b128 v[186:189], v145 offset:18432
	ds_read_b128 v[206:209], v145 offset:19456
	ds_read_b128 v[210:213], v145 offset:20480
	ds_read_b128 v[214:217], v145 offset:21504
	ds_read_b128 v[218:221], v145 offset:22528
	ds_read_b128 v[222:225], v145 offset:23552
	global_load_lds_dwordx4 v[142:143], off
	s_add_i32 m0, s38, 0x2000
	s_add_u32 s38, s16, 0x80000
	v_lshl_add_u64 v[190:191], s[16:17], 0, v[128:129]
	s_addc_u32 s39, s17, 0
	s_add_i32 s40, s40, s20
	global_load_lds_dwordx4 v[190:191], off
	v_lshl_add_u64 v[226:227], s[38:39], 0, v[132:133]
	s_mov_b32 m0, s40
	v_lshl_add_u64 v[228:229], s[18:19], 0, v[130:131]
	global_load_lds_dwordx4 v[226:227], off
	v_lshl_add_u64 v[226:227], s[38:39], 0, v[128:129]
	s_add_i32 m0, s40, 0x2000
	s_nop 0
	global_load_lds_dwordx4 v[226:227], off
	v_lshl_add_u64 v[226:227], s[18:19], 0, v[134:135]
	s_mov_b32 m0, s21
	s_nop 0
	global_load_lds_dwordx4 v[226:227], off
	s_mov_b32 m0, s22
	s_nop 0
	global_load_lds_dwordx4 v[228:229], off
	s_waitcnt vmcnt(8)
	s_waitcnt lgkmcnt(0)
	s_setprio 1
	s_barrier
; #define PG8_STAGE(bufoff, gbase, voff) do { _Pragma("unroll") for (int _i = 0; _i < 2; ++_i) \
;         __builtin_amdgcn_global_load_lds((const unsigned*)((const char*)(gbase) + (voff)[_i]), (LAS unsigned*)(lds + (bufoff) + ldsw + _i * 8192), 16, 0, 0); } while (0)
; #define PG8_LDA(dst, b, h) do { _Pragma("unroll") for (int m = 0; m < 4; ++m) _Pragma("unroll") for (int k = 0; k < 2; ++k) dst[m][k] = *(const LAS bf16x8*)(lds + PG8_SA(b, h) + aoff + m * 2048 + k * 1024); } while (0)
; #define PG8_LDB(dst, b, h) do { _Pragma("unroll") for (int n = 0; n < 2; ++n) _Pragma("unroll") for (int k = 0; k < 2; ++k) dst[n][k] = *(const LAS bf16x8*)(lds + PG8_SB(b, h) + boff + n * 2048 + k * 1024); } while (0)
; #define PG8_MMA(ai, bj, At, Bt) do { __builtin_amdgcn_s_setprio(1); _Pragma("unroll") for (int m = 0; m < 4; ++m) _Pragma("unroll") for (int n = 0; n < 2; ++n) _Pragma("unroll") for (int k = 0; k < 2; ++k) \
;         acc[ai][bj][m][n] = __builtin_amdgcn_mfma_f32_16x16x32_bf16(Bt[n][k], At[m][k], acc[ai][bj][m][n], 0, 0, 0); __builtin_amdgcn_s_setprio(0); } while (0)
; #define PG8_WAIT_V(n) asm volatile("s_waitcnt vmcnt(" #n ")" ::: "memory")
; #define PG8_WAIT_L(n) asm volatile("s_waitcnt lgkmcnt(" #n ")" ::: "memory")
; #define PG8_BAR __builtin_amdgcn_s_barrier()
; #define PG8_SCHED __builtin_amdgcn_sched_barrier(0)
; template <class Epi, bool PERMA = false, bool DUAL = false, bool ALIGN_EPI = true, bool SP2 = true>
; __device__ __forceinline__ void gemm_phase(LAS unsigned char* lds, const Gemm g, const StaticOrder& S, const Epi& E) {
;     ...
;             PG8_WAIT_V(8); PG8_WAIT_L(0); PG8_BAR; PG8_MMA(1, 0, At, B0); PG8_MMA(1, 1, At, B1); PG8_BAR; PG8_SCHED;
;             PG8_LDB(B0, 1, 0); PG8_LDB(B1, 1, 1); PG8_SCHED; PG8_LDA(At, 1, 0); PG8_STAGE(PG8_SA(0, 1), a2 + hstepA, voffA);
;             PG8_WAIT_V(8); PG8_WAIT_L(0); PG8_BAR; PG8_MMA(0, 0, At, B0); PG8_MMA(0, 1, At, B1); PG8_BAR; PG8_SCHED;
	v_mfma_f32_16x16x32_bf16 v[60:63], v[146:149], v[178:181], v[60:63]
	v_mfma_f32_16x16x32_bf16 v[56:59], v[154:157], v[178:181], v[56:59]
	v_mfma_f32_16x16x32_bf16 v[52:55], v[146:149], v[186:189], v[52:55]
	v_mfma_f32_16x16x32_bf16 v[44:47], v[154:157], v[186:189], v[44:47]
	v_mfma_f32_16x16x32_bf16 v[36:39], v[146:149], v[210:213], v[36:39]
	v_mfma_f32_16x16x32_bf16 v[28:31], v[154:157], v[210:213], v[28:31]
	v_mfma_f32_16x16x32_bf16 v[20:23], v[146:149], v[218:221], v[20:23]
	v_mfma_f32_16x16x32_bf16 v[12:15], v[154:157], v[218:221], v[12:15]
	v_mfma_f32_16x16x32_bf16 v[60:63], v[150:153], v[182:185], v[60:63]
	v_mfma_f32_16x16x32_bf16 v[56:59], v[158:161], v[182:185], v[56:59]
	v_mfma_f32_16x16x32_bf16 v[52:55], v[150:153], v[206:209], v[52:55]
	v_mfma_f32_16x16x32_bf16 v[44:47], v[158:161], v[206:209], v[44:47]
	v_mfma_f32_16x16x32_bf16 v[36:39], v[150:153], v[214:217], v[36:39]
	v_mfma_f32_16x16x32_bf16 v[28:31], v[158:161], v[214:217], v[28:31]
	v_mfma_f32_16x16x32_bf16 v[20:23], v[150:153], v[222:225], v[20:23]
	v_mfma_f32_16x16x32_bf16 v[12:15], v[158:161], v[222:225], v[12:15]
	v_mfma_f32_16x16x32_bf16 v[48:51], v[162:165], v[178:181], v[48:51]
	v_mfma_f32_16x16x32_bf16 v[40:43], v[170:173], v[178:181], v[40:43]
	v_mfma_f32_16x16x32_bf16 v[32:35], v[162:165], v[186:189], v[32:35]
	v_mfma_f32_16x16x32_bf16 v[24:27], v[170:173], v[186:189], v[24:27]
	v_mfma_f32_16x16x32_bf16 v[16:19], v[162:165], v[210:213], v[16:19]
	v_mfma_f32_16x16x32_bf16 v[8:11], v[170:173], v[210:213], v[8:11]
	v_mfma_f32_16x16x32_bf16 v[4:7], v[162:165], v[218:221], v[4:7]
	v_mfma_f32_16x16x32_bf16 v[0:3], v[170:173], v[218:221], v[0:3]
	v_mfma_f32_16x16x32_bf16 v[48:51], v[166:169], v[182:185], v[48:51]
	v_mfma_f32_16x16x32_bf16 v[40:43], v[174:177], v[182:185], v[40:43]
	v_mfma_f32_16x16x32_bf16 v[32:35], v[166:169], v[206:209], v[32:35]
	v_mfma_f32_16x16x32_bf16 v[24:27], v[174:177], v[206:209], v[24:27]
	v_mfma_f32_16x16x32_bf16 v[16:19], v[166:169], v[214:217], v[16:19]
	v_mfma_f32_16x16x32_bf16 v[8:11], v[174:177], v[214:217], v[8:11]
	v_mfma_f32_16x16x32_bf16 v[4:7], v[166:169], v[222:225], v[4:7]
	v_mfma_f32_16x16x32_bf16 v[0:3], v[174:177], v[222:225], v[0:3]
	s_barrier
	s_setprio 0
	s_add_i32 s38, 0, 0x18000
	s_add_i32 s39, 0, 0x1c000
	v_add_u32_e32 v158, s38, v144
	v_add_u32_e32 v174, s39, v144
	ds_read_b128 v[146:149], v158
	ds_read_b128 v[150:153], v158 offset:1024
	ds_read_b128 v[154:157], v158 offset:2048
	ds_read_b128 v[158:161], v158 offset:3072
	ds_read_b128 v[162:165], v174
	ds_read_b128 v[166:169], v174 offset:1024
	ds_read_b128 v[170:173], v174 offset:2048
	ds_read_b128 v[174:177], v174 offset:3072
	s_add_u32 s18, s18, 0x100000
	s_addc_u32 s19, s19, 0
	s_mov_b32 m0, s23
	v_lshl_add_u64 v[238:239], s[18:19], 0, v[134:135]
	ds_read_b128 v[178:181], v145 offset:32768
	ds_read_b128 v[182:185], v145 offset:33792
	ds_read_b128 v[186:189], v145 offset:34816
	ds_read_b128 v[206:209], v145 offset:35840
	ds_read_b128 v[210:213], v145 offset:36864
	ds_read_b128 v[214:217], v145 offset:37888
	ds_read_b128 v[218:221], v145 offset:38912
	ds_read_b128 v[222:225], v145 offset:39936
	global_load_lds_dwordx4 v[238:239], off
	v_lshl_add_u64 v[238:239], s[18:19], 0, v[130:131]
	s_mov_b32 m0, s24
	s_nop 0
	global_load_lds_dwordx4 v[238:239], off
	s_waitcnt vmcnt(8)
	s_waitcnt lgkmcnt(0)
	s_setprio 1
	s_barrier
	v_mfma_f32_16x16x32_bf16 v[124:127], v[146:149], v[178:181], v[124:127]
	v_mfma_f32_16x16x32_bf16 v[120:123], v[154:157], v[178:181], v[120:123]
	v_mfma_f32_16x16x32_bf16 v[116:119], v[146:149], v[186:189], v[116:119]
	v_mfma_f32_16x16x32_bf16 v[108:111], v[154:157], v[186:189], v[108:111]
	v_mfma_f32_16x16x32_bf16 v[100:103], v[146:149], v[210:213], v[100:103]
	v_mfma_f32_16x16x32_bf16 v[92:95], v[154:157], v[210:213], v[92:95]
	v_mfma_f32_16x16x32_bf16 v[84:87], v[146:149], v[218:221], v[84:87]
	v_mfma_f32_16x16x32_bf16 v[76:79], v[154:157], v[218:221], v[76:79]
	v_mfma_f32_16x16x32_bf16 v[124:127], v[150:153], v[182:185], v[124:127]
	v_mfma_f32_16x16x32_bf16 v[120:123], v[158:161], v[182:185], v[120:123]
	v_mfma_f32_16x16x32_bf16 v[116:119], v[150:153], v[206:209], v[116:119]
	v_mfma_f32_16x16x32_bf16 v[108:111], v[158:161], v[206:209], v[108:111]
	v_mfma_f32_16x16x32_bf16 v[100:103], v[150:153], v[214:217], v[100:103]
	v_mfma_f32_16x16x32_bf16 v[92:95], v[158:161], v[214:217], v[92:95]
	v_mfma_f32_16x16x32_bf16 v[84:87], v[150:153], v[222:225], v[84:87]
	v_mfma_f32_16x16x32_bf16 v[76:79], v[158:161], v[222:225], v[76:79]
	v_mfma_f32_16x16x32_bf16 v[112:115], v[162:165], v[178:181], v[112:115]
	v_mfma_f32_16x16x32_bf16 v[104:107], v[170:173], v[178:181], v[104:107]
	v_mfma_f32_16x16x32_bf16 v[96:99], v[162:165], v[186:189], v[96:99]
	v_mfma_f32_16x16x32_bf16 v[88:91], v[170:173], v[186:189], v[88:91]
	v_mfma_f32_16x16x32_bf16 v[80:83], v[162:165], v[210:213], v[80:83]
	v_mfma_f32_16x16x32_bf16 v[72:75], v[170:173], v[210:213], v[72:75]
	v_mfma_f32_16x16x32_bf16 v[68:71], v[162:165], v[218:221], v[68:71]
	v_mfma_f32_16x16x32_bf16 v[64:67], v[170:173], v[218:221], v[64:67]
	v_mfma_f32_16x16x32_bf16 v[112:115], v[166:169], v[182:185], v[112:115]
	v_mfma_f32_16x16x32_bf16 v[104:107], v[174:177], v[182:185], v[104:107]
	v_mfma_f32_16x16x32_bf16 v[96:99], v[166:169], v[206:209], v[96:99]
	v_mfma_f32_16x16x32_bf16 v[88:91], v[174:177], v[206:209], v[88:91]
	v_mfma_f32_16x16x32_bf16 v[80:83], v[166:169], v[214:217], v[80:83]
	v_mfma_f32_16x16x32_bf16 v[72:75], v[174:177], v[214:217], v[72:75]
	v_mfma_f32_16x16x32_bf16 v[68:71], v[166:169], v[222:225], v[68:71]
	v_mfma_f32_16x16x32_bf16 v[64:67], v[174:177], v[222:225], v[64:67]
	s_barrier
; #define PG8_STAGE(bufoff, gbase, voff) do { _Pragma("unroll") for (int _i = 0; _i < 2; ++_i) \
;         __builtin_amdgcn_global_load_lds((const unsigned*)((const char*)(gbase) + (voff)[_i]), (LAS unsigned*)(lds + (bufoff) + ldsw + _i * 8192), 16, 0, 0); } while (0)
; #define PG8_LDA(dst, b, h) do { _Pragma("unroll") for (int m = 0; m < 4; ++m) _Pragma("unroll") for (int k = 0; k < 2; ++k) dst[m][k] = *(const LAS bf16x8*)(lds + PG8_SA(b, h) + aoff + m * 2048 + k * 1024); } while (0)
; #define PG8_MMA(ai, bj, At, Bt) do { __builtin_amdgcn_s_setprio(1); _Pragma("unroll") for (int m = 0; m < 4; ++m) _Pragma("unroll") for (int n = 0; n < 2; ++n) _Pragma("unroll") for (int k = 0; k < 2; ++k) \
;         acc[ai][bj][m][n] = __builtin_amdgcn_mfma_f32_16x16x32_bf16(Bt[n][k], At[m][k], acc[ai][bj][m][n], 0, 0, 0); __builtin_amdgcn_s_setprio(0); } while (0)
; #define PG8_WAIT_V(n) asm volatile("s_waitcnt vmcnt(" #n ")" ::: "memory")
; #define PG8_WAIT_L(n) asm volatile("s_waitcnt lgkmcnt(" #n ")" ::: "memory")
; #define PG8_BAR __builtin_amdgcn_s_barrier()
; #define PG8_SCHED __builtin_amdgcn_sched_barrier(0)
; template <class Epi, bool PERMA = false, bool DUAL = false, bool ALIGN_EPI = true, bool SP2 = true>
; __device__ __forceinline__ void gemm_phase(LAS unsigned char* lds, const Gemm g, const StaticOrder& S, const Epi& E) {
;     ...
;         for (int t = 0; t < nt; t += 2) {
;     ...
;             PG8_LDA(At, 1, 1); PG8_STAGE(PG8_SB(1, 0), b3, voffB); PG8_STAGE(PG8_SB(1, 1), b3 + hstepB, voffB); PG8_STAGE(PG8_SA(1, 0), a3, voffA);
;             PG8_WAIT_V(8); PG8_WAIT_L(0); PG8_BAR; PG8_MMA(1, 0, At, B0); PG8_MMA(1, 1, At, B1); PG8_BAR; PG8_SCHED;
;     ...
;         if constexpr (ALIGN_EPI) { if (wr == 0) PG8_BAR; }
	s_setprio 0
	s_add_i32 s18, s38, s20
	v_lshl_add_u64 v[142:143], v[142:143], 0, s[46:47]
	s_mov_b32 m0, s18
	ds_read_b128 v[178:181], v145 offset:49152
	ds_read_b128 v[182:185], v145 offset:50176
	ds_read_b128 v[186:189], v145 offset:51200
	ds_read_b128 v[206:209], v145 offset:52224
	ds_read_b128 v[210:213], v145 offset:53248
	ds_read_b128 v[214:217], v145 offset:54272
	ds_read_b128 v[218:221], v145 offset:55296
	ds_read_b128 v[222:225], v145 offset:56320
	global_load_lds_dwordx4 v[142:143], off
	s_add_i32 m0, s18, 0x2000
	s_add_u32 s16, s16, 0x80080
	v_lshl_add_u64 v[142:143], v[190:191], 0, s[46:47]
	s_addc_u32 s17, s17, 0
	s_add_i32 s18, s39, s20
	global_load_lds_dwordx4 v[142:143], off
	v_lshl_add_u64 v[142:143], s[16:17], 0, v[132:133]
	s_mov_b32 m0, s18
	s_nop 0
	global_load_lds_dwordx4 v[142:143], off
	v_lshl_add_u64 v[142:143], s[16:17], 0, v[128:129]
	s_add_i32 m0, s18, 0x2000
	s_nop 0
	global_load_lds_dwordx4 v[142:143], off
	v_lshl_add_u64 v[142:143], v[226:227], 0, s[46:47]
	s_mov_b32 m0, s27
	s_nop 0
	global_load_lds_dwordx4 v[142:143], off
	v_lshl_add_u64 v[142:143], v[228:229], 0, s[46:47]
	s_mov_b32 m0, s28
	s_nop 0
	global_load_lds_dwordx4 v[142:143], off
	s_waitcnt vmcnt(8)
	s_waitcnt lgkmcnt(0)
	s_setprio 1
	s_barrier
	v_mfma_f32_16x16x32_bf16 v[60:63], v[146:149], v[178:181], v[60:63]
	v_mfma_f32_16x16x32_bf16 v[56:59], v[154:157], v[178:181], v[56:59]
	v_mfma_f32_16x16x32_bf16 v[52:55], v[146:149], v[186:189], v[52:55]
	v_mfma_f32_16x16x32_bf16 v[44:47], v[154:157], v[186:189], v[44:47]
	v_mfma_f32_16x16x32_bf16 v[36:39], v[146:149], v[210:213], v[36:39]
	v_mfma_f32_16x16x32_bf16 v[28:31], v[154:157], v[210:213], v[28:31]
	v_mfma_f32_16x16x32_bf16 v[20:23], v[146:149], v[218:221], v[20:23]
	v_mfma_f32_16x16x32_bf16 v[12:15], v[154:157], v[218:221], v[12:15]
	v_mfma_f32_16x16x32_bf16 v[60:63], v[150:153], v[182:185], v[60:63]
	v_mfma_f32_16x16x32_bf16 v[56:59], v[158:161], v[182:185], v[56:59]
	v_mfma_f32_16x16x32_bf16 v[52:55], v[150:153], v[206:209], v[52:55]
	v_mfma_f32_16x16x32_bf16 v[44:47], v[158:161], v[206:209], v[44:47]
	v_mfma_f32_16x16x32_bf16 v[36:39], v[150:153], v[214:217], v[36:39]
	v_mfma_f32_16x16x32_bf16 v[28:31], v[158:161], v[214:217], v[28:31]
	v_mfma_f32_16x16x32_bf16 v[20:23], v[150:153], v[222:225], v[20:23]
	v_mfma_f32_16x16x32_bf16 v[12:15], v[158:161], v[222:225], v[12:15]
	v_mfma_f32_16x16x32_bf16 v[48:51], v[162:165], v[178:181], v[48:51]
	v_mfma_f32_16x16x32_bf16 v[40:43], v[170:173], v[178:181], v[40:43]
	v_mfma_f32_16x16x32_bf16 v[32:35], v[162:165], v[186:189], v[32:35]
	v_mfma_f32_16x16x32_bf16 v[24:27], v[170:173], v[186:189], v[24:27]
	v_mfma_f32_16x16x32_bf16 v[16:19], v[162:165], v[210:213], v[16:19]
	v_mfma_f32_16x16x32_bf16 v[8:11], v[170:173], v[210:213], v[8:11]
	v_mfma_f32_16x16x32_bf16 v[4:7], v[162:165], v[218:221], v[4:7]
	v_mfma_f32_16x16x32_bf16 v[0:3], v[170:173], v[218:221], v[0:3]
	v_mfma_f32_16x16x32_bf16 v[48:51], v[166:169], v[182:185], v[48:51]
	v_mfma_f32_16x16x32_bf16 v[40:43], v[174:177], v[182:185], v[40:43]
	v_mfma_f32_16x16x32_bf16 v[32:35], v[166:169], v[206:209], v[32:35]
	v_mfma_f32_16x16x32_bf16 v[24:27], v[174:177], v[206:209], v[24:27]
	v_mfma_f32_16x16x32_bf16 v[16:19], v[166:169], v[214:217], v[16:19]
	v_mfma_f32_16x16x32_bf16 v[8:11], v[174:177], v[214:217], v[8:11]
	v_mfma_f32_16x16x32_bf16 v[4:7], v[166:169], v[222:225], v[4:7]
	v_mfma_f32_16x16x32_bf16 v[0:3], v[174:177], v[222:225], v[0:3]
	s_barrier
	s_setprio 0
	s_add_i32 s37, s37, 2
	s_add_u32 s14, s14, 0x100
	s_addc_u32 s15, s15, 0
	s_add_u32 s35, s35, 0x100
	s_addc_u32 s36, s36, 0
	s_cmp_gt_u32 s37, 29
	s_cbranch_scc0 .LBB0_405
	s_and_b64 vcc, exec, s[4:5]
	s_cbranch_vccz .LBB0_408
	s_barrier

; #define PG8_STAGE(bufoff, gbase, voff) do { _Pragma("unroll") for (int _i = 0; _i < 2; ++_i) \
;         __builtin_amdgcn_global_load_lds((const unsigned*)((const char*)(gbase) + (voff)[_i]), (LAS unsigned*)(lds + (bufoff) + ldsw + _i * 8192), 16, 0, 0); } while (0)
; #define PG8_LDA(dst, b, h) do { _Pragma("unroll") for (int m = 0; m < 4; ++m) _Pragma("unroll") for (int k = 0; k < 2; ++k) dst[m][k] = *(const LAS bf16x8*)(lds + PG8_SA(b, h) + aoff + m * 2048 + k * 1024); } while (0)
; #define PG8_LDB(dst, b, h) do { _Pragma("unroll") for (int n = 0; n < 2; ++n) _Pragma("unroll") for (int k = 0; k < 2; ++k) dst[n][k] = *(const LAS bf16x8*)(lds + PG8_SB(b, h) + boff + n * 2048 + k * 1024); } while (0)
; #define PG8_MMA(ai, bj, At, Bt) do { __builtin_amdgcn_s_setprio(1); _Pragma("unroll") for (int m = 0; m < 4; ++m) _Pragma("unroll") for (int n = 0; n < 2; ++n) _Pragma("unroll") for (int k = 0; k < 2; ++k) \
;         acc[ai][bj][m][n] = __builtin_amdgcn_mfma_f32_16x16x32_bf16(Bt[n][k], At[m][k], acc[ai][bj][m][n], 0, 0, 0); __builtin_amdgcn_s_setprio(0); } while (0)
; #define PG8_WAIT_V(n) asm volatile("s_waitcnt vmcnt(" #n ")" ::: "memory")
; #define PG8_WAIT_L(n) asm volatile("s_waitcnt lgkmcnt(" #n ")" ::: "memory")
; #define PG8_BAR __builtin_amdgcn_s_barrier()
; template <class Epi, bool PERMA = false, bool DUAL = false, bool ALIGN_EPI = true, bool SP2 = true>
; __device__ __forceinline__ void gemm_phase(LAS unsigned char* lds, const Gemm g, const StaticOrder& S, const Epi& E) {
;     ...
;             const bool last = (t == nt - 2);
;             const char* a1 = cA + (size_t)(t + 1) * kstep;
;             const char* a2 = last ? nA : cA + (size_t)(t + 2) * kstep; const char* b2 = last ? nB : cB + (size_t)(t + 2) * kstep;
;             const char* a3 = a2 + kstep; const char* b3 = b2 + kstep;
;             if constexpr (SP2) {
;             PG8_LDB(B0, 0, 0); PG8_LDB(B1, 0, 1); PG8_SCHED; PG8_LDA(At, 0, 0); PG8_STAGE(PG8_SA(1, 1), a1 + hstepA, voffA);
;             PG8_WAIT_V(8); PG8_WAIT_L(0); PG8_BAR; PG8_MMA(0, 0, At, B0); PG8_MMA(0, 1, At, B1); PG8_BAR; PG8_SCHED;
;             PG8_LDA(At, 0, 1); PG8_STAGE(PG8_SB(0, 0), b2, voffB); PG8_STAGE(PG8_SB(0, 1), b2 + hstepB, voffB); PG8_STAGE(PG8_SA(0, 0), a2, voffA);
;             PG8_WAIT_V(8); PG8_WAIT_L(0); PG8_BAR; PG8_MMA(1, 0, At, B0); PG8_MMA(1, 1, At, B1); PG8_BAR; PG8_SCHED;
.LBB0_528:
	s_add_u32 s22, s20, 0x100
	s_addc_u32 s23, s21, 0
	s_add_i32 s52, 0, 0x10000
	s_cmp_eq_u32 s51, 28
	s_cselect_b32 s27, s15, s23
	s_cselect_b32 s26, s39, s22
	s_cselect_b32 s25, s13, s50
	s_cselect_b32 s24, s48, s49
	s_add_i32 s53, 0, 0x14000
	v_add_u32_e32 v108, s52, v193
	v_add_u32_e32 v124, s53, v193
	ds_read_b128 v[96:99], v108
	ds_read_b128 v[100:103], v108 offset:1024
	ds_read_b128 v[104:107], v108 offset:2048
	ds_read_b128 v[108:111], v108 offset:3072
	ds_read_b128 v[112:115], v124
	ds_read_b128 v[116:119], v124 offset:1024
	ds_read_b128 v[120:123], v124 offset:2048
	ds_read_b128 v[124:127], v124 offset:3072
	v_lshl_add_u64 v[220:221], s[20:21], 0, v[216:217]
	s_add_i32 m0, s29, 0xc000
	ds_read_b128 v[128:131], v224
	ds_read_b128 v[132:135], v224 offset:1024
	ds_read_b128 v[136:139], v224 offset:2048
	ds_read_b128 v[144:147], v224 offset:3072
	ds_read_b128 v[152:155], v224 offset:4096
	ds_read_b128 v[160:163], v224 offset:5120
	ds_read_b128 v[168:171], v224 offset:6144
	ds_read_b128 v[188:191], v224 offset:7168
	global_load_lds_dwordx4 v[220:221], off
	v_lshl_add_u64 v[220:221], s[20:21], 0, v[218:219]
	s_add_i32 m0, s29, 0xe000
	s_nop 0
	global_load_lds_dwordx4 v[220:221], off
	s_waitcnt vmcnt(8)
	s_waitcnt lgkmcnt(0)
	s_setprio 1
	s_barrier
	v_mfma_f32_16x16x32_bf16 v[184:187], v[96:99], v[128:131], v[184:187]
	v_mfma_f32_16x16x32_bf16 v[92:95], v[104:107], v[128:131], v[92:95]
	v_mfma_f32_16x16x32_bf16 v[180:183], v[96:99], v[136:139], v[180:183]
	v_mfma_f32_16x16x32_bf16 v[88:91], v[104:107], v[136:139], v[88:91]
	v_mfma_f32_16x16x32_bf16 v[176:179], v[96:99], v[152:155], v[176:179]
	v_mfma_f32_16x16x32_bf16 v[84:87], v[104:107], v[152:155], v[84:87]
	v_mfma_f32_16x16x32_bf16 v[172:175], v[96:99], v[168:171], v[172:175]
	v_mfma_f32_16x16x32_bf16 v[80:83], v[104:107], v[168:171], v[80:83]
	v_mfma_f32_16x16x32_bf16 v[184:187], v[100:103], v[132:135], v[184:187]
	v_mfma_f32_16x16x32_bf16 v[92:95], v[108:111], v[132:135], v[92:95]
	v_mfma_f32_16x16x32_bf16 v[180:183], v[100:103], v[144:147], v[180:183]
	v_mfma_f32_16x16x32_bf16 v[88:91], v[108:111], v[144:147], v[88:91]
	v_mfma_f32_16x16x32_bf16 v[176:179], v[100:103], v[160:163], v[176:179]
	v_mfma_f32_16x16x32_bf16 v[84:87], v[108:111], v[160:163], v[84:87]
	v_mfma_f32_16x16x32_bf16 v[172:175], v[100:103], v[188:191], v[172:175]
	v_mfma_f32_16x16x32_bf16 v[80:83], v[108:111], v[188:191], v[80:83]
	v_mfma_f32_16x16x32_bf16 v[164:167], v[112:115], v[128:131], v[164:167]
	v_mfma_f32_16x16x32_bf16 v[76:79], v[120:123], v[128:131], v[76:79]
	v_mfma_f32_16x16x32_bf16 v[72:75], v[120:123], v[136:139], v[72:75]
	v_mfma_f32_16x16x32_bf16 v[68:71], v[120:123], v[152:155], v[68:71]
	v_mfma_f32_16x16x32_bf16 v[64:67], v[120:123], v[168:171], v[64:67]
	v_mfma_f32_16x16x32_bf16 v[164:167], v[116:119], v[132:135], v[164:167]
	v_mfma_f32_16x16x32_bf16 v[76:79], v[124:127], v[132:135], v[76:79]
	v_mfma_f32_16x16x32_bf16 v[128:131], v[112:115], v[136:139], v[156:159]
	v_mfma_f32_16x16x32_bf16 v[72:75], v[124:127], v[144:147], v[72:75]
	v_mfma_f32_16x16x32_bf16 v[132:135], v[112:115], v[152:155], v[148:151]
	v_mfma_f32_16x16x32_bf16 v[68:71], v[124:127], v[160:163], v[68:71]
	v_mfma_f32_16x16x32_bf16 v[136:139], v[112:115], v[168:171], v[140:143]
	v_mfma_f32_16x16x32_bf16 v[64:67], v[124:127], v[188:191], v[64:67]
	v_mfma_f32_16x16x32_bf16 v[128:131], v[116:119], v[144:147], v[128:131]
	v_mfma_f32_16x16x32_bf16 v[132:135], v[116:119], v[160:163], v[132:135]
	v_mfma_f32_16x16x32_bf16 v[136:139], v[116:119], v[188:191], v[136:139]
	s_barrier
	s_setprio 0
	s_add_i32 s20, s52, s28
	v_lshl_add_u64 v[220:221], s[24:25], 0, v[210:211]
	s_mov_b32 m0, s20
	ds_read_b128 v[140:143], v224 offset:16384
	ds_read_b128 v[144:147], v224 offset:17408
	ds_read_b128 v[148:151], v224 offset:18432
	ds_read_b128 v[152:155], v224 offset:19456
	ds_read_b128 v[156:159], v224 offset:20480
	ds_read_b128 v[160:163], v224 offset:21504
	ds_read_b128 v[168:171], v224 offset:22528
	ds_read_b128 v[188:191], v224 offset:23552
	global_load_lds_dwordx4 v[220:221], off
	s_add_i32 m0, s20, 0x2000
	s_add_u32 s20, s24, 0x80000
	v_lshl_add_u64 v[238:239], s[24:25], 0, v[206:207]
	s_addc_u32 s21, s25, 0
	s_add_i32 s52, s53, s28
	global_load_lds_dwordx4 v[238:239], off
	v_lshl_add_u64 v[226:227], s[20:21], 0, v[210:211]
	s_mov_b32 m0, s52
	v_lshl_add_u64 v[240:241], s[26:27], 0, v[212:213]
	global_load_lds_dwordx4 v[226:227], off
	v_lshl_add_u64 v[226:227], s[20:21], 0, v[206:207]
	s_add_i32 m0, s52, 0x2000
	v_lshl_add_u64 v[242:243], s[26:27], 0, v[208:209]
	global_load_lds_dwordx4 v[226:227], off
	s_mov_b32 m0, s29
	s_nop 0
	global_load_lds_dwordx4 v[240:241], off
	s_mov_b32 m0, s30
	s_nop 0
	global_load_lds_dwordx4 v[242:243], off
	s_waitcnt vmcnt(8)
	s_waitcnt lgkmcnt(0)
	s_setprio 1
	s_barrier
; #define PG8_STAGE(bufoff, gbase, voff) do { _Pragma("unroll") for (int _i = 0; _i < 2; ++_i) \
;         __builtin_amdgcn_global_load_lds((const unsigned*)((const char*)(gbase) + (voff)[_i]), (LAS unsigned*)(lds + (bufoff) + ldsw + _i * 8192), 16, 0, 0); } while (0)
; #define PG8_LDA(dst, b, h) do { _Pragma("unroll") for (int m = 0; m < 4; ++m) _Pragma("unroll") for (int k = 0; k < 2; ++k) dst[m][k] = *(const LAS bf16x8*)(lds + PG8_SA(b, h) + aoff + m * 2048 + k * 1024); } while (0)
; #define PG8_LDB(dst, b, h) do { _Pragma("unroll") for (int n = 0; n < 2; ++n) _Pragma("unroll") for (int k = 0; k < 2; ++k) dst[n][k] = *(const LAS bf16x8*)(lds + PG8_SB(b, h) + boff + n * 2048 + k * 1024); } while (0)
; #define PG8_MMA(ai, bj, At, Bt) do { __builtin_amdgcn_s_setprio(1); _Pragma("unroll") for (int m = 0; m < 4; ++m) _Pragma("unroll") for (int n = 0; n < 2; ++n) _Pragma("unroll") for (int k = 0; k < 2; ++k) \
;         acc[ai][bj][m][n] = __builtin_amdgcn_mfma_f32_16x16x32_bf16(Bt[n][k], At[m][k], acc[ai][bj][m][n], 0, 0, 0); __builtin_amdgcn_s_setprio(0); } while (0)
; #define PG8_WAIT_V(n) asm volatile("s_waitcnt vmcnt(" #n ")" ::: "memory")
; #define PG8_WAIT_L(n) asm volatile("s_waitcnt lgkmcnt(" #n ")" ::: "memory")
; #define PG8_BAR __builtin_amdgcn_s_barrier()
; #define PG8_SCHED __builtin_amdgcn_sched_barrier(0)
; template <class Epi, bool PERMA = false, bool DUAL = false, bool ALIGN_EPI = true, bool SP2 = true>
; __device__ __forceinline__ void gemm_phase(LAS unsigned char* lds, const Gemm g, const StaticOrder& S, const Epi& E) {
;     ...
;             PG8_WAIT_V(8); PG8_WAIT_L(0); PG8_BAR; PG8_MMA(1, 0, At, B0); PG8_MMA(1, 1, At, B1); PG8_BAR; PG8_SCHED;
;             PG8_LDB(B0, 1, 0); PG8_LDB(B1, 1, 1); PG8_SCHED; PG8_LDA(At, 1, 0); PG8_STAGE(PG8_SA(0, 1), a2 + hstepA, voffA);
;             PG8_WAIT_V(8); PG8_WAIT_L(0); PG8_BAR; PG8_MMA(0, 0, At, B0); PG8_MMA(0, 1, At, B1); PG8_BAR; PG8_SCHED;
	v_mfma_f32_16x16x32_bf16 v[60:63], v[96:99], v[140:143], v[60:63]
	v_mfma_f32_16x16x32_bf16 v[28:31], v[104:107], v[140:143], v[28:31]
	v_mfma_f32_16x16x32_bf16 v[56:59], v[96:99], v[148:151], v[56:59]
	v_mfma_f32_16x16x32_bf16 v[24:27], v[104:107], v[148:151], v[24:27]
	v_mfma_f32_16x16x32_bf16 v[52:55], v[96:99], v[156:159], v[52:55]
	v_mfma_f32_16x16x32_bf16 v[20:23], v[104:107], v[156:159], v[20:23]
	v_mfma_f32_16x16x32_bf16 v[48:51], v[96:99], v[168:171], v[48:51]
	v_mfma_f32_16x16x32_bf16 v[16:19], v[104:107], v[168:171], v[16:19]
	v_mfma_f32_16x16x32_bf16 v[60:63], v[100:103], v[144:147], v[60:63]
	v_mfma_f32_16x16x32_bf16 v[28:31], v[108:111], v[144:147], v[28:31]
	v_mfma_f32_16x16x32_bf16 v[56:59], v[100:103], v[152:155], v[56:59]
	v_mfma_f32_16x16x32_bf16 v[24:27], v[108:111], v[152:155], v[24:27]
	v_mfma_f32_16x16x32_bf16 v[52:55], v[100:103], v[160:163], v[52:55]
	v_mfma_f32_16x16x32_bf16 v[20:23], v[108:111], v[160:163], v[20:23]
	v_mfma_f32_16x16x32_bf16 v[48:51], v[100:103], v[188:191], v[48:51]
	v_mfma_f32_16x16x32_bf16 v[16:19], v[108:111], v[188:191], v[16:19]
	v_mfma_f32_16x16x32_bf16 v[44:47], v[112:115], v[140:143], v[44:47]
	v_mfma_f32_16x16x32_bf16 v[12:15], v[120:123], v[140:143], v[12:15]
	v_mfma_f32_16x16x32_bf16 v[40:43], v[112:115], v[148:151], v[40:43]
	v_mfma_f32_16x16x32_bf16 v[8:11], v[120:123], v[148:151], v[8:11]
	v_mfma_f32_16x16x32_bf16 v[36:39], v[112:115], v[156:159], v[36:39]
	v_mfma_f32_16x16x32_bf16 v[4:7], v[120:123], v[156:159], v[4:7]
	v_mfma_f32_16x16x32_bf16 v[32:35], v[112:115], v[168:171], v[32:35]
	v_mfma_f32_16x16x32_bf16 v[0:3], v[120:123], v[168:171], v[0:3]
	v_mfma_f32_16x16x32_bf16 v[44:47], v[116:119], v[144:147], v[44:47]
	v_mfma_f32_16x16x32_bf16 v[12:15], v[124:127], v[144:147], v[12:15]
	v_mfma_f32_16x16x32_bf16 v[40:43], v[116:119], v[152:155], v[40:43]
	v_mfma_f32_16x16x32_bf16 v[8:11], v[124:127], v[152:155], v[8:11]
	v_mfma_f32_16x16x32_bf16 v[36:39], v[116:119], v[160:163], v[36:39]
	v_mfma_f32_16x16x32_bf16 v[4:7], v[124:127], v[160:163], v[4:7]
	v_mfma_f32_16x16x32_bf16 v[32:35], v[116:119], v[188:191], v[32:35]
	v_mfma_f32_16x16x32_bf16 v[0:3], v[124:127], v[188:191], v[0:3]
	s_barrier
	s_setprio 0
	s_add_i32 s52, 0, 0x18000
	s_add_i32 s53, 0, 0x1c000
	v_add_u32_e32 v108, s52, v193
	v_add_u32_e32 v124, s53, v193
	ds_read_b128 v[96:99], v108
	ds_read_b128 v[100:103], v108 offset:1024
	ds_read_b128 v[104:107], v108 offset:2048
	ds_read_b128 v[108:111], v108 offset:3072
	ds_read_b128 v[112:115], v124
	ds_read_b128 v[116:119], v124 offset:1024
	ds_read_b128 v[120:123], v124 offset:2048
	ds_read_b128 v[124:127], v124 offset:3072
	s_add_u32 s20, s26, 0x80000
	s_addc_u32 s21, s27, 0
	s_mov_b32 m0, s31
	v_lshl_add_u64 v[156:157], s[20:21], 0, v[212:213]
	ds_read_b128 v[140:143], v224 offset:32768
	ds_read_b128 v[144:147], v224 offset:33792
	ds_read_b128 v[148:151], v224 offset:34816
	ds_read_b128 v[152:155], v224 offset:35840
	ds_read_b128 v[160:163], v224 offset:36864
	ds_read_b128 v[168:171], v224 offset:37888
	ds_read_b128 v[188:191], v224 offset:38912
	ds_read_b128 v[226:229], v224 offset:39936
	global_load_lds_dwordx4 v[156:157], off
	v_lshl_add_u64 v[156:157], s[20:21], 0, v[208:209]
	s_mov_b32 m0, s34
	s_nop 0
	global_load_lds_dwordx4 v[156:157], off
	s_waitcnt vmcnt(8)
	s_waitcnt lgkmcnt(0)
	s_setprio 1
	s_barrier
	v_mfma_f32_16x16x32_bf16 v[156:159], v[96:99], v[140:143], v[184:187]
	v_mfma_f32_16x16x32_bf16 v[184:187], v[100:103], v[144:147], v[156:159]
	v_mfma_f32_16x16x32_bf16 v[156:159], v[96:99], v[148:151], v[180:183]
	v_mfma_f32_16x16x32_bf16 v[180:183], v[100:103], v[152:155], v[156:159]
	v_mfma_f32_16x16x32_bf16 v[156:159], v[96:99], v[160:163], v[176:179]
	v_mfma_f32_16x16x32_bf16 v[92:95], v[104:107], v[140:143], v[92:95]
	v_mfma_f32_16x16x32_bf16 v[88:91], v[104:107], v[148:151], v[88:91]
	v_mfma_f32_16x16x32_bf16 v[176:179], v[100:103], v[168:171], v[156:159]
	v_mfma_f32_16x16x32_bf16 v[84:87], v[104:107], v[160:163], v[84:87]
	v_mfma_f32_16x16x32_bf16 v[156:159], v[96:99], v[188:191], v[172:175]
	v_mfma_f32_16x16x32_bf16 v[80:83], v[104:107], v[188:191], v[80:83]
	v_mfma_f32_16x16x32_bf16 v[92:95], v[108:111], v[144:147], v[92:95]
	v_mfma_f32_16x16x32_bf16 v[88:91], v[108:111], v[152:155], v[88:91]
	v_mfma_f32_16x16x32_bf16 v[84:87], v[108:111], v[168:171], v[84:87]
	v_mfma_f32_16x16x32_bf16 v[172:175], v[100:103], v[226:229], v[156:159]
	v_mfma_f32_16x16x32_bf16 v[80:83], v[108:111], v[226:229], v[80:83]
	v_mfma_f32_16x16x32_bf16 v[156:159], v[112:115], v[140:143], v[164:167]
	v_mfma_f32_16x16x32_bf16 v[128:131], v[112:115], v[148:151], v[128:131]
	v_mfma_f32_16x16x32_bf16 v[164:167], v[116:119], v[144:147], v[156:159]
	v_mfma_f32_16x16x32_bf16 v[156:159], v[116:119], v[152:155], v[128:131]
	v_mfma_f32_16x16x32_bf16 v[128:131], v[112:115], v[160:163], v[132:135]
	v_mfma_f32_16x16x32_bf16 v[76:79], v[120:123], v[140:143], v[76:79]
	v_mfma_f32_16x16x32_bf16 v[72:75], v[120:123], v[148:151], v[72:75]
	v_mfma_f32_16x16x32_bf16 v[148:151], v[116:119], v[168:171], v[128:131]
	v_mfma_f32_16x16x32_bf16 v[68:71], v[120:123], v[160:163], v[68:71]
	v_mfma_f32_16x16x32_bf16 v[128:131], v[112:115], v[188:191], v[136:139]
	v_mfma_f32_16x16x32_bf16 v[64:67], v[120:123], v[188:191], v[64:67]
	v_mfma_f32_16x16x32_bf16 v[76:79], v[124:127], v[144:147], v[76:79]
	v_mfma_f32_16x16x32_bf16 v[72:75], v[124:127], v[152:155], v[72:75]
	v_mfma_f32_16x16x32_bf16 v[68:71], v[124:127], v[168:171], v[68:71]
	v_mfma_f32_16x16x32_bf16 v[140:143], v[116:119], v[226:229], v[128:131]
	v_mfma_f32_16x16x32_bf16 v[64:67], v[124:127], v[226:229], v[64:67]
	s_barrier
; #define PG8_STAGE(bufoff, gbase, voff) do { _Pragma("unroll") for (int _i = 0; _i < 2; ++_i) \
;         __builtin_amdgcn_global_load_lds((const unsigned*)((const char*)(gbase) + (voff)[_i]), (LAS unsigned*)(lds + (bufoff) + ldsw + _i * 8192), 16, 0, 0); } while (0)
; #define PG8_LDA(dst, b, h) do { _Pragma("unroll") for (int m = 0; m < 4; ++m) _Pragma("unroll") for (int k = 0; k < 2; ++k) dst[m][k] = *(const LAS bf16x8*)(lds + PG8_SA(b, h) + aoff + m * 2048 + k * 1024); } while (0)
; #define PG8_MMA(ai, bj, At, Bt) do { __builtin_amdgcn_s_setprio(1); _Pragma("unroll") for (int m = 0; m < 4; ++m) _Pragma("unroll") for (int n = 0; n < 2; ++n) _Pragma("unroll") for (int k = 0; k < 2; ++k) \
;         acc[ai][bj][m][n] = __builtin_amdgcn_mfma_f32_16x16x32_bf16(Bt[n][k], At[m][k], acc[ai][bj][m][n], 0, 0, 0); __builtin_amdgcn_s_setprio(0); } while (0)
; #define PG8_WAIT_V(n) asm volatile("s_waitcnt vmcnt(" #n ")" ::: "memory")
; #define PG8_WAIT_L(n) asm volatile("s_waitcnt lgkmcnt(" #n ")" ::: "memory")
; #define PG8_BAR __builtin_amdgcn_s_barrier()
; #define PG8_SCHED __builtin_amdgcn_sched_barrier(0)
; template <class Epi, bool PERMA = false, bool DUAL = false, bool ALIGN_EPI = true, bool SP2 = true>
; __device__ __forceinline__ void gemm_phase(LAS unsigned char* lds, const Gemm g, const StaticOrder& S, const Epi& E) {
;     ...
;             PG8_LDA(At, 1, 1); PG8_STAGE(PG8_SB(1, 0), b3, voffB); PG8_STAGE(PG8_SB(1, 1), b3 + hstepB, voffB); PG8_STAGE(PG8_SA(1, 0), a3, voffA);
;             PG8_WAIT_V(8); PG8_WAIT_L(0); PG8_BAR; PG8_MMA(1, 0, At, B0); PG8_MMA(1, 1, At, B1); PG8_BAR; PG8_SCHED;
;     __device__ __forceinline__ void operator()(const f32x4 (&acc)[2][2][4][2], const Unit& u, int wr, int wc, int fr, int fq) const {
;     ...
;         const int ch0 = u.pn * HALF + wc * 32 + 8 * fq;
;         const int tok0 = u.pm * BM + wr * 64 + 4 * fr;
;         f32x4 wgt[2][8];
; #pragma unroll
;         for (int n = 0; n < 2; ++n) { const float* wp = cw + ch0 + 4 * n;
;             wgt[n][0] = *(const f32x4*)wp; wgt[n][1] = *(const f32x4*)(wp + 2 * DFF); wgt[n][2] = *(const f32x4*)(wp + 4 * DFF); wgt[n][3] = *(const f32x4*)(cb + ch0 + 4 * n);
;             wgt[n][4] = *(const f32x4*)(wp + DFF); wgt[n][5] = *(const f32x4*)(wp + 3 * DFF); wgt[n][6] = *(const f32x4*)(wp + 5 * DFF); wgt[n][7] = *(const f32x4*)(cb + DFF + ch0 + 4 * n); }
	s_setprio 0
	s_add_i32 s20, s52, s28
	v_lshl_add_u64 v[220:221], v[220:221], 0, s[56:57]
	s_mov_b32 m0, s20
	ds_read_b128 v[128:131], v224 offset:49152
	ds_read_b128 v[132:135], v224 offset:50176
	ds_read_b128 v[136:139], v224 offset:51200
	ds_read_b128 v[144:147], v224 offset:52224
	ds_read_b128 v[152:155], v224 offset:53248
	ds_read_b128 v[160:163], v224 offset:54272
	ds_read_b128 v[168:171], v224 offset:55296
	ds_read_b128 v[188:191], v224 offset:56320
	global_load_lds_dwordx4 v[220:221], off
	s_add_i32 m0, s20, 0x2000
	s_add_u32 s20, s24, 0x80080
	v_lshl_add_u64 v[220:221], v[238:239], 0, s[56:57]
	s_addc_u32 s21, s25, 0
	s_add_i32 s24, s53, s28
	global_load_lds_dwordx4 v[220:221], off
	v_lshl_add_u64 v[220:221], s[20:21], 0, v[210:211]
	s_mov_b32 m0, s24
	s_nop 0
	global_load_lds_dwordx4 v[220:221], off
	v_lshl_add_u64 v[220:221], s[20:21], 0, v[206:207]
	s_add_i32 m0, s24, 0x2000
	s_nop 0
	global_load_lds_dwordx4 v[220:221], off
	v_lshl_add_u64 v[220:221], v[240:241], 0, s[56:57]
	s_mov_b32 m0, s35
	s_nop 0
	global_load_lds_dwordx4 v[220:221], off
	v_lshl_add_u64 v[220:221], v[242:243], 0, s[56:57]
	s_mov_b32 m0, s36
	s_nop 0
	global_load_lds_dwordx4 v[220:221], off
	s_waitcnt vmcnt(8)
	s_waitcnt lgkmcnt(0)
	s_setprio 1
	s_barrier
	v_mfma_f32_16x16x32_bf16 v[60:63], v[96:99], v[128:131], v[60:63]
	v_mfma_f32_16x16x32_bf16 v[28:31], v[104:107], v[128:131], v[28:31]
	v_mfma_f32_16x16x32_bf16 v[56:59], v[96:99], v[136:139], v[56:59]
	v_mfma_f32_16x16x32_bf16 v[24:27], v[104:107], v[136:139], v[24:27]
	v_mfma_f32_16x16x32_bf16 v[52:55], v[96:99], v[152:155], v[52:55]
	v_mfma_f32_16x16x32_bf16 v[20:23], v[104:107], v[152:155], v[20:23]
	v_mfma_f32_16x16x32_bf16 v[48:51], v[96:99], v[168:171], v[48:51]
	v_mfma_f32_16x16x32_bf16 v[16:19], v[104:107], v[168:171], v[16:19]
	v_mfma_f32_16x16x32_bf16 v[60:63], v[100:103], v[132:135], v[60:63]
	v_mfma_f32_16x16x32_bf16 v[28:31], v[108:111], v[132:135], v[28:31]
	v_mfma_f32_16x16x32_bf16 v[56:59], v[100:103], v[144:147], v[56:59]
	v_mfma_f32_16x16x32_bf16 v[24:27], v[108:111], v[144:147], v[24:27]
	v_mfma_f32_16x16x32_bf16 v[52:55], v[100:103], v[160:163], v[52:55]
	v_mfma_f32_16x16x32_bf16 v[20:23], v[108:111], v[160:163], v[20:23]
	v_mfma_f32_16x16x32_bf16 v[48:51], v[100:103], v[188:191], v[48:51]
	v_mfma_f32_16x16x32_bf16 v[16:19], v[108:111], v[188:191], v[16:19]
	v_mfma_f32_16x16x32_bf16 v[44:47], v[112:115], v[128:131], v[44:47]
	v_mfma_f32_16x16x32_bf16 v[12:15], v[120:123], v[128:131], v[12:15]
	v_mfma_f32_16x16x32_bf16 v[40:43], v[112:115], v[136:139], v[40:43]
	v_mfma_f32_16x16x32_bf16 v[8:11], v[120:123], v[136:139], v[8:11]
	v_mfma_f32_16x16x32_bf16 v[36:39], v[112:115], v[152:155], v[36:39]
	v_mfma_f32_16x16x32_bf16 v[4:7], v[120:123], v[152:155], v[4:7]
	v_mfma_f32_16x16x32_bf16 v[32:35], v[112:115], v[168:171], v[32:35]
	v_mfma_f32_16x16x32_bf16 v[0:3], v[120:123], v[168:171], v[0:3]
	v_mfma_f32_16x16x32_bf16 v[44:47], v[116:119], v[132:135], v[44:47]
	v_mfma_f32_16x16x32_bf16 v[12:15], v[124:127], v[132:135], v[12:15]
	v_mfma_f32_16x16x32_bf16 v[40:43], v[116:119], v[144:147], v[40:43]
	v_mfma_f32_16x16x32_bf16 v[8:11], v[124:127], v[144:147], v[8:11]
	v_mfma_f32_16x16x32_bf16 v[36:39], v[116:119], v[160:163], v[36:39]
	v_mfma_f32_16x16x32_bf16 v[4:7], v[124:127], v[160:163], v[4:7]
	v_mfma_f32_16x16x32_bf16 v[32:35], v[116:119], v[188:191], v[32:35]
	v_mfma_f32_16x16x32_bf16 v[0:3], v[124:127], v[188:191], v[0:3]
	s_barrier
	s_setprio 0
	s_add_i32 s51, s51, 2
	s_add_u32 s49, s49, 0x100
	s_addc_u32 s50, s50, 0
	s_cmp_gt_u32 s51, 29
	s_mov_b64 s[20:21], s[22:23]
	s_cbranch_scc0 .LBB0_528
	v_lshl_or_b32 v220, s38, 7, v214
	v_ashrrev_i32_e32 v221, 31, v220
	v_lshlrev_b64 v[96:97], 2, v[220:221]
	v_lshl_add_u64 v[112:113], s[2:3], 0, v[96:97]
	v_add_co_u32_e32 v102, vcc, s72, v112
	s_mov_b64 s[20:21], 0xb000
	s_nop 0
	v_addc_co_u32_e32 v103, vcc, 0, v113, vcc
	s_mov_b32 s13, 0x16000
	v_lshl_add_u64 v[100:101], v[112:113], 0, s[20:21]
	s_mov_b64 s[20:21], 0x16000
	v_add_co_u32_e32 v106, vcc, s13, v112
	s_nop 0
	v_lshl_add_u64 v[104:105], v[112:113], 0, s[20:21]
	v_addc_co_u32_e32 v107, vcc, 0, v113, vcc
	v_lshl_add_u64 v[114:115], s[6:7], 0, v[96:97]
	v_lshl_add_u64 v[188:189], s[10:11], 0, v[96:97]
	global_load_dwordx4 v[96:99], v[112:113], off offset:16
	global_load_dwordx4 v[128:131], v[112:113], off
	global_load_dwordx4 v[132:135], v[102:103], off
	s_nop 0
	global_load_dwordx4 v[100:103], v[100:101], off offset:16
	s_nop 0
	global_load_dwordx4 v[136:139], v[106:107], off
	s_nop 0
	global_load_dwordx4 v[104:107], v[104:105], off offset:16
	s_nop 0
	global_load_dwordx4 v[108:111], v[114:115], off offset:16
	global_load_dwordx4 v[144:147], v[114:115], off
	s_movk_i32 s13, 0x5000
	v_add_co_u32_e32 v116, vcc, s13, v112
	s_mov_b64 s[20:21], 0x5800
	s_nop 0
	v_addc_co_u32_e32 v117, vcc, 0, v113, vcc
	s_mov_b32 s13, 0x10000
	v_lshl_add_u64 v[114:115], v[112:113], 0, s[20:21]
	s_mov_b64 s[20:21], 0x10800
	v_add_co_u32_e32 v120, vcc, s13, v112
	global_load_dwordx4 v[160:163], v[116:117], off offset:2048
	s_nop 0
	global_load_dwordx4 v[116:119], v[114:115], off offset:16
	v_lshl_add_u64 v[114:115], v[112:113], 0, s[20:21]
	v_addc_co_u32_e32 v121, vcc, 0, v113, vcc
	s_mov_b64 s[20:21], 0x1b800
	s_mov_b32 s13, 0x1b000
	global_load_dwordx4 v[168:171], v[120:121], off offset:2048
	s_nop 0
	global_load_dwordx4 v[120:123], v[114:115], off offset:16
	v_lshl_add_u64 v[114:115], v[112:113], 0, s[20:21]
	v_add_co_u32_e32 v112, vcc, s13, v112
	s_nop 0
	v_addc_co_u32_e32 v113, vcc, 0, v113, vcc
	global_load_dwordx4 v[152:155], v[112:113], off offset:2048
	s_nop 0
	global_load_dwordx4 v[112:115], v[114:115], off offset:16
	s_nop 0
	global_load_dwordx4 v[124:127], v[188:189], off offset:16
	s_nop 0
	global_load_dwordx4 v[188:191], v[188:189], off
	s_and_b64 vcc, exec, s[4:5]
	s_cbranch_vccz .LBB0_531
	s_barrier

; #define PG8_STAGE(bufoff, gbase, voff) do { _Pragma("unroll") for (int _i = 0; _i < 2; ++_i) \
;         __builtin_amdgcn_global_load_lds((const unsigned*)((const char*)(gbase) + (voff)[_i]), (LAS unsigned*)(lds + (bufoff) + ldsw + _i * 8192), 16, 0, 0); } while (0)
; #define PG8_LDA(dst, b, h) do { _Pragma("unroll") for (int m = 0; m < 4; ++m) _Pragma("unroll") for (int k = 0; k < 2; ++k) dst[m][k] = *(const LAS bf16x8*)(lds + PG8_SA(b, h) + aoff + m * 2048 + k * 1024); } while (0)
; #define PG8_LDB(dst, b, h) do { _Pragma("unroll") for (int n = 0; n < 2; ++n) _Pragma("unroll") for (int k = 0; k < 2; ++k) dst[n][k] = *(const LAS bf16x8*)(lds + PG8_SB(b, h) + boff + n * 2048 + k * 1024); } while (0)
; #define PG8_MMA(ai, bj, At, Bt) do { __builtin_amdgcn_s_setprio(1); _Pragma("unroll") for (int m = 0; m < 4; ++m) _Pragma("unroll") for (int n = 0; n < 2; ++n) _Pragma("unroll") for (int k = 0; k < 2; ++k) \
;         acc[ai][bj][m][n] = __builtin_amdgcn_mfma_f32_16x16x32_bf16(Bt[n][k], At[m][k], acc[ai][bj][m][n], 0, 0, 0); __builtin_amdgcn_s_setprio(0); } while (0)
; #define PG8_WAIT_V(n) asm volatile("s_waitcnt vmcnt(" #n ")" ::: "memory")
; #define PG8_WAIT_L(n) asm volatile("s_waitcnt lgkmcnt(" #n ")" ::: "memory")
; #define PG8_BAR __builtin_amdgcn_s_barrier()
; template <class Epi, bool PERMA = false, bool DUAL = false, bool ALIGN_EPI = true, bool SP2 = true>
; __device__ __forceinline__ void gemm_phase(LAS unsigned char* lds, const Gemm g, const StaticOrder& S, const Epi& E) {
;     ...
;             const bool last = (t == nt - 2);
;             const char* a1 = cA + (size_t)(t + 1) * kstep;
;             const char* a2 = last ? nA : cA + (size_t)(t + 2) * kstep; const char* b2 = last ? nB : cB + (size_t)(t + 2) * kstep;
;             const char* a3 = a2 + kstep; const char* b3 = b2 + kstep;
;             if constexpr (SP2) {
;             PG8_LDB(B0, 0, 0); PG8_LDB(B1, 0, 1); PG8_SCHED; PG8_LDA(At, 0, 0); PG8_STAGE(PG8_SA(1, 1), a1 + hstepA, voffA);
;             PG8_WAIT_V(8); PG8_WAIT_L(0); PG8_BAR; PG8_MMA(0, 0, At, B0); PG8_MMA(0, 1, At, B1); PG8_BAR; PG8_SCHED;
;             PG8_LDA(At, 0, 1); PG8_STAGE(PG8_SB(0, 0), b2, voffB); PG8_STAGE(PG8_SB(0, 1), b2 + hstepB, voffB); PG8_STAGE(PG8_SA(0, 0), a2, voffA);
;             PG8_WAIT_V(8); PG8_WAIT_L(0); PG8_BAR; PG8_MMA(1, 0, At, B0); PG8_MMA(1, 1, At, B1); PG8_BAR; PG8_SCHED;
.LBB0_675:
	s_add_u32 s14, s12, 0x100
	s_addc_u32 s15, s13, 0
	s_add_i32 s36, 0, 0x10000
	s_cmpk_eq_i32 s33, 0x54
	s_cselect_b32 s19, s1, s15
	s_cselect_b32 s18, s0, s14
	s_cselect_b32 s17, s7, s11
	s_cselect_b32 s16, s6, s9
	s_add_i32 s37, 0, 0x14000
	v_add_u32_e32 v116, s36, v193
	v_add_u32_e32 v156, s37, v193
	ds_read_b128 v[104:107], v116
	ds_read_b128 v[108:111], v116 offset:1024
	ds_read_b128 v[112:115], v116 offset:2048
	ds_read_b128 v[116:119], v116 offset:3072
	ds_read_b128 v[144:147], v156
	ds_read_b128 v[148:151], v156 offset:1024
	ds_read_b128 v[152:155], v156 offset:2048
	ds_read_b128 v[156:159], v156 offset:3072
	v_lshl_add_u64 v[206:207], s[12:13], 0, v[180:181]
	s_add_i32 m0, s21, 0xc000
	ds_read_b128 v[184:187], v212
	ds_read_b128 v[188:191], v212 offset:1024
	ds_read_b128 v[214:217], v212 offset:2048
	ds_read_b128 v[218:221], v212 offset:3072
	ds_read_b128 v[222:225], v212 offset:4096
	ds_read_b128 v[226:229], v212 offset:5120
	ds_read_b128 v[238:241], v212 offset:6144
	ds_read_b128 v[242:245], v212 offset:7168
	global_load_lds_dwordx4 v[206:207], off
	v_lshl_add_u64 v[206:207], s[12:13], 0, v[182:183]
	s_add_i32 m0, s21, 0xe000
	s_nop 0
	global_load_lds_dwordx4 v[206:207], off
	s_waitcnt vmcnt(8)
	s_waitcnt lgkmcnt(0)
	s_setprio 1
	s_barrier
	v_mfma_f32_16x16x32_bf16 v[140:143], v[104:107], v[184:187], v[140:143]
	v_mfma_f32_16x16x32_bf16 v[136:139], v[112:115], v[184:187], v[136:139]
	v_mfma_f32_16x16x32_bf16 v[124:127], v[104:107], v[214:217], v[124:127]
	v_mfma_f32_16x16x32_bf16 v[120:123], v[112:115], v[214:217], v[120:123]
	v_mfma_f32_16x16x32_bf16 v[92:95], v[104:107], v[222:225], v[92:95]
	v_mfma_f32_16x16x32_bf16 v[88:91], v[112:115], v[222:225], v[88:91]
	v_mfma_f32_16x16x32_bf16 v[76:79], v[104:107], v[238:241], v[76:79]
	v_mfma_f32_16x16x32_bf16 v[72:75], v[112:115], v[238:241], v[72:75]
	v_mfma_f32_16x16x32_bf16 v[140:143], v[108:111], v[188:191], v[140:143]
	v_mfma_f32_16x16x32_bf16 v[136:139], v[116:119], v[188:191], v[136:139]
	v_mfma_f32_16x16x32_bf16 v[124:127], v[108:111], v[218:221], v[124:127]
	v_mfma_f32_16x16x32_bf16 v[120:123], v[116:119], v[218:221], v[120:123]
	v_mfma_f32_16x16x32_bf16 v[92:95], v[108:111], v[226:229], v[92:95]
	v_mfma_f32_16x16x32_bf16 v[88:91], v[116:119], v[226:229], v[88:91]
	v_mfma_f32_16x16x32_bf16 v[76:79], v[108:111], v[242:245], v[76:79]
	v_mfma_f32_16x16x32_bf16 v[72:75], v[116:119], v[242:245], v[72:75]
	v_mfma_f32_16x16x32_bf16 v[132:135], v[144:147], v[184:187], v[132:135]
	v_mfma_f32_16x16x32_bf16 v[128:131], v[152:155], v[184:187], v[128:131]
	v_mfma_f32_16x16x32_bf16 v[100:103], v[144:147], v[214:217], v[100:103]
	v_mfma_f32_16x16x32_bf16 v[96:99], v[152:155], v[214:217], v[96:99]
	v_mfma_f32_16x16x32_bf16 v[84:87], v[144:147], v[222:225], v[84:87]
	v_mfma_f32_16x16x32_bf16 v[80:83], v[152:155], v[222:225], v[80:83]
	v_mfma_f32_16x16x32_bf16 v[68:71], v[144:147], v[238:241], v[68:71]
	v_mfma_f32_16x16x32_bf16 v[64:67], v[152:155], v[238:241], v[64:67]
	v_mfma_f32_16x16x32_bf16 v[132:135], v[148:151], v[188:191], v[132:135]
	v_mfma_f32_16x16x32_bf16 v[128:131], v[156:159], v[188:191], v[128:131]
	v_mfma_f32_16x16x32_bf16 v[100:103], v[148:151], v[218:221], v[100:103]
	v_mfma_f32_16x16x32_bf16 v[96:99], v[156:159], v[218:221], v[96:99]
	v_mfma_f32_16x16x32_bf16 v[84:87], v[148:151], v[226:229], v[84:87]
	v_mfma_f32_16x16x32_bf16 v[80:83], v[156:159], v[226:229], v[80:83]
	v_mfma_f32_16x16x32_bf16 v[68:71], v[148:151], v[242:245], v[68:71]
	v_mfma_f32_16x16x32_bf16 v[64:67], v[156:159], v[242:245], v[64:67]
	s_barrier
	s_setprio 0
	s_add_i32 s12, s36, s20
	v_lshl_add_u64 v[206:207], s[16:17], 0, v[164:165]
	s_mov_b32 m0, s12
	ds_read_b128 v[184:187], v212 offset:16384
	ds_read_b128 v[188:191], v212 offset:17408
	ds_read_b128 v[214:217], v212 offset:18432
	ds_read_b128 v[218:221], v212 offset:19456
	ds_read_b128 v[222:225], v212 offset:20480
	ds_read_b128 v[226:229], v212 offset:21504
	ds_read_b128 v[238:241], v212 offset:22528
	ds_read_b128 v[242:245], v212 offset:23552
	global_load_lds_dwordx4 v[206:207], off
	s_add_i32 m0, s12, 0x2000
	s_add_u32 s12, s16, 0x160000
	v_lshl_add_u64 v[246:247], s[16:17], 0, v[160:161]
	s_addc_u32 s13, s17, 0
	s_add_i32 s36, s37, s20
	global_load_lds_dwordx4 v[246:247], off
	v_lshl_add_u64 v[248:249], s[12:13], 0, v[164:165]
	s_mov_b32 m0, s36
	v_lshl_add_u64 v[194:195], s[18:19], 0, v[162:163]
	global_load_lds_dwordx4 v[248:249], off
	v_lshl_add_u64 v[248:249], s[12:13], 0, v[160:161]
	s_add_i32 m0, s36, 0x2000
	s_nop 0
	global_load_lds_dwordx4 v[248:249], off
	v_lshl_add_u64 v[248:249], s[18:19], 0, v[166:167]
	s_mov_b32 m0, s21
	s_nop 0
	global_load_lds_dwordx4 v[248:249], off
	s_mov_b32 m0, s22
	s_nop 0
	global_load_lds_dwordx4 v[194:195], off
	s_waitcnt vmcnt(8)
	s_waitcnt lgkmcnt(0)
	s_setprio 1
	s_barrier
; #define PG8_STAGE(bufoff, gbase, voff) do { _Pragma("unroll") for (int _i = 0; _i < 2; ++_i) \
;         __builtin_amdgcn_global_load_lds((const unsigned*)((const char*)(gbase) + (voff)[_i]), (LAS unsigned*)(lds + (bufoff) + ldsw + _i * 8192), 16, 0, 0); } while (0)
; #define PG8_LDA(dst, b, h) do { _Pragma("unroll") for (int m = 0; m < 4; ++m) _Pragma("unroll") for (int k = 0; k < 2; ++k) dst[m][k] = *(const LAS bf16x8*)(lds + PG8_SA(b, h) + aoff + m * 2048 + k * 1024); } while (0)
; #define PG8_LDB(dst, b, h) do { _Pragma("unroll") for (int n = 0; n < 2; ++n) _Pragma("unroll") for (int k = 0; k < 2; ++k) dst[n][k] = *(const LAS bf16x8*)(lds + PG8_SB(b, h) + boff + n * 2048 + k * 1024); } while (0)
; #define PG8_MMA(ai, bj, At, Bt) do { __builtin_amdgcn_s_setprio(1); _Pragma("unroll") for (int m = 0; m < 4; ++m) _Pragma("unroll") for (int n = 0; n < 2; ++n) _Pragma("unroll") for (int k = 0; k < 2; ++k) \
;         acc[ai][bj][m][n] = __builtin_amdgcn_mfma_f32_16x16x32_bf16(Bt[n][k], At[m][k], acc[ai][bj][m][n], 0, 0, 0); __builtin_amdgcn_s_setprio(0); } while (0)
; #define PG8_WAIT_V(n) asm volatile("s_waitcnt vmcnt(" #n ")" ::: "memory")
; #define PG8_WAIT_L(n) asm volatile("s_waitcnt lgkmcnt(" #n ")" ::: "memory")
; #define PG8_BAR __builtin_amdgcn_s_barrier()
; #define PG8_SCHED __builtin_amdgcn_sched_barrier(0)
; template <class Epi, bool PERMA = false, bool DUAL = false, bool ALIGN_EPI = true, bool SP2 = true>
; __device__ __forceinline__ void gemm_phase(LAS unsigned char* lds, const Gemm g, const StaticOrder& S, const Epi& E) {
;     ...
;             PG8_WAIT_V(8); PG8_WAIT_L(0); PG8_BAR; PG8_MMA(1, 0, At, B0); PG8_MMA(1, 1, At, B1); PG8_BAR; PG8_SCHED;
;             PG8_LDB(B0, 1, 0); PG8_LDB(B1, 1, 1); PG8_SCHED; PG8_LDA(At, 1, 0); PG8_STAGE(PG8_SA(0, 1), a2 + hstepA, voffA);
;             PG8_WAIT_V(8); PG8_WAIT_L(0); PG8_BAR; PG8_MMA(0, 0, At, B0); PG8_MMA(0, 1, At, B1); PG8_BAR; PG8_SCHED;
	v_mfma_f32_16x16x32_bf16 v[60:63], v[104:107], v[184:187], v[60:63]
	v_mfma_f32_16x16x32_bf16 v[56:59], v[112:115], v[184:187], v[56:59]
	v_mfma_f32_16x16x32_bf16 v[44:47], v[104:107], v[214:217], v[44:47]
	v_mfma_f32_16x16x32_bf16 v[40:43], v[112:115], v[214:217], v[40:43]
	v_mfma_f32_16x16x32_bf16 v[28:31], v[104:107], v[222:225], v[28:31]
	v_mfma_f32_16x16x32_bf16 v[24:27], v[112:115], v[222:225], v[24:27]
	v_mfma_f32_16x16x32_bf16 v[12:15], v[104:107], v[238:241], v[12:15]
	v_mfma_f32_16x16x32_bf16 v[8:11], v[112:115], v[238:241], v[8:11]
	v_mfma_f32_16x16x32_bf16 v[60:63], v[108:111], v[188:191], v[60:63]
	v_mfma_f32_16x16x32_bf16 v[56:59], v[116:119], v[188:191], v[56:59]
	v_mfma_f32_16x16x32_bf16 v[44:47], v[108:111], v[218:221], v[44:47]
	v_mfma_f32_16x16x32_bf16 v[40:43], v[116:119], v[218:221], v[40:43]
	v_mfma_f32_16x16x32_bf16 v[28:31], v[108:111], v[226:229], v[28:31]
	v_mfma_f32_16x16x32_bf16 v[24:27], v[116:119], v[226:229], v[24:27]
	v_mfma_f32_16x16x32_bf16 v[12:15], v[108:111], v[242:245], v[12:15]
	v_mfma_f32_16x16x32_bf16 v[8:11], v[116:119], v[242:245], v[8:11]
	v_mfma_f32_16x16x32_bf16 v[52:55], v[144:147], v[184:187], v[52:55]
	v_mfma_f32_16x16x32_bf16 v[48:51], v[152:155], v[184:187], v[48:51]
	v_mfma_f32_16x16x32_bf16 v[36:39], v[144:147], v[214:217], v[36:39]
	v_mfma_f32_16x16x32_bf16 v[32:35], v[152:155], v[214:217], v[32:35]
	v_mfma_f32_16x16x32_bf16 v[20:23], v[144:147], v[222:225], v[20:23]
	v_mfma_f32_16x16x32_bf16 v[16:19], v[152:155], v[222:225], v[16:19]
	v_mfma_f32_16x16x32_bf16 v[4:7], v[144:147], v[238:241], v[4:7]
	v_mfma_f32_16x16x32_bf16 v[0:3], v[152:155], v[238:241], v[0:3]
	v_mfma_f32_16x16x32_bf16 v[52:55], v[148:151], v[188:191], v[52:55]
	v_mfma_f32_16x16x32_bf16 v[48:51], v[156:159], v[188:191], v[48:51]
	v_mfma_f32_16x16x32_bf16 v[36:39], v[148:151], v[218:221], v[36:39]
	v_mfma_f32_16x16x32_bf16 v[32:35], v[156:159], v[218:221], v[32:35]
	v_mfma_f32_16x16x32_bf16 v[20:23], v[148:151], v[226:229], v[20:23]
	v_mfma_f32_16x16x32_bf16 v[16:19], v[156:159], v[226:229], v[16:19]
	v_mfma_f32_16x16x32_bf16 v[4:7], v[148:151], v[242:245], v[4:7]
	v_mfma_f32_16x16x32_bf16 v[0:3], v[156:159], v[242:245], v[0:3]
	s_barrier
	s_setprio 0
	s_add_i32 s36, 0, 0x18000
	s_add_i32 s37, 0, 0x1c000
	v_add_u32_e32 v116, s36, v193
	v_add_u32_e32 v156, s37, v193
	ds_read_b128 v[104:107], v116
	ds_read_b128 v[108:111], v116 offset:1024
	ds_read_b128 v[112:115], v116 offset:2048
	ds_read_b128 v[116:119], v116 offset:3072
	ds_read_b128 v[144:147], v156
	ds_read_b128 v[148:151], v156 offset:1024
	ds_read_b128 v[152:155], v156 offset:2048
	ds_read_b128 v[156:159], v156 offset:3072
	s_add_u32 s12, s18, 0x160000
	s_addc_u32 s13, s19, 0
	s_mov_b32 m0, s23
	v_lshl_add_u64 v[196:197], s[12:13], 0, v[166:167]
	ds_read_b128 v[184:187], v212 offset:32768
	ds_read_b128 v[188:191], v212 offset:33792
	ds_read_b128 v[214:217], v212 offset:34816
	ds_read_b128 v[218:221], v212 offset:35840
	ds_read_b128 v[222:225], v212 offset:36864
	ds_read_b128 v[226:229], v212 offset:37888
	ds_read_b128 v[238:241], v212 offset:38912
	ds_read_b128 v[242:245], v212 offset:39936
	global_load_lds_dwordx4 v[196:197], off
	v_lshl_add_u64 v[196:197], s[12:13], 0, v[162:163]
	s_mov_b32 m0, s24
	s_nop 0
	global_load_lds_dwordx4 v[196:197], off
	s_waitcnt vmcnt(8)
	s_waitcnt lgkmcnt(0)
	s_setprio 1
	s_barrier
	v_mfma_f32_16x16x32_bf16 v[140:143], v[104:107], v[184:187], v[140:143]
	v_mfma_f32_16x16x32_bf16 v[136:139], v[112:115], v[184:187], v[136:139]
	v_mfma_f32_16x16x32_bf16 v[124:127], v[104:107], v[214:217], v[124:127]
	v_mfma_f32_16x16x32_bf16 v[120:123], v[112:115], v[214:217], v[120:123]
	v_mfma_f32_16x16x32_bf16 v[92:95], v[104:107], v[222:225], v[92:95]
	v_mfma_f32_16x16x32_bf16 v[88:91], v[112:115], v[222:225], v[88:91]
	v_mfma_f32_16x16x32_bf16 v[76:79], v[104:107], v[238:241], v[76:79]
	v_mfma_f32_16x16x32_bf16 v[72:75], v[112:115], v[238:241], v[72:75]
	v_mfma_f32_16x16x32_bf16 v[140:143], v[108:111], v[188:191], v[140:143]
	v_mfma_f32_16x16x32_bf16 v[136:139], v[116:119], v[188:191], v[136:139]
	v_mfma_f32_16x16x32_bf16 v[124:127], v[108:111], v[218:221], v[124:127]
	v_mfma_f32_16x16x32_bf16 v[120:123], v[116:119], v[218:221], v[120:123]
	v_mfma_f32_16x16x32_bf16 v[92:95], v[108:111], v[226:229], v[92:95]
	v_mfma_f32_16x16x32_bf16 v[88:91], v[116:119], v[226:229], v[88:91]
	v_mfma_f32_16x16x32_bf16 v[76:79], v[108:111], v[242:245], v[76:79]
	v_mfma_f32_16x16x32_bf16 v[72:75], v[116:119], v[242:245], v[72:75]
	v_mfma_f32_16x16x32_bf16 v[132:135], v[144:147], v[184:187], v[132:135]
	v_mfma_f32_16x16x32_bf16 v[128:131], v[152:155], v[184:187], v[128:131]
	v_mfma_f32_16x16x32_bf16 v[100:103], v[144:147], v[214:217], v[100:103]
	v_mfma_f32_16x16x32_bf16 v[96:99], v[152:155], v[214:217], v[96:99]
	v_mfma_f32_16x16x32_bf16 v[84:87], v[144:147], v[222:225], v[84:87]
	v_mfma_f32_16x16x32_bf16 v[80:83], v[152:155], v[222:225], v[80:83]
	v_mfma_f32_16x16x32_bf16 v[68:71], v[144:147], v[238:241], v[68:71]
	v_mfma_f32_16x16x32_bf16 v[64:67], v[152:155], v[238:241], v[64:67]
	v_mfma_f32_16x16x32_bf16 v[132:135], v[148:151], v[188:191], v[132:135]
	v_mfma_f32_16x16x32_bf16 v[128:131], v[156:159], v[188:191], v[128:131]
	v_mfma_f32_16x16x32_bf16 v[100:103], v[148:151], v[218:221], v[100:103]
	v_mfma_f32_16x16x32_bf16 v[96:99], v[156:159], v[218:221], v[96:99]
	v_mfma_f32_16x16x32_bf16 v[84:87], v[148:151], v[226:229], v[84:87]
	v_mfma_f32_16x16x32_bf16 v[80:83], v[156:159], v[226:229], v[80:83]
	v_mfma_f32_16x16x32_bf16 v[68:71], v[148:151], v[242:245], v[68:71]
	v_mfma_f32_16x16x32_bf16 v[64:67], v[156:159], v[242:245], v[64:67]
	s_barrier
; #define PG8_STAGE(bufoff, gbase, voff) do { _Pragma("unroll") for (int _i = 0; _i < 2; ++_i) \
;         __builtin_amdgcn_global_load_lds((const unsigned*)((const char*)(gbase) + (voff)[_i]), (LAS unsigned*)(lds + (bufoff) + ldsw + _i * 8192), 16, 0, 0); } while (0)
; #define PG8_LDA(dst, b, h) do { _Pragma("unroll") for (int m = 0; m < 4; ++m) _Pragma("unroll") for (int k = 0; k < 2; ++k) dst[m][k] = *(const LAS bf16x8*)(lds + PG8_SA(b, h) + aoff + m * 2048 + k * 1024); } while (0)
; #define PG8_MMA(ai, bj, At, Bt) do { __builtin_amdgcn_s_setprio(1); _Pragma("unroll") for (int m = 0; m < 4; ++m) _Pragma("unroll") for (int n = 0; n < 2; ++n) _Pragma("unroll") for (int k = 0; k < 2; ++k) \
;         acc[ai][bj][m][n] = __builtin_amdgcn_mfma_f32_16x16x32_bf16(Bt[n][k], At[m][k], acc[ai][bj][m][n], 0, 0, 0); __builtin_amdgcn_s_setprio(0); } while (0)
; #define PG8_WAIT_V(n) asm volatile("s_waitcnt vmcnt(" #n ")" ::: "memory")
; #define PG8_WAIT_L(n) asm volatile("s_waitcnt lgkmcnt(" #n ")" ::: "memory")
; #define PG8_BAR __builtin_amdgcn_s_barrier()
; #define PG8_SCHED __builtin_amdgcn_sched_barrier(0)
; template <class Epi, bool PERMA = false, bool DUAL = false, bool ALIGN_EPI = true, bool SP2 = true>
; __device__ __forceinline__ void gemm_phase(LAS unsigned char* lds, const Gemm g, const StaticOrder& S, const Epi& E) {
;     ...
;         for (int t = 0; t < nt; t += 2) {
;     ...
;             PG8_LDA(At, 1, 1); PG8_STAGE(PG8_SB(1, 0), b3, voffB); PG8_STAGE(PG8_SB(1, 1), b3 + hstepB, voffB); PG8_STAGE(PG8_SA(1, 0), a3, voffA);
;             PG8_WAIT_V(8); PG8_WAIT_L(0); PG8_BAR; PG8_MMA(1, 0, At, B0); PG8_MMA(1, 1, At, B1); PG8_BAR; PG8_SCHED;
;     ...
;         if constexpr (ALIGN_EPI) { if (wr == 0) PG8_BAR; }
	s_setprio 0
	s_add_i32 s12, s36, s20
	v_lshl_add_u64 v[196:197], v[206:207], 0, s[38:39]
	s_mov_b32 m0, s12
	ds_read_b128 v[184:187], v212 offset:49152
	ds_read_b128 v[188:191], v212 offset:50176
	ds_read_b128 v[214:217], v212 offset:51200
	ds_read_b128 v[218:221], v212 offset:52224
	ds_read_b128 v[222:225], v212 offset:53248
	ds_read_b128 v[226:229], v212 offset:54272
	ds_read_b128 v[238:241], v212 offset:55296
	ds_read_b128 v[242:245], v212 offset:56320
	global_load_lds_dwordx4 v[196:197], off
	s_add_i32 m0, s12, 0x2000
	s_add_u32 s12, s16, 0x160080
	v_lshl_add_u64 v[196:197], v[246:247], 0, s[38:39]
	s_addc_u32 s13, s17, 0
	s_add_i32 s16, s37, s20
	global_load_lds_dwordx4 v[196:197], off
	v_lshl_add_u64 v[196:197], s[12:13], 0, v[164:165]
	s_mov_b32 m0, s16
	v_lshl_add_u64 v[194:195], v[194:195], 0, s[38:39]
	global_load_lds_dwordx4 v[196:197], off
	v_lshl_add_u64 v[196:197], s[12:13], 0, v[160:161]
	s_add_i32 m0, s16, 0x2000
	s_nop 0
	global_load_lds_dwordx4 v[196:197], off
	v_lshl_add_u64 v[196:197], v[248:249], 0, s[38:39]
	s_mov_b32 m0, s29
	s_nop 0
	global_load_lds_dwordx4 v[196:197], off
	s_mov_b32 m0, s30
	s_nop 0
	global_load_lds_dwordx4 v[194:195], off
	s_waitcnt vmcnt(8)
	s_waitcnt lgkmcnt(0)
	s_setprio 1
	s_barrier
	v_mfma_f32_16x16x32_bf16 v[60:63], v[104:107], v[184:187], v[60:63]
	v_mfma_f32_16x16x32_bf16 v[56:59], v[112:115], v[184:187], v[56:59]
	v_mfma_f32_16x16x32_bf16 v[44:47], v[104:107], v[214:217], v[44:47]
	v_mfma_f32_16x16x32_bf16 v[40:43], v[112:115], v[214:217], v[40:43]
	v_mfma_f32_16x16x32_bf16 v[28:31], v[104:107], v[222:225], v[28:31]
	v_mfma_f32_16x16x32_bf16 v[24:27], v[112:115], v[222:225], v[24:27]
	v_mfma_f32_16x16x32_bf16 v[12:15], v[104:107], v[238:241], v[12:15]
	v_mfma_f32_16x16x32_bf16 v[8:11], v[112:115], v[238:241], v[8:11]
	v_mfma_f32_16x16x32_bf16 v[60:63], v[108:111], v[188:191], v[60:63]
	v_mfma_f32_16x16x32_bf16 v[56:59], v[116:119], v[188:191], v[56:59]
	v_mfma_f32_16x16x32_bf16 v[44:47], v[108:111], v[218:221], v[44:47]
	v_mfma_f32_16x16x32_bf16 v[40:43], v[116:119], v[218:221], v[40:43]
	v_mfma_f32_16x16x32_bf16 v[28:31], v[108:111], v[226:229], v[28:31]
	v_mfma_f32_16x16x32_bf16 v[24:27], v[116:119], v[226:229], v[24:27]
	v_mfma_f32_16x16x32_bf16 v[12:15], v[108:111], v[242:245], v[12:15]
	v_mfma_f32_16x16x32_bf16 v[8:11], v[116:119], v[242:245], v[8:11]
	v_mfma_f32_16x16x32_bf16 v[52:55], v[144:147], v[184:187], v[52:55]
	v_mfma_f32_16x16x32_bf16 v[48:51], v[152:155], v[184:187], v[48:51]
	v_mfma_f32_16x16x32_bf16 v[36:39], v[144:147], v[214:217], v[36:39]
	v_mfma_f32_16x16x32_bf16 v[32:35], v[152:155], v[214:217], v[32:35]
	v_mfma_f32_16x16x32_bf16 v[20:23], v[144:147], v[222:225], v[20:23]
	v_mfma_f32_16x16x32_bf16 v[16:19], v[152:155], v[222:225], v[16:19]
	v_mfma_f32_16x16x32_bf16 v[4:7], v[144:147], v[238:241], v[4:7]
	v_mfma_f32_16x16x32_bf16 v[0:3], v[152:155], v[238:241], v[0:3]
	v_mfma_f32_16x16x32_bf16 v[52:55], v[148:151], v[188:191], v[52:55]
	v_mfma_f32_16x16x32_bf16 v[48:51], v[156:159], v[188:191], v[48:51]
	v_mfma_f32_16x16x32_bf16 v[36:39], v[148:151], v[218:221], v[36:39]
	v_mfma_f32_16x16x32_bf16 v[32:35], v[156:159], v[218:221], v[32:35]
	v_mfma_f32_16x16x32_bf16 v[20:23], v[148:151], v[226:229], v[20:23]
	v_mfma_f32_16x16x32_bf16 v[16:19], v[156:159], v[226:229], v[16:19]
	v_mfma_f32_16x16x32_bf16 v[4:7], v[148:151], v[242:245], v[4:7]
	v_mfma_f32_16x16x32_bf16 v[0:3], v[156:159], v[242:245], v[0:3]
	s_barrier
	s_setprio 0
	s_add_i32 s33, s33, 2
	s_add_u32 s9, s9, 0x100
	s_addc_u32 s11, s11, 0
	s_cmpk_gt_u32 s33, 0x55
	s_mov_b64 s[12:13], s[14:15]
	s_cbranch_scc0 .LBB0_675
	s_and_b64 vcc, exec, s[4:5]
	s_cbranch_vccz .LBB0_678
	s_barrier

; #define PG8_STAGE(bufoff, gbase, voff) do { _Pragma("unroll") for (int _i = 0; _i < 2; ++_i) \
;         __builtin_amdgcn_global_load_lds((const unsigned*)((const char*)(gbase) + (voff)[_i]), (LAS unsigned*)(lds + (bufoff) + ldsw + _i * 8192), 16, 0, 0); } while (0)
; #define PG8_LDA(dst, b, h) do { _Pragma("unroll") for (int m = 0; m < 4; ++m) _Pragma("unroll") for (int k = 0; k < 2; ++k) dst[m][k] = *(const LAS bf16x8*)(lds + PG8_SA(b, h) + aoff + m * 2048 + k * 1024); } while (0)
; #define PG8_LDB(dst, b, h) do { _Pragma("unroll") for (int n = 0; n < 2; ++n) _Pragma("unroll") for (int k = 0; k < 2; ++k) dst[n][k] = *(const LAS bf16x8*)(lds + PG8_SB(b, h) + boff + n * 2048 + k * 1024); } while (0)
; #define PG8_MMA(ai, bj, At, Bt) do { __builtin_amdgcn_s_setprio(1); _Pragma("unroll") for (int m = 0; m < 4; ++m) _Pragma("unroll") for (int n = 0; n < 2; ++n) _Pragma("unroll") for (int k = 0; k < 2; ++k) \
;         acc[ai][bj][m][n] = __builtin_amdgcn_mfma_f32_16x16x32_bf16(Bt[n][k], At[m][k], acc[ai][bj][m][n], 0, 0, 0); __builtin_amdgcn_s_setprio(0); } while (0)
; #define PG8_WAIT_V(n) asm volatile("s_waitcnt vmcnt(" #n ")" ::: "memory")
; #define PG8_WAIT_L(n) asm volatile("s_waitcnt lgkmcnt(" #n ")" ::: "memory")
; #define PG8_BAR __builtin_amdgcn_s_barrier()
; template <class Epi, bool PERMA = false, bool DUAL = false, bool ALIGN_EPI = true, bool SP2 = true>
; __device__ __forceinline__ void gemm_phase(LAS unsigned char* lds, const Gemm g, const StaticOrder& S, const Epi& E) {
;     ...
;             const bool last = (t == nt - 2);
;             const char* a1 = cA + (size_t)(t + 1) * kstep;
;             const char* a2 = last ? nA : cA + (size_t)(t + 2) * kstep; const char* b2 = last ? nB : cB + (size_t)(t + 2) * kstep;
;             const char* a3 = a2 + kstep; const char* b3 = b2 + kstep;
;             if constexpr (SP2) {
;             PG8_LDB(B0, 0, 0); PG8_LDB(B1, 0, 1); PG8_SCHED; PG8_LDA(At, 0, 0); PG8_STAGE(PG8_SA(1, 1), a1 + hstepA, voffA);
;             PG8_WAIT_V(8); PG8_WAIT_L(0); PG8_BAR; PG8_MMA(0, 0, At, B0); PG8_MMA(0, 1, At, B1); PG8_BAR; PG8_SCHED;
;             PG8_LDA(At, 0, 1); PG8_STAGE(PG8_SB(0, 0), b2, voffB); PG8_STAGE(PG8_SB(0, 1), b2 + hstepB, voffB); PG8_STAGE(PG8_SA(0, 0), a2, voffA);
;             PG8_WAIT_V(8); PG8_WAIT_L(0); PG8_BAR; PG8_MMA(1, 0, At, B0); PG8_MMA(1, 1, At, B1); PG8_BAR; PG8_SCHED;
.LBB0_770:
	s_add_u32 s23, s14, s22
	s_addc_u32 s28, s15, 0
	s_add_u32 s26, s23, 0x100
	s_addc_u32 s27, s28, 0
	s_and_b64 s[24:25], s[20:21], exec
	s_cselect_b32 s25, s9, s27
	s_cselect_b32 s24, s47, s26
	s_add_u32 s22, s16, s22
	s_addc_u32 s26, s17, 0
	s_add_u32 s22, s22, 0x100
	s_addc_u32 s26, s26, 0
	s_add_i32 s57, 0, 0x10000
	s_and_b64 s[20:21], s[20:21], exec
	s_cselect_b32 s27, s7, s26
	s_cselect_b32 s26, s48, s22
	s_add_i32 s21, 0, 0x14000
	s_add_u32 s30, s23, 0x10080
	s_addc_u32 s31, s28, 0
	s_add_i32 s56, s57, s35
	s_add_i32 m0, s36, 0xc000
	s_add_i32 s59, s36, 0xe000
	s_add_i32 s53, s56, 0x2000
	v_add_u32_e32 v138, s57, v140
	s_add_u32 s28, s26, 0x10000
	ds_read_b128 v[142:145], v138
	ds_read_b128 v[146:149], v138 offset:1024
	ds_read_b128 v[150:153], v138 offset:2048
	ds_read_b128 v[154:157], v138 offset:3072
	v_add_u32_e32 v138, s21, v140
	s_addc_u32 s29, s27, 0
	s_add_i32 s55, s21, s35
	ds_read_b128 v[158:161], v138
	ds_read_b128 v[162:165], v138 offset:1024
	ds_read_b128 v[166:169], v138 offset:2048
	ds_read_b128 v[170:173], v138 offset:3072
	s_add_i32 s54, s55, 0x2000
	s_add_i32 s52, 0, 0x18000
	s_add_i32 s51, 0, 0x1c000
	s_add_u32 s22, s24, 0x10000
	s_addc_u32 s23, s25, 0
	s_add_i32 s50, s52, s35
	s_add_i32 s49, s50, 0x2000
	s_add_u32 s20, s26, 0x10080
	s_addc_u32 s21, s27, 0
	s_add_i32 s58, s51, s35
	s_add_i32 s57, s58, 0x2000
	v_lshl_add_u64 v[138:139], s[30:31], 0, v[134:135]
	ds_read_b128 v[174:177], v141
	ds_read_b128 v[178:181], v141 offset:1024
	ds_read_b128 v[182:185], v141 offset:2048
	ds_read_b128 v[186:189], v141 offset:3072
	ds_read_b128 v[206:209], v141 offset:4096
	ds_read_b128 v[210:213], v141 offset:5120
	ds_read_b128 v[214:217], v141 offset:6144
	ds_read_b128 v[218:221], v141 offset:7168
	global_load_lds_dwordx4 v[138:139], off
	v_lshl_add_u64 v[138:139], s[30:31], 0, v[130:131]
	s_mov_b32 m0, s59
	s_nop 0
	global_load_lds_dwordx4 v[138:139], off
	s_waitcnt vmcnt(8)
	s_waitcnt lgkmcnt(0)
	s_setprio 1
	s_barrier
	v_mfma_f32_16x16x32_bf16 v[124:127], v[142:145], v[174:177], v[124:127]
	v_mfma_f32_16x16x32_bf16 v[120:123], v[150:153], v[174:177], v[120:123]
	v_mfma_f32_16x16x32_bf16 v[116:119], v[142:145], v[182:185], v[116:119]
	v_mfma_f32_16x16x32_bf16 v[108:111], v[150:153], v[182:185], v[108:111]
	v_mfma_f32_16x16x32_bf16 v[100:103], v[142:145], v[206:209], v[100:103]
	v_mfma_f32_16x16x32_bf16 v[92:95], v[150:153], v[206:209], v[92:95]
	v_mfma_f32_16x16x32_bf16 v[84:87], v[142:145], v[214:217], v[84:87]
	v_mfma_f32_16x16x32_bf16 v[76:79], v[150:153], v[214:217], v[76:79]
	v_mfma_f32_16x16x32_bf16 v[124:127], v[146:149], v[178:181], v[124:127]
	v_mfma_f32_16x16x32_bf16 v[120:123], v[154:157], v[178:181], v[120:123]
	v_mfma_f32_16x16x32_bf16 v[116:119], v[146:149], v[186:189], v[116:119]
	v_mfma_f32_16x16x32_bf16 v[108:111], v[154:157], v[186:189], v[108:111]
	v_mfma_f32_16x16x32_bf16 v[100:103], v[146:149], v[210:213], v[100:103]
	v_mfma_f32_16x16x32_bf16 v[92:95], v[154:157], v[210:213], v[92:95]
	v_mfma_f32_16x16x32_bf16 v[84:87], v[146:149], v[218:221], v[84:87]
	v_mfma_f32_16x16x32_bf16 v[76:79], v[154:157], v[218:221], v[76:79]
	v_mfma_f32_16x16x32_bf16 v[112:115], v[158:161], v[174:177], v[112:115]
	v_mfma_f32_16x16x32_bf16 v[104:107], v[166:169], v[174:177], v[104:107]
	v_mfma_f32_16x16x32_bf16 v[96:99], v[158:161], v[182:185], v[96:99]
	v_mfma_f32_16x16x32_bf16 v[88:91], v[166:169], v[182:185], v[88:91]
	v_mfma_f32_16x16x32_bf16 v[80:83], v[158:161], v[206:209], v[80:83]
	v_mfma_f32_16x16x32_bf16 v[72:75], v[166:169], v[206:209], v[72:75]
	v_mfma_f32_16x16x32_bf16 v[68:71], v[158:161], v[214:217], v[68:71]
	v_mfma_f32_16x16x32_bf16 v[64:67], v[166:169], v[214:217], v[64:67]
	v_mfma_f32_16x16x32_bf16 v[112:115], v[162:165], v[178:181], v[112:115]
	v_mfma_f32_16x16x32_bf16 v[104:107], v[170:173], v[178:181], v[104:107]
	v_mfma_f32_16x16x32_bf16 v[96:99], v[162:165], v[186:189], v[96:99]
	v_mfma_f32_16x16x32_bf16 v[88:91], v[170:173], v[186:189], v[88:91]
	v_mfma_f32_16x16x32_bf16 v[80:83], v[162:165], v[210:213], v[80:83]
	v_mfma_f32_16x16x32_bf16 v[72:75], v[170:173], v[210:213], v[72:75]
	v_mfma_f32_16x16x32_bf16 v[68:71], v[162:165], v[218:221], v[68:71]
	v_mfma_f32_16x16x32_bf16 v[64:67], v[170:173], v[218:221], v[64:67]
	s_barrier
	s_setprio 0
	s_mov_b32 m0, s56
	v_lshl_add_u64 v[138:139], s[26:27], 0, v[132:133]
	ds_read_b128 v[174:177], v141 offset:16384
	ds_read_b128 v[178:181], v141 offset:17408
	ds_read_b128 v[182:185], v141 offset:18432
	ds_read_b128 v[186:189], v141 offset:19456
	ds_read_b128 v[206:209], v141 offset:20480
	ds_read_b128 v[210:213], v141 offset:21504
	ds_read_b128 v[214:217], v141 offset:22528
	ds_read_b128 v[218:221], v141 offset:23552
	global_load_lds_dwordx4 v[138:139], off
	v_lshl_add_u64 v[190:191], s[26:27], 0, v[128:129]
	s_mov_b32 m0, s53
	v_lshl_add_u64 v[194:195], s[28:29], 0, v[132:133]
	global_load_lds_dwordx4 v[190:191], off
	s_mov_b32 m0, s55
	v_lshl_add_u64 v[196:197], s[24:25], 0, v[130:131]
	global_load_lds_dwordx4 v[194:195], off
	v_lshl_add_u64 v[194:195], s[28:29], 0, v[128:129]
	s_mov_b32 m0, s54
	s_nop 0
	global_load_lds_dwordx4 v[194:195], off
	v_lshl_add_u64 v[194:195], s[24:25], 0, v[134:135]
	s_mov_b32 m0, s36
	s_nop 0
	global_load_lds_dwordx4 v[194:195], off
	s_mov_b32 m0, s37
	s_nop 0
	global_load_lds_dwordx4 v[196:197], off
	s_waitcnt vmcnt(8)
	s_waitcnt lgkmcnt(0)
	s_setprio 1
	s_barrier
; #define PG8_STAGE(bufoff, gbase, voff) do { _Pragma("unroll") for (int _i = 0; _i < 2; ++_i) \
;         __builtin_amdgcn_global_load_lds((const unsigned*)((const char*)(gbase) + (voff)[_i]), (LAS unsigned*)(lds + (bufoff) + ldsw + _i * 8192), 16, 0, 0); } while (0)
; #define PG8_LDA(dst, b, h) do { _Pragma("unroll") for (int m = 0; m < 4; ++m) _Pragma("unroll") for (int k = 0; k < 2; ++k) dst[m][k] = *(const LAS bf16x8*)(lds + PG8_SA(b, h) + aoff + m * 2048 + k * 1024); } while (0)
; #define PG8_LDB(dst, b, h) do { _Pragma("unroll") for (int n = 0; n < 2; ++n) _Pragma("unroll") for (int k = 0; k < 2; ++k) dst[n][k] = *(const LAS bf16x8*)(lds + PG8_SB(b, h) + boff + n * 2048 + k * 1024); } while (0)
; #define PG8_MMA(ai, bj, At, Bt) do { __builtin_amdgcn_s_setprio(1); _Pragma("unroll") for (int m = 0; m < 4; ++m) _Pragma("unroll") for (int n = 0; n < 2; ++n) _Pragma("unroll") for (int k = 0; k < 2; ++k) \
;         acc[ai][bj][m][n] = __builtin_amdgcn_mfma_f32_16x16x32_bf16(Bt[n][k], At[m][k], acc[ai][bj][m][n], 0, 0, 0); __builtin_amdgcn_s_setprio(0); } while (0)
; #define PG8_WAIT_V(n) asm volatile("s_waitcnt vmcnt(" #n ")" ::: "memory")
; #define PG8_WAIT_L(n) asm volatile("s_waitcnt lgkmcnt(" #n ")" ::: "memory")
; #define PG8_BAR __builtin_amdgcn_s_barrier()
; #define PG8_SCHED __builtin_amdgcn_sched_barrier(0)
; template <class Epi, bool PERMA = false, bool DUAL = false, bool ALIGN_EPI = true, bool SP2 = true>
; __device__ __forceinline__ void gemm_phase(LAS unsigned char* lds, const Gemm g, const StaticOrder& S, const Epi& E) {
;     ...
;             PG8_WAIT_V(8); PG8_WAIT_L(0); PG8_BAR; PG8_MMA(1, 0, At, B0); PG8_MMA(1, 1, At, B1); PG8_BAR; PG8_SCHED;
;             PG8_LDB(B0, 1, 0); PG8_LDB(B1, 1, 1); PG8_SCHED; PG8_LDA(At, 1, 0); PG8_STAGE(PG8_SA(0, 1), a2 + hstepA, voffA);
;             PG8_WAIT_V(8); PG8_WAIT_L(0); PG8_BAR; PG8_MMA(0, 0, At, B0); PG8_MMA(0, 1, At, B1); PG8_BAR; PG8_SCHED;
	v_mfma_f32_16x16x32_bf16 v[60:63], v[142:145], v[174:177], v[60:63]
	v_mfma_f32_16x16x32_bf16 v[56:59], v[150:153], v[174:177], v[56:59]
	v_mfma_f32_16x16x32_bf16 v[52:55], v[142:145], v[182:185], v[52:55]
	v_mfma_f32_16x16x32_bf16 v[44:47], v[150:153], v[182:185], v[44:47]
	v_mfma_f32_16x16x32_bf16 v[36:39], v[142:145], v[206:209], v[36:39]
	v_mfma_f32_16x16x32_bf16 v[28:31], v[150:153], v[206:209], v[28:31]
	v_mfma_f32_16x16x32_bf16 v[20:23], v[142:145], v[214:217], v[20:23]
	v_mfma_f32_16x16x32_bf16 v[12:15], v[150:153], v[214:217], v[12:15]
	v_mfma_f32_16x16x32_bf16 v[60:63], v[146:149], v[178:181], v[60:63]
	v_mfma_f32_16x16x32_bf16 v[56:59], v[154:157], v[178:181], v[56:59]
	v_mfma_f32_16x16x32_bf16 v[52:55], v[146:149], v[186:189], v[52:55]
	v_mfma_f32_16x16x32_bf16 v[44:47], v[154:157], v[186:189], v[44:47]
	v_mfma_f32_16x16x32_bf16 v[36:39], v[146:149], v[210:213], v[36:39]
	v_mfma_f32_16x16x32_bf16 v[28:31], v[154:157], v[210:213], v[28:31]
	v_mfma_f32_16x16x32_bf16 v[20:23], v[146:149], v[218:221], v[20:23]
	v_mfma_f32_16x16x32_bf16 v[12:15], v[154:157], v[218:221], v[12:15]
	v_mfma_f32_16x16x32_bf16 v[48:51], v[158:161], v[174:177], v[48:51]
	v_mfma_f32_16x16x32_bf16 v[40:43], v[166:169], v[174:177], v[40:43]
	v_mfma_f32_16x16x32_bf16 v[32:35], v[158:161], v[182:185], v[32:35]
	v_mfma_f32_16x16x32_bf16 v[24:27], v[166:169], v[182:185], v[24:27]
	v_mfma_f32_16x16x32_bf16 v[16:19], v[158:161], v[206:209], v[16:19]
	v_mfma_f32_16x16x32_bf16 v[8:11], v[166:169], v[206:209], v[8:11]
	v_mfma_f32_16x16x32_bf16 v[4:7], v[158:161], v[214:217], v[4:7]
	v_mfma_f32_16x16x32_bf16 v[0:3], v[166:169], v[214:217], v[0:3]
	v_mfma_f32_16x16x32_bf16 v[48:51], v[162:165], v[178:181], v[48:51]
	v_mfma_f32_16x16x32_bf16 v[40:43], v[170:173], v[178:181], v[40:43]
	v_mfma_f32_16x16x32_bf16 v[32:35], v[162:165], v[186:189], v[32:35]
	v_mfma_f32_16x16x32_bf16 v[24:27], v[170:173], v[186:189], v[24:27]
	v_mfma_f32_16x16x32_bf16 v[16:19], v[162:165], v[210:213], v[16:19]
	v_mfma_f32_16x16x32_bf16 v[8:11], v[170:173], v[210:213], v[8:11]
	v_mfma_f32_16x16x32_bf16 v[4:7], v[162:165], v[218:221], v[4:7]
	v_mfma_f32_16x16x32_bf16 v[0:3], v[170:173], v[218:221], v[0:3]
	s_barrier
	s_setprio 0
	v_add_u32_e32 v154, s52, v140
	v_add_u32_e32 v170, s51, v140
	ds_read_b128 v[142:145], v154
	ds_read_b128 v[146:149], v154 offset:1024
	ds_read_b128 v[150:153], v154 offset:2048
	ds_read_b128 v[154:157], v154 offset:3072
	ds_read_b128 v[158:161], v170
	ds_read_b128 v[162:165], v170 offset:1024
	ds_read_b128 v[166:169], v170 offset:2048
	ds_read_b128 v[170:173], v170 offset:3072
	s_mov_b32 m0, s38
	v_lshl_add_u64 v[222:223], s[22:23], 0, v[134:135]
	ds_read_b128 v[174:177], v141 offset:32768
	ds_read_b128 v[178:181], v141 offset:33792
	ds_read_b128 v[182:185], v141 offset:34816
	ds_read_b128 v[186:189], v141 offset:35840
	ds_read_b128 v[206:209], v141 offset:36864
	ds_read_b128 v[210:213], v141 offset:37888
	ds_read_b128 v[214:217], v141 offset:38912
	ds_read_b128 v[218:221], v141 offset:39936
	global_load_lds_dwordx4 v[222:223], off
	v_lshl_add_u64 v[222:223], s[22:23], 0, v[130:131]
	s_mov_b32 m0, s39
	s_nop 0
	global_load_lds_dwordx4 v[222:223], off
	s_waitcnt vmcnt(8)
	s_waitcnt lgkmcnt(0)
	s_setprio 1
	s_barrier
	v_mfma_f32_16x16x32_bf16 v[124:127], v[142:145], v[174:177], v[124:127]
	v_mfma_f32_16x16x32_bf16 v[120:123], v[150:153], v[174:177], v[120:123]
	v_mfma_f32_16x16x32_bf16 v[116:119], v[142:145], v[182:185], v[116:119]
	v_mfma_f32_16x16x32_bf16 v[108:111], v[150:153], v[182:185], v[108:111]
	v_mfma_f32_16x16x32_bf16 v[100:103], v[142:145], v[206:209], v[100:103]
	v_mfma_f32_16x16x32_bf16 v[92:95], v[150:153], v[206:209], v[92:95]
	v_mfma_f32_16x16x32_bf16 v[84:87], v[142:145], v[214:217], v[84:87]
	v_mfma_f32_16x16x32_bf16 v[76:79], v[150:153], v[214:217], v[76:79]
	v_mfma_f32_16x16x32_bf16 v[124:127], v[146:149], v[178:181], v[124:127]
	v_mfma_f32_16x16x32_bf16 v[120:123], v[154:157], v[178:181], v[120:123]
	v_mfma_f32_16x16x32_bf16 v[116:119], v[146:149], v[186:189], v[116:119]
	v_mfma_f32_16x16x32_bf16 v[108:111], v[154:157], v[186:189], v[108:111]
	v_mfma_f32_16x16x32_bf16 v[100:103], v[146:149], v[210:213], v[100:103]
	v_mfma_f32_16x16x32_bf16 v[92:95], v[154:157], v[210:213], v[92:95]
	v_mfma_f32_16x16x32_bf16 v[84:87], v[146:149], v[218:221], v[84:87]
	v_mfma_f32_16x16x32_bf16 v[76:79], v[154:157], v[218:221], v[76:79]
	v_mfma_f32_16x16x32_bf16 v[112:115], v[158:161], v[174:177], v[112:115]
	v_mfma_f32_16x16x32_bf16 v[104:107], v[166:169], v[174:177], v[104:107]
	v_mfma_f32_16x16x32_bf16 v[96:99], v[158:161], v[182:185], v[96:99]
	v_mfma_f32_16x16x32_bf16 v[88:91], v[166:169], v[182:185], v[88:91]
	v_mfma_f32_16x16x32_bf16 v[80:83], v[158:161], v[206:209], v[80:83]
	v_mfma_f32_16x16x32_bf16 v[72:75], v[166:169], v[206:209], v[72:75]
	v_mfma_f32_16x16x32_bf16 v[68:71], v[158:161], v[214:217], v[68:71]
	v_mfma_f32_16x16x32_bf16 v[64:67], v[166:169], v[214:217], v[64:67]
	v_mfma_f32_16x16x32_bf16 v[112:115], v[162:165], v[178:181], v[112:115]
	v_mfma_f32_16x16x32_bf16 v[104:107], v[170:173], v[178:181], v[104:107]
	v_mfma_f32_16x16x32_bf16 v[96:99], v[162:165], v[186:189], v[96:99]
	v_mfma_f32_16x16x32_bf16 v[88:91], v[170:173], v[186:189], v[88:91]
	v_mfma_f32_16x16x32_bf16 v[80:83], v[162:165], v[210:213], v[80:83]
	v_mfma_f32_16x16x32_bf16 v[72:75], v[170:173], v[210:213], v[72:75]
	v_mfma_f32_16x16x32_bf16 v[68:71], v[162:165], v[218:221], v[68:71]
	v_mfma_f32_16x16x32_bf16 v[64:67], v[170:173], v[218:221], v[64:67]
	s_barrier
; #define PG8_STAGE(bufoff, gbase, voff) do { _Pragma("unroll") for (int _i = 0; _i < 2; ++_i) \
;         __builtin_amdgcn_global_load_lds((const unsigned*)((const char*)(gbase) + (voff)[_i]), (LAS unsigned*)(lds + (bufoff) + ldsw + _i * 8192), 16, 0, 0); } while (0)
; #define PG8_LDA(dst, b, h) do { _Pragma("unroll") for (int m = 0; m < 4; ++m) _Pragma("unroll") for (int k = 0; k < 2; ++k) dst[m][k] = *(const LAS bf16x8*)(lds + PG8_SA(b, h) + aoff + m * 2048 + k * 1024); } while (0)
; #define PG8_MMA(ai, bj, At, Bt) do { __builtin_amdgcn_s_setprio(1); _Pragma("unroll") for (int m = 0; m < 4; ++m) _Pragma("unroll") for (int n = 0; n < 2; ++n) _Pragma("unroll") for (int k = 0; k < 2; ++k) \
;         acc[ai][bj][m][n] = __builtin_amdgcn_mfma_f32_16x16x32_bf16(Bt[n][k], At[m][k], acc[ai][bj][m][n], 0, 0, 0); __builtin_amdgcn_s_setprio(0); } while (0)
; #define PG8_WAIT_V(n) asm volatile("s_waitcnt vmcnt(" #n ")" ::: "memory")
; #define PG8_WAIT_L(n) asm volatile("s_waitcnt lgkmcnt(" #n ")" ::: "memory")
; #define PG8_BAR __builtin_amdgcn_s_barrier()
; #define PG8_SCHED __builtin_amdgcn_sched_barrier(0)
; template <class Epi, bool PERMA = false, bool DUAL = false, bool ALIGN_EPI = true, bool SP2 = true>
; __device__ __forceinline__ void gemm_phase(LAS unsigned char* lds, const Gemm g, const StaticOrder& S, const Epi& E) {
;     ...
;         for (int t = 0; t < nt; t += 2) {
;     ...
;             PG8_LDA(At, 1, 1); PG8_STAGE(PG8_SB(1, 0), b3, voffB); PG8_STAGE(PG8_SB(1, 1), b3 + hstepB, voffB); PG8_STAGE(PG8_SA(1, 0), a3, voffA);
;             PG8_WAIT_V(8); PG8_WAIT_L(0); PG8_BAR; PG8_MMA(1, 0, At, B0); PG8_MMA(1, 1, At, B1); PG8_BAR; PG8_SCHED;
;     ...
;         if constexpr (ALIGN_EPI) { if (wr == 0) PG8_BAR; }
	s_setprio 0
	s_mov_b32 m0, s50
	v_lshl_add_u64 v[138:139], v[138:139], 0, s[68:69]
	ds_read_b128 v[174:177], v141 offset:49152
	ds_read_b128 v[178:181], v141 offset:50176
	ds_read_b128 v[182:185], v141 offset:51200
	ds_read_b128 v[186:189], v141 offset:52224
	ds_read_b128 v[206:209], v141 offset:53248
	ds_read_b128 v[210:213], v141 offset:54272
	ds_read_b128 v[214:217], v141 offset:55296
	ds_read_b128 v[218:221], v141 offset:56320
	global_load_lds_dwordx4 v[138:139], off
	v_lshl_add_u64 v[138:139], v[190:191], 0, s[68:69]
	s_mov_b32 m0, s49
	s_nop 0
	global_load_lds_dwordx4 v[138:139], off
	v_lshl_add_u64 v[138:139], s[20:21], 0, v[132:133]
	s_mov_b32 m0, s58
	s_nop 0
	global_load_lds_dwordx4 v[138:139], off
	v_lshl_add_u64 v[138:139], s[20:21], 0, v[128:129]
	s_mov_b32 m0, s57
	s_nop 0
	global_load_lds_dwordx4 v[138:139], off
	v_lshl_add_u64 v[138:139], v[194:195], 0, s[68:69]
	s_mov_b32 m0, s42
	s_nop 0
	global_load_lds_dwordx4 v[138:139], off
	v_lshl_add_u64 v[138:139], v[196:197], 0, s[68:69]
	s_mov_b32 m0, s43
	s_nop 0
	global_load_lds_dwordx4 v[138:139], off
	s_waitcnt vmcnt(8)
	s_waitcnt lgkmcnt(0)
	s_setprio 1
	s_barrier
	v_mfma_f32_16x16x32_bf16 v[60:63], v[142:145], v[174:177], v[60:63]
	v_mfma_f32_16x16x32_bf16 v[56:59], v[150:153], v[174:177], v[56:59]
	v_mfma_f32_16x16x32_bf16 v[52:55], v[142:145], v[182:185], v[52:55]
	v_mfma_f32_16x16x32_bf16 v[44:47], v[150:153], v[182:185], v[44:47]
	v_mfma_f32_16x16x32_bf16 v[36:39], v[142:145], v[206:209], v[36:39]
	v_mfma_f32_16x16x32_bf16 v[28:31], v[150:153], v[206:209], v[28:31]
	v_mfma_f32_16x16x32_bf16 v[20:23], v[142:145], v[214:217], v[20:23]
	v_mfma_f32_16x16x32_bf16 v[12:15], v[150:153], v[214:217], v[12:15]
	v_mfma_f32_16x16x32_bf16 v[60:63], v[146:149], v[178:181], v[60:63]
	v_mfma_f32_16x16x32_bf16 v[56:59], v[154:157], v[178:181], v[56:59]
	v_mfma_f32_16x16x32_bf16 v[52:55], v[146:149], v[186:189], v[52:55]
	v_mfma_f32_16x16x32_bf16 v[44:47], v[154:157], v[186:189], v[44:47]
	v_mfma_f32_16x16x32_bf16 v[36:39], v[146:149], v[210:213], v[36:39]
	v_mfma_f32_16x16x32_bf16 v[28:31], v[154:157], v[210:213], v[28:31]
	v_mfma_f32_16x16x32_bf16 v[20:23], v[146:149], v[218:221], v[20:23]
	v_mfma_f32_16x16x32_bf16 v[12:15], v[154:157], v[218:221], v[12:15]
	v_mfma_f32_16x16x32_bf16 v[48:51], v[158:161], v[174:177], v[48:51]
	v_mfma_f32_16x16x32_bf16 v[40:43], v[166:169], v[174:177], v[40:43]
	v_mfma_f32_16x16x32_bf16 v[32:35], v[158:161], v[182:185], v[32:35]
	v_mfma_f32_16x16x32_bf16 v[24:27], v[166:169], v[182:185], v[24:27]
	v_mfma_f32_16x16x32_bf16 v[16:19], v[158:161], v[206:209], v[16:19]
	v_mfma_f32_16x16x32_bf16 v[8:11], v[166:169], v[206:209], v[8:11]
	v_mfma_f32_16x16x32_bf16 v[4:7], v[158:161], v[214:217], v[4:7]
	v_mfma_f32_16x16x32_bf16 v[0:3], v[166:169], v[214:217], v[0:3]
	v_mfma_f32_16x16x32_bf16 v[48:51], v[162:165], v[178:181], v[48:51]
	v_mfma_f32_16x16x32_bf16 v[40:43], v[170:173], v[178:181], v[40:43]
	v_mfma_f32_16x16x32_bf16 v[32:35], v[162:165], v[186:189], v[32:35]
	v_mfma_f32_16x16x32_bf16 v[24:27], v[170:173], v[186:189], v[24:27]
	v_mfma_f32_16x16x32_bf16 v[16:19], v[162:165], v[210:213], v[16:19]
	v_mfma_f32_16x16x32_bf16 v[8:11], v[170:173], v[210:213], v[8:11]
	v_mfma_f32_16x16x32_bf16 v[4:7], v[162:165], v[218:221], v[4:7]
	v_mfma_f32_16x16x32_bf16 v[0:3], v[170:173], v[218:221], v[0:3]
	s_barrier
	s_setprio 0
	s_movk_i32 s22, 0x100
	s_andn2_b64 vcc, exec, s[18:19]
	s_mov_b64 s[20:21], -1
	s_mov_b64 s[18:19], 0
	s_cbranch_vccz .LBB0_770
	s_and_b64 vcc, exec, s[4:5]
	s_cbranch_vccz .LBB0_773
	s_barrier

; #define PG8_STAGE(bufoff, gbase, voff) do { _Pragma("unroll") for (int _i = 0; _i < 2; ++_i) \
;         __builtin_amdgcn_global_load_lds((const unsigned*)((const char*)(gbase) + (voff)[_i]), (LAS unsigned*)(lds + (bufoff) + ldsw + _i * 8192), 16, 0, 0); } while (0)
; #define PG8_LDA(dst, b, h) do { _Pragma("unroll") for (int m = 0; m < 4; ++m) _Pragma("unroll") for (int k = 0; k < 2; ++k) dst[m][k] = *(const LAS bf16x8*)(lds + PG8_SA(b, h) + aoff + m * 2048 + k * 1024); } while (0)
; #define PG8_LDB(dst, b, h) do { _Pragma("unroll") for (int n = 0; n < 2; ++n) _Pragma("unroll") for (int k = 0; k < 2; ++k) dst[n][k] = *(const LAS bf16x8*)(lds + PG8_SB(b, h) + boff + n * 2048 + k * 1024); } while (0)
; #define PG8_MMA(ai, bj, At, Bt) do { __builtin_amdgcn_s_setprio(1); _Pragma("unroll") for (int m = 0; m < 4; ++m) _Pragma("unroll") for (int n = 0; n < 2; ++n) _Pragma("unroll") for (int k = 0; k < 2; ++k) \
;         acc[ai][bj][m][n] = __builtin_amdgcn_mfma_f32_16x16x32_bf16(Bt[n][k], At[m][k], acc[ai][bj][m][n], 0, 0, 0); __builtin_amdgcn_s_setprio(0); } while (0)
; #define PG8_WAIT_V(n) asm volatile("s_waitcnt vmcnt(" #n ")" ::: "memory")
; #define PG8_WAIT_L(n) asm volatile("s_waitcnt lgkmcnt(" #n ")" ::: "memory")
; #define PG8_BAR __builtin_amdgcn_s_barrier()
; template <class Epi, bool PERMA = false, bool DUAL = false, bool ALIGN_EPI = true, bool SP2 = true>
; __device__ __forceinline__ void gemm_phase(LAS unsigned char* lds, const Gemm g, const StaticOrder& S, const Epi& E) {
;     ...
;             const bool last = (t == nt - 2);
;             const char* a1 = cA + (size_t)(t + 1) * kstep;
;             const char* a2 = last ? nA : cA + (size_t)(t + 2) * kstep; const char* b2 = last ? nB : cB + (size_t)(t + 2) * kstep;
;             const char* a3 = a2 + kstep; const char* b3 = b2 + kstep;
;             if constexpr (SP2) {
;             PG8_LDB(B0, 0, 0); PG8_LDB(B1, 0, 1); PG8_SCHED; PG8_LDA(At, 0, 0); PG8_STAGE(PG8_SA(1, 1), a1 + hstepA, voffA);
;             PG8_WAIT_V(8); PG8_WAIT_L(0); PG8_BAR; PG8_MMA(0, 0, At, B0); PG8_MMA(0, 1, At, B1); PG8_BAR; PG8_SCHED;
;             PG8_LDA(At, 0, 1); PG8_STAGE(PG8_SB(0, 0), b2, voffB); PG8_STAGE(PG8_SB(0, 1), b2 + hstepB, voffB); PG8_STAGE(PG8_SA(0, 0), a2, voffA);
;             PG8_WAIT_V(8); PG8_WAIT_L(0); PG8_BAR; PG8_MMA(1, 0, At, B0); PG8_MMA(1, 1, At, B1); PG8_BAR; PG8_SCHED;
.LBB0_790:
	s_add_u32 s14, s12, 0xfff80080
	s_addc_u32 s15, s13, -1
	s_add_i32 s36, 0, 0x10000
	s_cmp_eq_u32 s35, 28
	s_cselect_b32 s17, s7, s15
	s_cselect_b32 s16, s30, s14
	s_cselect_b32 s15, s5, s34
	s_cselect_b32 s14, s31, s33
	s_add_i32 s40, 0, 0x14000
	v_add_u32_e32 v140, s36, v190
	v_add_u32_e32 v156, s40, v190
	ds_read_b128 v[120:123], v140
	ds_read_b128 v[128:131], v140 offset:1024
	ds_read_b128 v[132:135], v140 offset:2048
	ds_read_b128 v[140:143], v140 offset:3072
	ds_read_b128 v[144:147], v156
	ds_read_b128 v[148:151], v156 offset:1024
	ds_read_b128 v[152:155], v156 offset:2048
	ds_read_b128 v[156:159], v156 offset:3072
	v_lshl_add_u64 v[194:195], s[12:13], 0, v[174:175]
	s_add_i32 m0, s19, 0xc000
	ds_read_b128 v[178:181], v191
	ds_read_b128 v[182:185], v191 offset:1024
	ds_read_b128 v[186:189], v191 offset:2048
	ds_read_b128 v[206:209], v191 offset:3072
	ds_read_b128 v[210:213], v191 offset:4096
	ds_read_b128 v[214:217], v191 offset:5120
	ds_read_b128 v[218:221], v191 offset:6144
	ds_read_b128 v[222:225], v191 offset:7168
	global_load_lds_dwordx4 v[194:195], off
	v_lshl_add_u64 v[194:195], s[12:13], 0, v[176:177]
	s_add_i32 m0, s19, 0xe000
	s_nop 0
	global_load_lds_dwordx4 v[194:195], off
	s_waitcnt vmcnt(8)
	s_waitcnt lgkmcnt(0)
	s_setprio 1
	s_barrier
	v_mfma_f32_16x16x32_bf16 v[136:139], v[120:123], v[178:181], v[136:139]
	v_mfma_f32_16x16x32_bf16 v[124:127], v[132:135], v[178:181], v[124:127]
	v_mfma_f32_16x16x32_bf16 v[108:111], v[120:123], v[186:189], v[108:111]
	v_mfma_f32_16x16x32_bf16 v[104:107], v[132:135], v[186:189], v[104:107]
	v_mfma_f32_16x16x32_bf16 v[92:95], v[120:123], v[210:213], v[92:95]
	v_mfma_f32_16x16x32_bf16 v[88:91], v[132:135], v[210:213], v[88:91]
	v_mfma_f32_16x16x32_bf16 v[76:79], v[120:123], v[218:221], v[76:79]
	v_mfma_f32_16x16x32_bf16 v[72:75], v[132:135], v[218:221], v[72:75]
	v_mfma_f32_16x16x32_bf16 v[136:139], v[128:131], v[182:185], v[136:139]
	v_mfma_f32_16x16x32_bf16 v[124:127], v[140:143], v[182:185], v[124:127]
	v_mfma_f32_16x16x32_bf16 v[108:111], v[128:131], v[206:209], v[108:111]
	v_mfma_f32_16x16x32_bf16 v[104:107], v[140:143], v[206:209], v[104:107]
	v_mfma_f32_16x16x32_bf16 v[92:95], v[128:131], v[214:217], v[92:95]
	v_mfma_f32_16x16x32_bf16 v[88:91], v[140:143], v[214:217], v[88:91]
	v_mfma_f32_16x16x32_bf16 v[76:79], v[128:131], v[222:225], v[76:79]
	v_mfma_f32_16x16x32_bf16 v[72:75], v[140:143], v[222:225], v[72:75]
	v_mfma_f32_16x16x32_bf16 v[116:119], v[144:147], v[178:181], v[116:119]
	v_mfma_f32_16x16x32_bf16 v[112:115], v[152:155], v[178:181], v[112:115]
	v_mfma_f32_16x16x32_bf16 v[100:103], v[144:147], v[186:189], v[100:103]
	v_mfma_f32_16x16x32_bf16 v[96:99], v[152:155], v[186:189], v[96:99]
	v_mfma_f32_16x16x32_bf16 v[84:87], v[144:147], v[210:213], v[84:87]
	v_mfma_f32_16x16x32_bf16 v[80:83], v[152:155], v[210:213], v[80:83]
	v_mfma_f32_16x16x32_bf16 v[68:71], v[144:147], v[218:221], v[68:71]
	v_mfma_f32_16x16x32_bf16 v[64:67], v[152:155], v[218:221], v[64:67]
	v_mfma_f32_16x16x32_bf16 v[116:119], v[148:151], v[182:185], v[116:119]
	v_mfma_f32_16x16x32_bf16 v[112:115], v[156:159], v[182:185], v[112:115]
	v_mfma_f32_16x16x32_bf16 v[100:103], v[148:151], v[206:209], v[100:103]
	v_mfma_f32_16x16x32_bf16 v[96:99], v[156:159], v[206:209], v[96:99]
	v_mfma_f32_16x16x32_bf16 v[84:87], v[148:151], v[214:217], v[84:87]
	v_mfma_f32_16x16x32_bf16 v[80:83], v[156:159], v[214:217], v[80:83]
	v_mfma_f32_16x16x32_bf16 v[68:71], v[148:151], v[222:225], v[68:71]
	v_mfma_f32_16x16x32_bf16 v[64:67], v[156:159], v[222:225], v[64:67]
	s_barrier
	s_setprio 0
	s_add_i32 s36, s36, s18
	v_lshl_add_u64 v[194:195], s[14:15], 0, v[164:165]
	s_mov_b32 m0, s36
	ds_read_b128 v[178:181], v191 offset:16384
	ds_read_b128 v[182:185], v191 offset:17408
	ds_read_b128 v[186:189], v191 offset:18432
	ds_read_b128 v[206:209], v191 offset:19456
	ds_read_b128 v[210:213], v191 offset:20480
	ds_read_b128 v[214:217], v191 offset:21504
	ds_read_b128 v[218:221], v191 offset:22528
	ds_read_b128 v[222:225], v191 offset:23552
	global_load_lds_dwordx4 v[194:195], off
	s_add_i32 m0, s36, 0x2000
	s_add_u32 s36, s14, 0x80000
	v_lshl_add_u64 v[196:197], s[14:15], 0, v[160:161]
	s_addc_u32 s37, s15, 0
	s_add_i32 s40, s40, s18
	global_load_lds_dwordx4 v[196:197], off
	v_lshl_add_u64 v[226:227], s[36:37], 0, v[164:165]
	s_mov_b32 m0, s40
	v_lshl_add_u64 v[228:229], s[16:17], 0, v[162:163]
	global_load_lds_dwordx4 v[226:227], off
	v_lshl_add_u64 v[226:227], s[36:37], 0, v[160:161]
	s_add_i32 m0, s40, 0x2000
	s_nop 0
	global_load_lds_dwordx4 v[226:227], off
	v_lshl_add_u64 v[226:227], s[16:17], 0, v[166:167]
	s_mov_b32 m0, s19
	s_nop 0
	global_load_lds_dwordx4 v[226:227], off
	s_mov_b32 m0, s20
	s_nop 0
	global_load_lds_dwordx4 v[228:229], off
	s_waitcnt vmcnt(8)
	s_waitcnt lgkmcnt(0)
	s_setprio 1
	s_barrier
; #define PG8_STAGE(bufoff, gbase, voff) do { _Pragma("unroll") for (int _i = 0; _i < 2; ++_i) \
;         __builtin_amdgcn_global_load_lds((const unsigned*)((const char*)(gbase) + (voff)[_i]), (LAS unsigned*)(lds + (bufoff) + ldsw + _i * 8192), 16, 0, 0); } while (0)
; #define PG8_LDA(dst, b, h) do { _Pragma("unroll") for (int m = 0; m < 4; ++m) _Pragma("unroll") for (int k = 0; k < 2; ++k) dst[m][k] = *(const LAS bf16x8*)(lds + PG8_SA(b, h) + aoff + m * 2048 + k * 1024); } while (0)
; #define PG8_LDB(dst, b, h) do { _Pragma("unroll") for (int n = 0; n < 2; ++n) _Pragma("unroll") for (int k = 0; k < 2; ++k) dst[n][k] = *(const LAS bf16x8*)(lds + PG8_SB(b, h) + boff + n * 2048 + k * 1024); } while (0)
; #define PG8_MMA(ai, bj, At, Bt) do { __builtin_amdgcn_s_setprio(1); _Pragma("unroll") for (int m = 0; m < 4; ++m) _Pragma("unroll") for (int n = 0; n < 2; ++n) _Pragma("unroll") for (int k = 0; k < 2; ++k) \
;         acc[ai][bj][m][n] = __builtin_amdgcn_mfma_f32_16x16x32_bf16(Bt[n][k], At[m][k], acc[ai][bj][m][n], 0, 0, 0); __builtin_amdgcn_s_setprio(0); } while (0)
; #define PG8_WAIT_V(n) asm volatile("s_waitcnt vmcnt(" #n ")" ::: "memory")
; #define PG8_WAIT_L(n) asm volatile("s_waitcnt lgkmcnt(" #n ")" ::: "memory")
; #define PG8_BAR __builtin_amdgcn_s_barrier()
; #define PG8_SCHED __builtin_amdgcn_sched_barrier(0)
; template <class Epi, bool PERMA = false, bool DUAL = false, bool ALIGN_EPI = true, bool SP2 = true>
; __device__ __forceinline__ void gemm_phase(LAS unsigned char* lds, const Gemm g, const StaticOrder& S, const Epi& E) {
;     ...
;             PG8_WAIT_V(8); PG8_WAIT_L(0); PG8_BAR; PG8_MMA(1, 0, At, B0); PG8_MMA(1, 1, At, B1); PG8_BAR; PG8_SCHED;
;             PG8_LDB(B0, 1, 0); PG8_LDB(B1, 1, 1); PG8_SCHED; PG8_LDA(At, 1, 0); PG8_STAGE(PG8_SA(0, 1), a2 + hstepA, voffA);
;             PG8_WAIT_V(8); PG8_WAIT_L(0); PG8_BAR; PG8_MMA(0, 0, At, B0); PG8_MMA(0, 1, At, B1); PG8_BAR; PG8_SCHED;
	v_mfma_f32_16x16x32_bf16 v[60:63], v[120:123], v[178:181], v[60:63]
	v_mfma_f32_16x16x32_bf16 v[56:59], v[132:135], v[178:181], v[56:59]
	v_mfma_f32_16x16x32_bf16 v[44:47], v[120:123], v[186:189], v[44:47]
	v_mfma_f32_16x16x32_bf16 v[40:43], v[132:135], v[186:189], v[40:43]
	v_mfma_f32_16x16x32_bf16 v[28:31], v[120:123], v[210:213], v[28:31]
	v_mfma_f32_16x16x32_bf16 v[24:27], v[132:135], v[210:213], v[24:27]
	v_mfma_f32_16x16x32_bf16 v[12:15], v[120:123], v[218:221], v[12:15]
	v_mfma_f32_16x16x32_bf16 v[8:11], v[132:135], v[218:221], v[8:11]
	v_mfma_f32_16x16x32_bf16 v[60:63], v[128:131], v[182:185], v[60:63]
	v_mfma_f32_16x16x32_bf16 v[56:59], v[140:143], v[182:185], v[56:59]
	v_mfma_f32_16x16x32_bf16 v[44:47], v[128:131], v[206:209], v[44:47]
	v_mfma_f32_16x16x32_bf16 v[40:43], v[140:143], v[206:209], v[40:43]
	v_mfma_f32_16x16x32_bf16 v[28:31], v[128:131], v[214:217], v[28:31]
	v_mfma_f32_16x16x32_bf16 v[24:27], v[140:143], v[214:217], v[24:27]
	v_mfma_f32_16x16x32_bf16 v[12:15], v[128:131], v[222:225], v[12:15]
	v_mfma_f32_16x16x32_bf16 v[8:11], v[140:143], v[222:225], v[8:11]
	v_mfma_f32_16x16x32_bf16 v[52:55], v[144:147], v[178:181], v[52:55]
	v_mfma_f32_16x16x32_bf16 v[48:51], v[152:155], v[178:181], v[48:51]
	v_mfma_f32_16x16x32_bf16 v[36:39], v[144:147], v[186:189], v[36:39]
	v_mfma_f32_16x16x32_bf16 v[32:35], v[152:155], v[186:189], v[32:35]
	v_mfma_f32_16x16x32_bf16 v[20:23], v[144:147], v[210:213], v[20:23]
	v_mfma_f32_16x16x32_bf16 v[16:19], v[152:155], v[210:213], v[16:19]
	v_mfma_f32_16x16x32_bf16 v[0:3], v[144:147], v[218:221], v[0:3]
	v_mfma_f32_16x16x32_bf16 v[4:7], v[152:155], v[218:221], v[4:7]
	v_mfma_f32_16x16x32_bf16 v[52:55], v[148:151], v[182:185], v[52:55]
	v_mfma_f32_16x16x32_bf16 v[48:51], v[156:159], v[182:185], v[48:51]
	v_mfma_f32_16x16x32_bf16 v[36:39], v[148:151], v[206:209], v[36:39]
	v_mfma_f32_16x16x32_bf16 v[32:35], v[156:159], v[206:209], v[32:35]
	v_mfma_f32_16x16x32_bf16 v[20:23], v[148:151], v[214:217], v[20:23]
	v_mfma_f32_16x16x32_bf16 v[16:19], v[156:159], v[214:217], v[16:19]
	v_mfma_f32_16x16x32_bf16 v[0:3], v[148:151], v[222:225], v[0:3]
	v_mfma_f32_16x16x32_bf16 v[4:7], v[156:159], v[222:225], v[4:7]
	s_barrier
	s_setprio 0
	s_add_i32 s36, 0, 0x18000
	s_add_i32 s37, 0, 0x1c000
	v_add_u32_e32 v140, s36, v190
	v_add_u32_e32 v156, s37, v190
	ds_read_b128 v[120:123], v140
	ds_read_b128 v[128:131], v140 offset:1024
	ds_read_b128 v[132:135], v140 offset:2048
	ds_read_b128 v[140:143], v140 offset:3072
	ds_read_b128 v[144:147], v156
	ds_read_b128 v[148:151], v156 offset:1024
	ds_read_b128 v[152:155], v156 offset:2048
	ds_read_b128 v[156:159], v156 offset:3072
	s_add_u32 s16, s16, 0x80000
	s_addc_u32 s17, s17, 0
	s_mov_b32 m0, s21
	v_lshl_add_u64 v[238:239], s[16:17], 0, v[166:167]
	ds_read_b128 v[178:181], v191 offset:32768
	ds_read_b128 v[182:185], v191 offset:33792
	ds_read_b128 v[186:189], v191 offset:34816
	ds_read_b128 v[206:209], v191 offset:35840
	ds_read_b128 v[210:213], v191 offset:36864
	ds_read_b128 v[214:217], v191 offset:37888
	ds_read_b128 v[218:221], v191 offset:38912
	ds_read_b128 v[222:225], v191 offset:39936
	global_load_lds_dwordx4 v[238:239], off
	v_lshl_add_u64 v[238:239], s[16:17], 0, v[162:163]
	s_mov_b32 m0, s22
	s_nop 0
	global_load_lds_dwordx4 v[238:239], off
	s_waitcnt vmcnt(8)
	s_waitcnt lgkmcnt(0)
	s_setprio 1
	s_barrier
	v_mfma_f32_16x16x32_bf16 v[136:139], v[120:123], v[178:181], v[136:139]
	v_mfma_f32_16x16x32_bf16 v[124:127], v[132:135], v[178:181], v[124:127]
	v_mfma_f32_16x16x32_bf16 v[108:111], v[120:123], v[186:189], v[108:111]
	v_mfma_f32_16x16x32_bf16 v[104:107], v[132:135], v[186:189], v[104:107]
	v_mfma_f32_16x16x32_bf16 v[92:95], v[120:123], v[210:213], v[92:95]
	v_mfma_f32_16x16x32_bf16 v[88:91], v[132:135], v[210:213], v[88:91]
	v_mfma_f32_16x16x32_bf16 v[76:79], v[120:123], v[218:221], v[76:79]
	v_mfma_f32_16x16x32_bf16 v[72:75], v[132:135], v[218:221], v[72:75]
	v_mfma_f32_16x16x32_bf16 v[136:139], v[128:131], v[182:185], v[136:139]
	v_mfma_f32_16x16x32_bf16 v[124:127], v[140:143], v[182:185], v[124:127]
	v_mfma_f32_16x16x32_bf16 v[108:111], v[128:131], v[206:209], v[108:111]
	v_mfma_f32_16x16x32_bf16 v[104:107], v[140:143], v[206:209], v[104:107]
	v_mfma_f32_16x16x32_bf16 v[92:95], v[128:131], v[214:217], v[92:95]
	v_mfma_f32_16x16x32_bf16 v[88:91], v[140:143], v[214:217], v[88:91]
	v_mfma_f32_16x16x32_bf16 v[76:79], v[128:131], v[222:225], v[76:79]
	v_mfma_f32_16x16x32_bf16 v[72:75], v[140:143], v[222:225], v[72:75]
	v_mfma_f32_16x16x32_bf16 v[116:119], v[144:147], v[178:181], v[116:119]
	v_mfma_f32_16x16x32_bf16 v[112:115], v[152:155], v[178:181], v[112:115]
	v_mfma_f32_16x16x32_bf16 v[100:103], v[144:147], v[186:189], v[100:103]
	v_mfma_f32_16x16x32_bf16 v[96:99], v[152:155], v[186:189], v[96:99]
	v_mfma_f32_16x16x32_bf16 v[84:87], v[144:147], v[210:213], v[84:87]
	v_mfma_f32_16x16x32_bf16 v[80:83], v[152:155], v[210:213], v[80:83]
	v_mfma_f32_16x16x32_bf16 v[68:71], v[144:147], v[218:221], v[68:71]
	v_mfma_f32_16x16x32_bf16 v[64:67], v[152:155], v[218:221], v[64:67]
	v_mfma_f32_16x16x32_bf16 v[116:119], v[148:151], v[182:185], v[116:119]
	v_mfma_f32_16x16x32_bf16 v[112:115], v[156:159], v[182:185], v[112:115]
	v_mfma_f32_16x16x32_bf16 v[100:103], v[148:151], v[206:209], v[100:103]
	v_mfma_f32_16x16x32_bf16 v[96:99], v[156:159], v[206:209], v[96:99]
	v_mfma_f32_16x16x32_bf16 v[84:87], v[148:151], v[214:217], v[84:87]
	v_mfma_f32_16x16x32_bf16 v[80:83], v[156:159], v[214:217], v[80:83]
	v_mfma_f32_16x16x32_bf16 v[68:71], v[148:151], v[222:225], v[68:71]
	v_mfma_f32_16x16x32_bf16 v[64:67], v[156:159], v[222:225], v[64:67]
	s_barrier
; #define PG8_STAGE(bufoff, gbase, voff) do { _Pragma("unroll") for (int _i = 0; _i < 2; ++_i) \
;         __builtin_amdgcn_global_load_lds((const unsigned*)((const char*)(gbase) + (voff)[_i]), (LAS unsigned*)(lds + (bufoff) + ldsw + _i * 8192), 16, 0, 0); } while (0)
; #define PG8_LDA(dst, b, h) do { _Pragma("unroll") for (int m = 0; m < 4; ++m) _Pragma("unroll") for (int k = 0; k < 2; ++k) dst[m][k] = *(const LAS bf16x8*)(lds + PG8_SA(b, h) + aoff + m * 2048 + k * 1024); } while (0)
; #define PG8_MMA(ai, bj, At, Bt) do { __builtin_amdgcn_s_setprio(1); _Pragma("unroll") for (int m = 0; m < 4; ++m) _Pragma("unroll") for (int n = 0; n < 2; ++n) _Pragma("unroll") for (int k = 0; k < 2; ++k) \
;         acc[ai][bj][m][n] = __builtin_amdgcn_mfma_f32_16x16x32_bf16(Bt[n][k], At[m][k], acc[ai][bj][m][n], 0, 0, 0); __builtin_amdgcn_s_setprio(0); } while (0)
; #define PG8_WAIT_V(n) asm volatile("s_waitcnt vmcnt(" #n ")" ::: "memory")
; #define PG8_WAIT_L(n) asm volatile("s_waitcnt lgkmcnt(" #n ")" ::: "memory")
; #define PG8_BAR __builtin_amdgcn_s_barrier()
; #define PG8_SCHED __builtin_amdgcn_sched_barrier(0)
; template <class Epi, bool PERMA = false, bool DUAL = false, bool ALIGN_EPI = true, bool SP2 = true>
; __device__ __forceinline__ void gemm_phase(LAS unsigned char* lds, const Gemm g, const StaticOrder& S, const Epi& E) {
;     ...
;         for (int t = 0; t < nt; t += 2) {
;     ...
;             PG8_LDA(At, 1, 1); PG8_STAGE(PG8_SB(1, 0), b3, voffB); PG8_STAGE(PG8_SB(1, 1), b3 + hstepB, voffB); PG8_STAGE(PG8_SA(1, 0), a3, voffA);
;             PG8_WAIT_V(8); PG8_WAIT_L(0); PG8_BAR; PG8_MMA(1, 0, At, B0); PG8_MMA(1, 1, At, B1); PG8_BAR; PG8_SCHED;
;     ...
;         if constexpr (ALIGN_EPI) { if (wr == 0) PG8_BAR; }
	s_setprio 0
	s_add_i32 s16, s36, s18
	v_lshl_add_u64 v[194:195], v[194:195], 0, s[46:47]
	s_mov_b32 m0, s16
	ds_read_b128 v[178:181], v191 offset:49152
	ds_read_b128 v[182:185], v191 offset:50176
	ds_read_b128 v[186:189], v191 offset:51200
	ds_read_b128 v[206:209], v191 offset:52224
	ds_read_b128 v[210:213], v191 offset:53248
	ds_read_b128 v[214:217], v191 offset:54272
	ds_read_b128 v[218:221], v191 offset:55296
	ds_read_b128 v[222:225], v191 offset:56320
	global_load_lds_dwordx4 v[194:195], off
	s_add_i32 m0, s16, 0x2000
	s_add_u32 s14, s14, 0x80080
	v_lshl_add_u64 v[194:195], v[196:197], 0, s[46:47]
	s_addc_u32 s15, s15, 0
	s_add_i32 s16, s37, s18
	global_load_lds_dwordx4 v[194:195], off
	v_lshl_add_u64 v[194:195], s[14:15], 0, v[164:165]
	s_mov_b32 m0, s16
	s_nop 0
	global_load_lds_dwordx4 v[194:195], off
	v_lshl_add_u64 v[194:195], s[14:15], 0, v[160:161]
	s_add_i32 m0, s16, 0x2000
	s_nop 0
	global_load_lds_dwordx4 v[194:195], off
	v_lshl_add_u64 v[194:195], v[226:227], 0, s[46:47]
	s_mov_b32 m0, s25
	s_nop 0
	global_load_lds_dwordx4 v[194:195], off
	v_lshl_add_u64 v[194:195], v[228:229], 0, s[46:47]
	s_mov_b32 m0, s26
	s_nop 0
	global_load_lds_dwordx4 v[194:195], off
	s_waitcnt vmcnt(8)
	s_waitcnt lgkmcnt(0)
	s_setprio 1
	s_barrier
	v_mfma_f32_16x16x32_bf16 v[60:63], v[120:123], v[178:181], v[60:63]
	v_mfma_f32_16x16x32_bf16 v[56:59], v[132:135], v[178:181], v[56:59]
	v_mfma_f32_16x16x32_bf16 v[44:47], v[120:123], v[186:189], v[44:47]
	v_mfma_f32_16x16x32_bf16 v[40:43], v[132:135], v[186:189], v[40:43]
	v_mfma_f32_16x16x32_bf16 v[28:31], v[120:123], v[210:213], v[28:31]
	v_mfma_f32_16x16x32_bf16 v[24:27], v[132:135], v[210:213], v[24:27]
	v_mfma_f32_16x16x32_bf16 v[12:15], v[120:123], v[218:221], v[12:15]
	v_mfma_f32_16x16x32_bf16 v[8:11], v[132:135], v[218:221], v[8:11]
	v_mfma_f32_16x16x32_bf16 v[60:63], v[128:131], v[182:185], v[60:63]
	v_mfma_f32_16x16x32_bf16 v[56:59], v[140:143], v[182:185], v[56:59]
	v_mfma_f32_16x16x32_bf16 v[44:47], v[128:131], v[206:209], v[44:47]
	v_mfma_f32_16x16x32_bf16 v[40:43], v[140:143], v[206:209], v[40:43]
	v_mfma_f32_16x16x32_bf16 v[28:31], v[128:131], v[214:217], v[28:31]
	v_mfma_f32_16x16x32_bf16 v[24:27], v[140:143], v[214:217], v[24:27]
	v_mfma_f32_16x16x32_bf16 v[12:15], v[128:131], v[222:225], v[12:15]
	v_mfma_f32_16x16x32_bf16 v[8:11], v[140:143], v[222:225], v[8:11]
	v_mfma_f32_16x16x32_bf16 v[52:55], v[144:147], v[178:181], v[52:55]
	v_mfma_f32_16x16x32_bf16 v[48:51], v[152:155], v[178:181], v[48:51]
	v_mfma_f32_16x16x32_bf16 v[36:39], v[144:147], v[186:189], v[36:39]
	v_mfma_f32_16x16x32_bf16 v[32:35], v[152:155], v[186:189], v[32:35]
	v_mfma_f32_16x16x32_bf16 v[20:23], v[144:147], v[210:213], v[20:23]
	v_mfma_f32_16x16x32_bf16 v[16:19], v[152:155], v[210:213], v[16:19]
	v_mfma_f32_16x16x32_bf16 v[0:3], v[144:147], v[218:221], v[0:3]
	v_mfma_f32_16x16x32_bf16 v[4:7], v[152:155], v[218:221], v[4:7]
	v_mfma_f32_16x16x32_bf16 v[52:55], v[148:151], v[182:185], v[52:55]
	v_mfma_f32_16x16x32_bf16 v[48:51], v[156:159], v[182:185], v[48:51]
	v_mfma_f32_16x16x32_bf16 v[36:39], v[148:151], v[206:209], v[36:39]
	v_mfma_f32_16x16x32_bf16 v[32:35], v[156:159], v[206:209], v[32:35]
	v_mfma_f32_16x16x32_bf16 v[20:23], v[148:151], v[214:217], v[20:23]
	v_mfma_f32_16x16x32_bf16 v[16:19], v[156:159], v[214:217], v[16:19]
	v_mfma_f32_16x16x32_bf16 v[0:3], v[148:151], v[222:225], v[0:3]
	v_mfma_f32_16x16x32_bf16 v[4:7], v[156:159], v[222:225], v[4:7]
	s_barrier
	s_setprio 0
	s_add_i32 s35, s35, 2
	s_add_u32 s12, s12, 0x100
	s_addc_u32 s13, s13, 0
	s_add_u32 s33, s33, 0x100
	s_addc_u32 s34, s34, 0
	s_cmp_gt_u32 s35, 29
	s_cbranch_scc0 .LBB0_790
	s_and_b64 vcc, exec, s[2:3]
	s_cbranch_vccz .LBB0_793
	s_barrier
